# K-loop: m0 write / address VALU reordered so no s_nop is needed before LDS-DMA pieces
# speedup vs baseline: 1.0168x; 1.0029x over previous
.LBB0_322:
	s_ashr_i32 s43, s42, 31
	s_lshl_b64 s[46:47], s[42:43], 19
	s_add_u32 s46, s12, s46
	s_addc_u32 s47, s13, s47
	s_and_b64 s[48:49], s[4:5], exec
	s_cselect_b32 s18, s47, s7
	s_cselect_b32 s43, s46, s6
	s_ashr_i32 s45, s44, 31
	s_lshl_b64 s[48:49], s[44:45], 19
	s_add_u32 s48, s59, s48
	s_addc_u32 s49, s60, s49
	s_and_b64 s[50:51], s[4:5], exec
	s_cselect_b32 s45, s49, s9
	s_cselect_b32 s55, s48, s8
	s_add_u32 s6, s6, 0x40080
	s_addc_u32 s7, s7, 0
	s_add_u32 s56, s8, 0x100
	s_addc_u32 s57, s9, 0
	s_mov_b32 s78, -2
	ds_read_b128 v[96:99], v209
	ds_read_b128 v[100:103], v209 offset:1024
	ds_read_b128 v[120:123], v209 offset:2048
	ds_read_b128 v[124:127], v209 offset:3072
	ds_read_b128 v[144:147], v210
	ds_read_b128 v[148:151], v210 offset:1024
	ds_read_b128 v[152:155], v210 offset:2048
	ds_read_b128 v[156:159], v210 offset:3072
	s_add_u32 s8, s6, 0xfffc0080
	s_addc_u32 s9, s7, -1
	s_cmp_eq_u32 s78, 12
	s_cselect_b32 s51, s18, s9
	s_cselect_b32 s50, s43, s8
	s_cselect_b32 s9, s45, s57
	s_cselect_b32 s8, s55, s56
	v_lshl_add_u64 v[206:207], s[6:7], 0, v[170:171]
	s_add_i32 m0, s17, 0xc000
	ds_read_b128 v[178:181], v211
	ds_read_b128 v[182:185], v211 offset:1024
	ds_read_b128 v[186:189], v211 offset:2048
	ds_read_b128 v[190:193], v211 offset:3072
	ds_read_b128 v[194:197], v211 offset:4096
	ds_read_b128 v[198:201], v211 offset:5120
	ds_read_b128 v[202:205], v211 offset:6144
	ds_read_b128 v[218:221], v211 offset:7168
	global_load_lds_dwordx4 v[206:207], off
	s_add_i32 m0, s17, 0xe000
	v_lshl_add_u64 v[206:207], s[6:7], 0, v[172:173]
	global_load_lds_dwordx4 v[206:207], off
	s_waitcnt vmcnt(8)
	s_waitcnt lgkmcnt(0)
	s_barrier
	s_setprio 1
	s_waitcnt lgkmcnt(0)
	v_mfma_f32_16x16x32_bf16 v[140:143], v[96:99], v[178:181], 0
	v_mfma_f32_16x16x32_bf16 v[136:139], v[120:123], v[178:181], 0
	v_mfma_f32_16x16x32_bf16 v[116:119], v[96:99], v[186:189], 0
	v_mfma_f32_16x16x32_bf16 v[112:115], v[120:123], v[186:189], 0
	v_mfma_f32_16x16x32_bf16 v[92:95], v[96:99], v[194:197], 0
	v_mfma_f32_16x16x32_bf16 v[88:91], v[120:123], v[194:197], 0
	v_mfma_f32_16x16x32_bf16 v[76:79], v[96:99], v[202:205], 0
	v_mfma_f32_16x16x32_bf16 v[72:75], v[120:123], v[202:205], 0
	v_mfma_f32_16x16x32_bf16 v[140:143], v[100:103], v[182:185], v[140:143]
	v_mfma_f32_16x16x32_bf16 v[136:139], v[124:127], v[182:185], v[136:139]
	v_mfma_f32_16x16x32_bf16 v[116:119], v[100:103], v[190:193], v[116:119]
	v_mfma_f32_16x16x32_bf16 v[112:115], v[124:127], v[190:193], v[112:115]
	v_mfma_f32_16x16x32_bf16 v[92:95], v[100:103], v[198:201], v[92:95]
	v_mfma_f32_16x16x32_bf16 v[88:91], v[124:127], v[198:201], v[88:91]
	v_mfma_f32_16x16x32_bf16 v[76:79], v[100:103], v[218:221], v[76:79]
	v_mfma_f32_16x16x32_bf16 v[72:75], v[124:127], v[218:221], v[72:75]
	s_setprio 0
	s_setprio 1
	v_mfma_f32_16x16x32_bf16 v[132:135], v[144:147], v[178:181], 0
	v_mfma_f32_16x16x32_bf16 v[128:131], v[152:155], v[178:181], 0
	v_mfma_f32_16x16x32_bf16 v[108:111], v[144:147], v[186:189], 0
	v_mfma_f32_16x16x32_bf16 v[104:107], v[152:155], v[186:189], 0
	v_mfma_f32_16x16x32_bf16 v[84:87], v[144:147], v[194:197], 0
	v_mfma_f32_16x16x32_bf16 v[80:83], v[152:155], v[194:197], 0
	v_mfma_f32_16x16x32_bf16 v[68:71], v[144:147], v[202:205], 0
	v_mfma_f32_16x16x32_bf16 v[64:67], v[152:155], v[202:205], 0
	v_mfma_f32_16x16x32_bf16 v[132:135], v[148:151], v[182:185], v[132:135]
	v_mfma_f32_16x16x32_bf16 v[128:131], v[156:159], v[182:185], v[128:131]
	v_mfma_f32_16x16x32_bf16 v[108:111], v[148:151], v[190:193], v[108:111]
	v_mfma_f32_16x16x32_bf16 v[104:107], v[156:159], v[190:193], v[104:107]
	s_setprio 2
	s_barrier
	v_mfma_f32_16x16x32_bf16 v[84:87], v[148:151], v[198:201], v[84:87]
	v_mfma_f32_16x16x32_bf16 v[80:83], v[156:159], v[198:201], v[80:83]
	v_mfma_f32_16x16x32_bf16 v[68:71], v[148:151], v[218:221], v[68:71]
	v_mfma_f32_16x16x32_bf16 v[64:67], v[156:159], v[218:221], v[64:67]
	s_setprio 0
	s_add_i32 s79, s73, s61
	v_lshl_add_u64 v[206:207], s[8:9], 0, v[162:163]
	s_mov_b32 m0, s79
	ds_read_b128 v[178:181], v211 offset:16384
	ds_read_b128 v[182:185], v211 offset:17408
	ds_read_b128 v[186:189], v211 offset:18432
	ds_read_b128 v[190:193], v211 offset:19456
	ds_read_b128 v[194:197], v211 offset:20480
	ds_read_b128 v[198:201], v211 offset:21504
	ds_read_b128 v[202:205], v211 offset:22528
	ds_read_b128 v[218:221], v211 offset:23552
	global_load_lds_dwordx4 v[206:207], off
	s_add_i32 m0, s79, 0x2000
	s_add_u32 s80, s8, 0x40000
	v_lshl_add_u64 v[222:223], s[8:9], 0, v[166:167]
	s_addc_u32 s81, s9, 0
	s_add_i32 s79, s74, s61
	global_load_lds_dwordx4 v[222:223], off
	v_lshl_add_u64 v[224:225], s[80:81], 0, v[162:163]
	s_mov_b32 m0, s79
	v_lshl_add_u64 v[226:227], s[50:51], 0, v[164:165]
	global_load_lds_dwordx4 v[224:225], off
	s_add_i32 m0, s79, 0x2000
	v_lshl_add_u64 v[224:225], s[80:81], 0, v[166:167]
	global_load_lds_dwordx4 v[224:225], off
	s_mov_b32 m0, s17
	v_lshl_add_u64 v[224:225], s[50:51], 0, v[160:161]
	global_load_lds_dwordx4 v[224:225], off
	s_mov_b32 m0, s62
	s_nop 0
	global_load_lds_dwordx4 v[226:227], off
	s_waitcnt vmcnt(8)
	s_waitcnt lgkmcnt(0)
	s_barrier
	s_setprio 1
	s_waitcnt lgkmcnt(0)
	v_mfma_f32_16x16x32_bf16 v[60:63], v[96:99], v[178:181], 0
	v_mfma_f32_16x16x32_bf16 v[56:59], v[120:123], v[178:181], 0
	v_mfma_f32_16x16x32_bf16 v[44:47], v[96:99], v[186:189], 0
	v_mfma_f32_16x16x32_bf16 v[40:43], v[120:123], v[186:189], 0
	v_mfma_f32_16x16x32_bf16 v[28:31], v[96:99], v[194:197], 0
	v_mfma_f32_16x16x32_bf16 v[24:27], v[120:123], v[194:197], 0
	v_mfma_f32_16x16x32_bf16 v[12:15], v[96:99], v[202:205], 0
	v_mfma_f32_16x16x32_bf16 v[8:11], v[120:123], v[202:205], 0
	v_mfma_f32_16x16x32_bf16 v[60:63], v[100:103], v[182:185], v[60:63]
	v_mfma_f32_16x16x32_bf16 v[56:59], v[124:127], v[182:185], v[56:59]
	v_mfma_f32_16x16x32_bf16 v[44:47], v[100:103], v[190:193], v[44:47]
	v_mfma_f32_16x16x32_bf16 v[40:43], v[124:127], v[190:193], v[40:43]
	v_mfma_f32_16x16x32_bf16 v[28:31], v[100:103], v[198:201], v[28:31]
	v_mfma_f32_16x16x32_bf16 v[24:27], v[124:127], v[198:201], v[24:27]
	v_mfma_f32_16x16x32_bf16 v[12:15], v[100:103], v[218:221], v[12:15]
	v_mfma_f32_16x16x32_bf16 v[8:11], v[124:127], v[218:221], v[8:11]
	s_setprio 0
	s_setprio 1
	v_mfma_f32_16x16x32_bf16 v[52:55], v[144:147], v[178:181], 0
	v_mfma_f32_16x16x32_bf16 v[48:51], v[152:155], v[178:181], 0
	v_mfma_f32_16x16x32_bf16 v[36:39], v[144:147], v[186:189], 0
	v_mfma_f32_16x16x32_bf16 v[32:35], v[152:155], v[186:189], 0
	v_mfma_f32_16x16x32_bf16 v[20:23], v[144:147], v[194:197], 0
	v_mfma_f32_16x16x32_bf16 v[16:19], v[152:155], v[194:197], 0
	v_mfma_f32_16x16x32_bf16 v[4:7], v[144:147], v[202:205], 0
	v_mfma_f32_16x16x32_bf16 v[0:3], v[152:155], v[202:205], 0
	v_mfma_f32_16x16x32_bf16 v[52:55], v[148:151], v[182:185], v[52:55]
	v_mfma_f32_16x16x32_bf16 v[48:51], v[156:159], v[182:185], v[48:51]
	v_mfma_f32_16x16x32_bf16 v[36:39], v[148:151], v[190:193], v[36:39]
	v_mfma_f32_16x16x32_bf16 v[32:35], v[156:159], v[190:193], v[32:35]
	s_setprio 2
	s_barrier
	v_mfma_f32_16x16x32_bf16 v[20:23], v[148:151], v[198:201], v[20:23]
	v_mfma_f32_16x16x32_bf16 v[16:19], v[156:159], v[198:201], v[16:19]
	v_mfma_f32_16x16x32_bf16 v[4:7], v[148:151], v[218:221], v[4:7]
	v_mfma_f32_16x16x32_bf16 v[0:3], v[156:159], v[218:221], v[0:3]
	s_setprio 0
	s_add_i32 s79, 0, 0x18000
	s_add_i32 s80, 0, 0x1c000
	v_add_u32_e32 v124, s79, v208
	v_add_u32_e32 v156, s80, v208
	ds_read_b128 v[96:99], v124
	ds_read_b128 v[100:103], v124 offset:1024
	ds_read_b128 v[120:123], v124 offset:2048
	ds_read_b128 v[124:127], v124 offset:3072
	ds_read_b128 v[144:147], v156
	ds_read_b128 v[148:151], v156 offset:1024
	ds_read_b128 v[152:155], v156 offset:2048
	ds_read_b128 v[156:159], v156 offset:3072
	s_add_u32 s50, s50, 0x40000
	s_addc_u32 s51, s51, 0
	s_mov_b32 m0, s63
	v_lshl_add_u64 v[228:229], s[50:51], 0, v[160:161]
	ds_read_b128 v[178:181], v211 offset:32768
	ds_read_b128 v[182:185], v211 offset:33792
	ds_read_b128 v[186:189], v211 offset:34816
	ds_read_b128 v[190:193], v211 offset:35840
	ds_read_b128 v[194:197], v211 offset:36864
	ds_read_b128 v[198:201], v211 offset:37888
	ds_read_b128 v[202:205], v211 offset:38912
	ds_read_b128 v[218:221], v211 offset:39936
	global_load_lds_dwordx4 v[228:229], off
	s_mov_b32 m0, s64
	v_lshl_add_u64 v[228:229], s[50:51], 0, v[164:165]
	global_load_lds_dwordx4 v[228:229], off
	s_waitcnt vmcnt(8)
	s_waitcnt lgkmcnt(0)
	s_barrier
	s_setprio 1
	s_waitcnt lgkmcnt(0)
	v_mfma_f32_16x16x32_bf16 v[140:143], v[96:99], v[178:181], v[140:143]
	v_mfma_f32_16x16x32_bf16 v[136:139], v[120:123], v[178:181], v[136:139]
	v_mfma_f32_16x16x32_bf16 v[116:119], v[96:99], v[186:189], v[116:119]
	v_mfma_f32_16x16x32_bf16 v[112:115], v[120:123], v[186:189], v[112:115]
	v_mfma_f32_16x16x32_bf16 v[92:95], v[96:99], v[194:197], v[92:95]
	v_mfma_f32_16x16x32_bf16 v[88:91], v[120:123], v[194:197], v[88:91]
	v_mfma_f32_16x16x32_bf16 v[76:79], v[96:99], v[202:205], v[76:79]
	v_mfma_f32_16x16x32_bf16 v[72:75], v[120:123], v[202:205], v[72:75]
	v_mfma_f32_16x16x32_bf16 v[140:143], v[100:103], v[182:185], v[140:143]
	v_mfma_f32_16x16x32_bf16 v[136:139], v[124:127], v[182:185], v[136:139]
	v_mfma_f32_16x16x32_bf16 v[116:119], v[100:103], v[190:193], v[116:119]
	v_mfma_f32_16x16x32_bf16 v[112:115], v[124:127], v[190:193], v[112:115]
	v_mfma_f32_16x16x32_bf16 v[92:95], v[100:103], v[198:201], v[92:95]
	v_mfma_f32_16x16x32_bf16 v[88:91], v[124:127], v[198:201], v[88:91]
	v_mfma_f32_16x16x32_bf16 v[76:79], v[100:103], v[218:221], v[76:79]
	v_mfma_f32_16x16x32_bf16 v[72:75], v[124:127], v[218:221], v[72:75]
	s_setprio 0
	s_setprio 1
	v_mfma_f32_16x16x32_bf16 v[132:135], v[144:147], v[178:181], v[132:135]
	v_mfma_f32_16x16x32_bf16 v[128:131], v[152:155], v[178:181], v[128:131]
	v_mfma_f32_16x16x32_bf16 v[108:111], v[144:147], v[186:189], v[108:111]
	v_mfma_f32_16x16x32_bf16 v[104:107], v[152:155], v[186:189], v[104:107]
	v_mfma_f32_16x16x32_bf16 v[84:87], v[144:147], v[194:197], v[84:87]
	v_mfma_f32_16x16x32_bf16 v[80:83], v[152:155], v[194:197], v[80:83]
	v_mfma_f32_16x16x32_bf16 v[68:71], v[144:147], v[202:205], v[68:71]
	v_mfma_f32_16x16x32_bf16 v[64:67], v[152:155], v[202:205], v[64:67]
	v_mfma_f32_16x16x32_bf16 v[132:135], v[148:151], v[182:185], v[132:135]
	v_mfma_f32_16x16x32_bf16 v[128:131], v[156:159], v[182:185], v[128:131]
	v_mfma_f32_16x16x32_bf16 v[108:111], v[148:151], v[190:193], v[108:111]
	v_mfma_f32_16x16x32_bf16 v[104:107], v[156:159], v[190:193], v[104:107]
	s_setprio 2
	s_barrier
	v_mfma_f32_16x16x32_bf16 v[84:87], v[148:151], v[198:201], v[84:87]
	v_mfma_f32_16x16x32_bf16 v[80:83], v[156:159], v[198:201], v[80:83]
	v_mfma_f32_16x16x32_bf16 v[68:71], v[148:151], v[218:221], v[68:71]
	v_mfma_f32_16x16x32_bf16 v[64:67], v[156:159], v[218:221], v[64:67]
	s_setprio 0
	s_add_i32 s50, s79, s61
	v_lshl_add_u64 v[206:207], v[206:207], 0, s[36:37]
	s_mov_b32 m0, s50
	ds_read_b128 v[178:181], v211 offset:49152
	ds_read_b128 v[182:185], v211 offset:50176
	ds_read_b128 v[186:189], v211 offset:51200
	ds_read_b128 v[190:193], v211 offset:52224
	ds_read_b128 v[194:197], v211 offset:53248
	ds_read_b128 v[198:201], v211 offset:54272
	ds_read_b128 v[202:205], v211 offset:55296
	ds_read_b128 v[218:221], v211 offset:56320
	global_load_lds_dwordx4 v[206:207], off
	s_add_i32 m0, s50, 0x2000
	s_add_u32 s8, s8, 0x40080
	v_lshl_add_u64 v[206:207], v[222:223], 0, s[36:37]
	s_addc_u32 s9, s9, 0
	s_add_i32 s50, s80, s61
	global_load_lds_dwordx4 v[206:207], off
	s_mov_b32 m0, s50
	v_lshl_add_u64 v[206:207], s[8:9], 0, v[162:163]
	global_load_lds_dwordx4 v[206:207], off
	s_add_i32 m0, s50, 0x2000
	v_lshl_add_u64 v[206:207], s[8:9], 0, v[166:167]
	global_load_lds_dwordx4 v[206:207], off
	s_mov_b32 m0, s68
	v_lshl_add_u64 v[206:207], v[224:225], 0, s[36:37]
	global_load_lds_dwordx4 v[206:207], off
	s_mov_b32 m0, s69
	v_lshl_add_u64 v[206:207], v[226:227], 0, s[36:37]
	global_load_lds_dwordx4 v[206:207], off
	s_waitcnt vmcnt(8)
	s_waitcnt lgkmcnt(0)
	s_barrier
	s_setprio 1
	s_waitcnt lgkmcnt(0)
	v_mfma_f32_16x16x32_bf16 v[60:63], v[96:99], v[178:181], v[60:63]
	v_mfma_f32_16x16x32_bf16 v[56:59], v[120:123], v[178:181], v[56:59]
	v_mfma_f32_16x16x32_bf16 v[44:47], v[96:99], v[186:189], v[44:47]
	v_mfma_f32_16x16x32_bf16 v[40:43], v[120:123], v[186:189], v[40:43]
	v_mfma_f32_16x16x32_bf16 v[28:31], v[96:99], v[194:197], v[28:31]
	v_mfma_f32_16x16x32_bf16 v[24:27], v[120:123], v[194:197], v[24:27]
	v_mfma_f32_16x16x32_bf16 v[12:15], v[96:99], v[202:205], v[12:15]
	v_mfma_f32_16x16x32_bf16 v[8:11], v[120:123], v[202:205], v[8:11]
	v_mfma_f32_16x16x32_bf16 v[60:63], v[100:103], v[182:185], v[60:63]
	v_mfma_f32_16x16x32_bf16 v[56:59], v[124:127], v[182:185], v[56:59]
	v_mfma_f32_16x16x32_bf16 v[44:47], v[100:103], v[190:193], v[44:47]
	v_mfma_f32_16x16x32_bf16 v[40:43], v[124:127], v[190:193], v[40:43]
	v_mfma_f32_16x16x32_bf16 v[28:31], v[100:103], v[198:201], v[28:31]
	v_mfma_f32_16x16x32_bf16 v[24:27], v[124:127], v[198:201], v[24:27]
	v_mfma_f32_16x16x32_bf16 v[12:15], v[100:103], v[218:221], v[12:15]
	v_mfma_f32_16x16x32_bf16 v[8:11], v[124:127], v[218:221], v[8:11]
	s_setprio 0
	s_setprio 1
	v_mfma_f32_16x16x32_bf16 v[52:55], v[144:147], v[178:181], v[52:55]
	v_mfma_f32_16x16x32_bf16 v[48:51], v[152:155], v[178:181], v[48:51]
	v_mfma_f32_16x16x32_bf16 v[36:39], v[144:147], v[186:189], v[36:39]
	v_mfma_f32_16x16x32_bf16 v[32:35], v[152:155], v[186:189], v[32:35]
	v_mfma_f32_16x16x32_bf16 v[20:23], v[144:147], v[194:197], v[20:23]
	v_mfma_f32_16x16x32_bf16 v[16:19], v[152:155], v[194:197], v[16:19]
	v_mfma_f32_16x16x32_bf16 v[4:7], v[144:147], v[202:205], v[4:7]
	v_mfma_f32_16x16x32_bf16 v[0:3], v[152:155], v[202:205], v[0:3]
	v_mfma_f32_16x16x32_bf16 v[52:55], v[148:151], v[182:185], v[52:55]
	v_mfma_f32_16x16x32_bf16 v[48:51], v[156:159], v[182:185], v[48:51]
	v_mfma_f32_16x16x32_bf16 v[36:39], v[148:151], v[190:193], v[36:39]
	v_mfma_f32_16x16x32_bf16 v[32:35], v[156:159], v[190:193], v[32:35]
	s_setprio 2
	s_barrier
	v_mfma_f32_16x16x32_bf16 v[20:23], v[148:151], v[198:201], v[20:23]
	v_mfma_f32_16x16x32_bf16 v[16:19], v[156:159], v[198:201], v[16:19]
	v_mfma_f32_16x16x32_bf16 v[4:7], v[148:151], v[218:221], v[4:7]
	v_mfma_f32_16x16x32_bf16 v[0:3], v[156:159], v[218:221], v[0:3]
	s_setprio 0
	s_add_i32 s78, s78, 2
	s_add_u32 s6, s6, 0x100
	s_addc_u32 s7, s7, 0
	s_add_u32 s56, s56, 0x100
	s_addc_u32 s57, s57, 0
	s_cmp_gt_u32 s78, 13
.LBB0_323:
	ds_read_b128 v[96:99], v209
	ds_read_b128 v[100:103], v209 offset:1024
	ds_read_b128 v[120:123], v209 offset:2048
	ds_read_b128 v[124:127], v209 offset:3072
	ds_read_b128 v[144:147], v210
	ds_read_b128 v[148:151], v210 offset:1024
	ds_read_b128 v[152:155], v210 offset:2048
	ds_read_b128 v[156:159], v210 offset:3072
	s_add_u32 s8, s6, 0xfffc0080
	s_addc_u32 s9, s7, -1
	s_cmp_eq_u32 s78, 12
	s_cselect_b32 s51, s18, s9
	s_cselect_b32 s50, s43, s8
	s_cselect_b32 s9, s45, s57
	s_cselect_b32 s8, s55, s56
	v_lshl_add_u64 v[206:207], s[6:7], 0, v[170:171]
	s_add_i32 m0, s17, 0xc000
	ds_read_b128 v[178:181], v211
	ds_read_b128 v[182:185], v211 offset:1024
	ds_read_b128 v[186:189], v211 offset:2048
	ds_read_b128 v[190:193], v211 offset:3072
	ds_read_b128 v[194:197], v211 offset:4096
	ds_read_b128 v[198:201], v211 offset:5120
	ds_read_b128 v[202:205], v211 offset:6144
	ds_read_b128 v[218:221], v211 offset:7168
	global_load_lds_dwordx4 v[206:207], off
	s_add_i32 m0, s17, 0xe000
	v_lshl_add_u64 v[206:207], s[6:7], 0, v[172:173]
	global_load_lds_dwordx4 v[206:207], off
	s_waitcnt vmcnt(8)
	s_waitcnt lgkmcnt(0)
	s_barrier
	s_setprio 1
	s_waitcnt lgkmcnt(0)
	v_mfma_f32_16x16x32_bf16 v[140:143], v[96:99], v[178:181], v[140:143]
	v_mfma_f32_16x16x32_bf16 v[136:139], v[120:123], v[178:181], v[136:139]
	v_mfma_f32_16x16x32_bf16 v[116:119], v[96:99], v[186:189], v[116:119]
	v_mfma_f32_16x16x32_bf16 v[112:115], v[120:123], v[186:189], v[112:115]
	v_mfma_f32_16x16x32_bf16 v[92:95], v[96:99], v[194:197], v[92:95]
	v_mfma_f32_16x16x32_bf16 v[88:91], v[120:123], v[194:197], v[88:91]
	v_mfma_f32_16x16x32_bf16 v[76:79], v[96:99], v[202:205], v[76:79]
	v_mfma_f32_16x16x32_bf16 v[72:75], v[120:123], v[202:205], v[72:75]
	v_mfma_f32_16x16x32_bf16 v[140:143], v[100:103], v[182:185], v[140:143]
	v_mfma_f32_16x16x32_bf16 v[136:139], v[124:127], v[182:185], v[136:139]
	v_mfma_f32_16x16x32_bf16 v[116:119], v[100:103], v[190:193], v[116:119]
	v_mfma_f32_16x16x32_bf16 v[112:115], v[124:127], v[190:193], v[112:115]
	v_mfma_f32_16x16x32_bf16 v[92:95], v[100:103], v[198:201], v[92:95]
	v_mfma_f32_16x16x32_bf16 v[88:91], v[124:127], v[198:201], v[88:91]
	v_mfma_f32_16x16x32_bf16 v[76:79], v[100:103], v[218:221], v[76:79]
	v_mfma_f32_16x16x32_bf16 v[72:75], v[124:127], v[218:221], v[72:75]
	s_setprio 0
	s_setprio 1
	v_mfma_f32_16x16x32_bf16 v[132:135], v[144:147], v[178:181], v[132:135]
	v_mfma_f32_16x16x32_bf16 v[128:131], v[152:155], v[178:181], v[128:131]
	v_mfma_f32_16x16x32_bf16 v[108:111], v[144:147], v[186:189], v[108:111]
	v_mfma_f32_16x16x32_bf16 v[104:107], v[152:155], v[186:189], v[104:107]
	v_mfma_f32_16x16x32_bf16 v[84:87], v[144:147], v[194:197], v[84:87]
	v_mfma_f32_16x16x32_bf16 v[80:83], v[152:155], v[194:197], v[80:83]
	v_mfma_f32_16x16x32_bf16 v[68:71], v[144:147], v[202:205], v[68:71]
	v_mfma_f32_16x16x32_bf16 v[64:67], v[152:155], v[202:205], v[64:67]
	v_mfma_f32_16x16x32_bf16 v[132:135], v[148:151], v[182:185], v[132:135]
	v_mfma_f32_16x16x32_bf16 v[128:131], v[156:159], v[182:185], v[128:131]
	v_mfma_f32_16x16x32_bf16 v[108:111], v[148:151], v[190:193], v[108:111]
	v_mfma_f32_16x16x32_bf16 v[104:107], v[156:159], v[190:193], v[104:107]
	s_setprio 2
	s_barrier
	v_mfma_f32_16x16x32_bf16 v[84:87], v[148:151], v[198:201], v[84:87]
	v_mfma_f32_16x16x32_bf16 v[80:83], v[156:159], v[198:201], v[80:83]
	v_mfma_f32_16x16x32_bf16 v[68:71], v[148:151], v[218:221], v[68:71]
	v_mfma_f32_16x16x32_bf16 v[64:67], v[156:159], v[218:221], v[64:67]
	s_setprio 0
	s_add_i32 s79, s73, s61
	v_lshl_add_u64 v[206:207], s[8:9], 0, v[162:163]
	s_mov_b32 m0, s79
	ds_read_b128 v[178:181], v211 offset:16384
	ds_read_b128 v[182:185], v211 offset:17408
	ds_read_b128 v[186:189], v211 offset:18432
	ds_read_b128 v[190:193], v211 offset:19456
	ds_read_b128 v[194:197], v211 offset:20480
	ds_read_b128 v[198:201], v211 offset:21504
	ds_read_b128 v[202:205], v211 offset:22528
	ds_read_b128 v[218:221], v211 offset:23552
	global_load_lds_dwordx4 v[206:207], off
	s_add_i32 m0, s79, 0x2000
	s_add_u32 s80, s8, 0x40000
	v_lshl_add_u64 v[222:223], s[8:9], 0, v[166:167]
	s_addc_u32 s81, s9, 0
	s_add_i32 s79, s74, s61
	global_load_lds_dwordx4 v[222:223], off
	v_lshl_add_u64 v[224:225], s[80:81], 0, v[162:163]
	s_mov_b32 m0, s79
	v_lshl_add_u64 v[226:227], s[50:51], 0, v[164:165]
	global_load_lds_dwordx4 v[224:225], off
	s_add_i32 m0, s79, 0x2000
	v_lshl_add_u64 v[224:225], s[80:81], 0, v[166:167]
	global_load_lds_dwordx4 v[224:225], off
	s_mov_b32 m0, s17
	v_lshl_add_u64 v[224:225], s[50:51], 0, v[160:161]
	global_load_lds_dwordx4 v[224:225], off
	s_mov_b32 m0, s62
	s_nop 0
	global_load_lds_dwordx4 v[226:227], off
	s_waitcnt vmcnt(8)
	s_waitcnt lgkmcnt(0)
	s_barrier
	s_setprio 1
	s_waitcnt lgkmcnt(0)
	v_mfma_f32_16x16x32_bf16 v[60:63], v[96:99], v[178:181], v[60:63]
	v_mfma_f32_16x16x32_bf16 v[56:59], v[120:123], v[178:181], v[56:59]
	v_mfma_f32_16x16x32_bf16 v[44:47], v[96:99], v[186:189], v[44:47]
	v_mfma_f32_16x16x32_bf16 v[40:43], v[120:123], v[186:189], v[40:43]
	v_mfma_f32_16x16x32_bf16 v[28:31], v[96:99], v[194:197], v[28:31]
	v_mfma_f32_16x16x32_bf16 v[24:27], v[120:123], v[194:197], v[24:27]
	v_mfma_f32_16x16x32_bf16 v[12:15], v[96:99], v[202:205], v[12:15]
	v_mfma_f32_16x16x32_bf16 v[8:11], v[120:123], v[202:205], v[8:11]
	v_mfma_f32_16x16x32_bf16 v[60:63], v[100:103], v[182:185], v[60:63]
	v_mfma_f32_16x16x32_bf16 v[56:59], v[124:127], v[182:185], v[56:59]
	v_mfma_f32_16x16x32_bf16 v[44:47], v[100:103], v[190:193], v[44:47]
	v_mfma_f32_16x16x32_bf16 v[40:43], v[124:127], v[190:193], v[40:43]
	v_mfma_f32_16x16x32_bf16 v[28:31], v[100:103], v[198:201], v[28:31]
	v_mfma_f32_16x16x32_bf16 v[24:27], v[124:127], v[198:201], v[24:27]
	v_mfma_f32_16x16x32_bf16 v[12:15], v[100:103], v[218:221], v[12:15]
	v_mfma_f32_16x16x32_bf16 v[8:11], v[124:127], v[218:221], v[8:11]
	s_setprio 0
	s_setprio 1
	v_mfma_f32_16x16x32_bf16 v[52:55], v[144:147], v[178:181], v[52:55]
	v_mfma_f32_16x16x32_bf16 v[48:51], v[152:155], v[178:181], v[48:51]
	v_mfma_f32_16x16x32_bf16 v[36:39], v[144:147], v[186:189], v[36:39]
	v_mfma_f32_16x16x32_bf16 v[32:35], v[152:155], v[186:189], v[32:35]
	v_mfma_f32_16x16x32_bf16 v[20:23], v[144:147], v[194:197], v[20:23]
	v_mfma_f32_16x16x32_bf16 v[16:19], v[152:155], v[194:197], v[16:19]
	v_mfma_f32_16x16x32_bf16 v[4:7], v[144:147], v[202:205], v[4:7]
	v_mfma_f32_16x16x32_bf16 v[0:3], v[152:155], v[202:205], v[0:3]
	v_mfma_f32_16x16x32_bf16 v[52:55], v[148:151], v[182:185], v[52:55]
	v_mfma_f32_16x16x32_bf16 v[48:51], v[156:159], v[182:185], v[48:51]
	v_mfma_f32_16x16x32_bf16 v[36:39], v[148:151], v[190:193], v[36:39]
	v_mfma_f32_16x16x32_bf16 v[32:35], v[156:159], v[190:193], v[32:35]
	s_setprio 2
	s_barrier
	v_mfma_f32_16x16x32_bf16 v[20:23], v[148:151], v[198:201], v[20:23]
	v_mfma_f32_16x16x32_bf16 v[16:19], v[156:159], v[198:201], v[16:19]
	v_mfma_f32_16x16x32_bf16 v[4:7], v[148:151], v[218:221], v[4:7]
	v_mfma_f32_16x16x32_bf16 v[0:3], v[156:159], v[218:221], v[0:3]
	s_setprio 0
	s_add_i32 s79, 0, 0x18000
	s_add_i32 s80, 0, 0x1c000
	v_add_u32_e32 v124, s79, v208
	v_add_u32_e32 v156, s80, v208
	ds_read_b128 v[96:99], v124
	ds_read_b128 v[100:103], v124 offset:1024
	ds_read_b128 v[120:123], v124 offset:2048
	ds_read_b128 v[124:127], v124 offset:3072
	ds_read_b128 v[144:147], v156
	ds_read_b128 v[148:151], v156 offset:1024
	ds_read_b128 v[152:155], v156 offset:2048
	ds_read_b128 v[156:159], v156 offset:3072
	s_add_u32 s50, s50, 0x40000
	s_addc_u32 s51, s51, 0
	s_mov_b32 m0, s63
	v_lshl_add_u64 v[228:229], s[50:51], 0, v[160:161]
	ds_read_b128 v[178:181], v211 offset:32768
	ds_read_b128 v[182:185], v211 offset:33792
	ds_read_b128 v[186:189], v211 offset:34816
	ds_read_b128 v[190:193], v211 offset:35840
	ds_read_b128 v[194:197], v211 offset:36864
	ds_read_b128 v[198:201], v211 offset:37888
	ds_read_b128 v[202:205], v211 offset:38912
	ds_read_b128 v[218:221], v211 offset:39936
	global_load_lds_dwordx4 v[228:229], off
	s_mov_b32 m0, s64
	v_lshl_add_u64 v[228:229], s[50:51], 0, v[164:165]
	global_load_lds_dwordx4 v[228:229], off
	s_waitcnt vmcnt(8)
	s_waitcnt lgkmcnt(0)
	s_barrier
	s_setprio 1
	s_waitcnt lgkmcnt(0)
	v_mfma_f32_16x16x32_bf16 v[140:143], v[96:99], v[178:181], v[140:143]
	v_mfma_f32_16x16x32_bf16 v[136:139], v[120:123], v[178:181], v[136:139]
	v_mfma_f32_16x16x32_bf16 v[116:119], v[96:99], v[186:189], v[116:119]
	v_mfma_f32_16x16x32_bf16 v[112:115], v[120:123], v[186:189], v[112:115]
	v_mfma_f32_16x16x32_bf16 v[92:95], v[96:99], v[194:197], v[92:95]
	v_mfma_f32_16x16x32_bf16 v[88:91], v[120:123], v[194:197], v[88:91]
	v_mfma_f32_16x16x32_bf16 v[76:79], v[96:99], v[202:205], v[76:79]
	v_mfma_f32_16x16x32_bf16 v[72:75], v[120:123], v[202:205], v[72:75]
	v_mfma_f32_16x16x32_bf16 v[140:143], v[100:103], v[182:185], v[140:143]
	v_mfma_f32_16x16x32_bf16 v[136:139], v[124:127], v[182:185], v[136:139]
	v_mfma_f32_16x16x32_bf16 v[116:119], v[100:103], v[190:193], v[116:119]
	v_mfma_f32_16x16x32_bf16 v[112:115], v[124:127], v[190:193], v[112:115]
	v_mfma_f32_16x16x32_bf16 v[92:95], v[100:103], v[198:201], v[92:95]
	v_mfma_f32_16x16x32_bf16 v[88:91], v[124:127], v[198:201], v[88:91]
	v_mfma_f32_16x16x32_bf16 v[76:79], v[100:103], v[218:221], v[76:79]
	v_mfma_f32_16x16x32_bf16 v[72:75], v[124:127], v[218:221], v[72:75]
	s_setprio 0
	s_setprio 1
	v_mfma_f32_16x16x32_bf16 v[132:135], v[144:147], v[178:181], v[132:135]
	v_mfma_f32_16x16x32_bf16 v[128:131], v[152:155], v[178:181], v[128:131]
	v_mfma_f32_16x16x32_bf16 v[108:111], v[144:147], v[186:189], v[108:111]
	v_mfma_f32_16x16x32_bf16 v[104:107], v[152:155], v[186:189], v[104:107]
	v_mfma_f32_16x16x32_bf16 v[84:87], v[144:147], v[194:197], v[84:87]
	v_mfma_f32_16x16x32_bf16 v[80:83], v[152:155], v[194:197], v[80:83]
	v_mfma_f32_16x16x32_bf16 v[68:71], v[144:147], v[202:205], v[68:71]
	v_mfma_f32_16x16x32_bf16 v[64:67], v[152:155], v[202:205], v[64:67]
	v_mfma_f32_16x16x32_bf16 v[132:135], v[148:151], v[182:185], v[132:135]
	v_mfma_f32_16x16x32_bf16 v[128:131], v[156:159], v[182:185], v[128:131]
	v_mfma_f32_16x16x32_bf16 v[108:111], v[148:151], v[190:193], v[108:111]
	v_mfma_f32_16x16x32_bf16 v[104:107], v[156:159], v[190:193], v[104:107]
	s_setprio 2
	s_barrier
	v_mfma_f32_16x16x32_bf16 v[84:87], v[148:151], v[198:201], v[84:87]
	v_mfma_f32_16x16x32_bf16 v[80:83], v[156:159], v[198:201], v[80:83]
	v_mfma_f32_16x16x32_bf16 v[68:71], v[148:151], v[218:221], v[68:71]
	v_mfma_f32_16x16x32_bf16 v[64:67], v[156:159], v[218:221], v[64:67]
	s_setprio 0
	s_add_i32 s50, s79, s61
	v_lshl_add_u64 v[206:207], v[206:207], 0, s[36:37]
	s_mov_b32 m0, s50
	ds_read_b128 v[178:181], v211 offset:49152
	ds_read_b128 v[182:185], v211 offset:50176
	ds_read_b128 v[186:189], v211 offset:51200
	ds_read_b128 v[190:193], v211 offset:52224
	ds_read_b128 v[194:197], v211 offset:53248
	ds_read_b128 v[198:201], v211 offset:54272
	ds_read_b128 v[202:205], v211 offset:55296
	ds_read_b128 v[218:221], v211 offset:56320
	global_load_lds_dwordx4 v[206:207], off
	s_add_i32 m0, s50, 0x2000
	s_add_u32 s8, s8, 0x40080
	v_lshl_add_u64 v[206:207], v[222:223], 0, s[36:37]
	s_addc_u32 s9, s9, 0
	s_add_i32 s50, s80, s61
	global_load_lds_dwordx4 v[206:207], off
	s_mov_b32 m0, s50
	v_lshl_add_u64 v[206:207], s[8:9], 0, v[162:163]
	global_load_lds_dwordx4 v[206:207], off
	s_add_i32 m0, s50, 0x2000
	v_lshl_add_u64 v[206:207], s[8:9], 0, v[166:167]
	global_load_lds_dwordx4 v[206:207], off
	s_mov_b32 m0, s68
	v_lshl_add_u64 v[206:207], v[224:225], 0, s[36:37]
	global_load_lds_dwordx4 v[206:207], off
	s_mov_b32 m0, s69
	v_lshl_add_u64 v[206:207], v[226:227], 0, s[36:37]
	global_load_lds_dwordx4 v[206:207], off
	s_waitcnt vmcnt(8)
	s_waitcnt lgkmcnt(0)
	s_barrier
	s_setprio 1
	s_waitcnt lgkmcnt(0)
	v_mfma_f32_16x16x32_bf16 v[60:63], v[96:99], v[178:181], v[60:63]
	v_mfma_f32_16x16x32_bf16 v[56:59], v[120:123], v[178:181], v[56:59]
	v_mfma_f32_16x16x32_bf16 v[44:47], v[96:99], v[186:189], v[44:47]
	v_mfma_f32_16x16x32_bf16 v[40:43], v[120:123], v[186:189], v[40:43]
	v_mfma_f32_16x16x32_bf16 v[28:31], v[96:99], v[194:197], v[28:31]
	v_mfma_f32_16x16x32_bf16 v[24:27], v[120:123], v[194:197], v[24:27]
	v_mfma_f32_16x16x32_bf16 v[12:15], v[96:99], v[202:205], v[12:15]
	v_mfma_f32_16x16x32_bf16 v[8:11], v[120:123], v[202:205], v[8:11]
	v_mfma_f32_16x16x32_bf16 v[60:63], v[100:103], v[182:185], v[60:63]
	v_mfma_f32_16x16x32_bf16 v[56:59], v[124:127], v[182:185], v[56:59]
	v_mfma_f32_16x16x32_bf16 v[44:47], v[100:103], v[190:193], v[44:47]
	v_mfma_f32_16x16x32_bf16 v[40:43], v[124:127], v[190:193], v[40:43]
	v_mfma_f32_16x16x32_bf16 v[28:31], v[100:103], v[198:201], v[28:31]
	v_mfma_f32_16x16x32_bf16 v[24:27], v[124:127], v[198:201], v[24:27]
	v_mfma_f32_16x16x32_bf16 v[12:15], v[100:103], v[218:221], v[12:15]
	v_mfma_f32_16x16x32_bf16 v[8:11], v[124:127], v[218:221], v[8:11]
	s_setprio 0
	s_setprio 1
	v_mfma_f32_16x16x32_bf16 v[52:55], v[144:147], v[178:181], v[52:55]
	v_mfma_f32_16x16x32_bf16 v[48:51], v[152:155], v[178:181], v[48:51]
	v_mfma_f32_16x16x32_bf16 v[36:39], v[144:147], v[186:189], v[36:39]
	v_mfma_f32_16x16x32_bf16 v[32:35], v[152:155], v[186:189], v[32:35]
	v_mfma_f32_16x16x32_bf16 v[20:23], v[144:147], v[194:197], v[20:23]
	v_mfma_f32_16x16x32_bf16 v[16:19], v[152:155], v[194:197], v[16:19]
	v_mfma_f32_16x16x32_bf16 v[4:7], v[144:147], v[202:205], v[4:7]
	v_mfma_f32_16x16x32_bf16 v[0:3], v[152:155], v[202:205], v[0:3]
	v_mfma_f32_16x16x32_bf16 v[52:55], v[148:151], v[182:185], v[52:55]
	v_mfma_f32_16x16x32_bf16 v[48:51], v[156:159], v[182:185], v[48:51]
	v_mfma_f32_16x16x32_bf16 v[36:39], v[148:151], v[190:193], v[36:39]
	v_mfma_f32_16x16x32_bf16 v[32:35], v[156:159], v[190:193], v[32:35]
	s_setprio 2
	s_barrier
	v_mfma_f32_16x16x32_bf16 v[20:23], v[148:151], v[198:201], v[20:23]
	v_mfma_f32_16x16x32_bf16 v[16:19], v[156:159], v[198:201], v[16:19]
	v_mfma_f32_16x16x32_bf16 v[4:7], v[148:151], v[218:221], v[4:7]
	v_mfma_f32_16x16x32_bf16 v[0:3], v[156:159], v[218:221], v[0:3]
	s_setprio 0
	s_add_i32 s78, s78, 2
	s_add_u32 s6, s6, 0x100
	s_addc_u32 s7, s7, 0
	s_add_u32 s56, s56, 0x100
	s_addc_u32 s57, s57, 0
	s_cmp_gt_u32 s78, 13
	s_cbranch_scc0 .LBB0_323

.LBB0_697:
	s_and_b32 s29, s69, 0x1000
	s_add_i32 s70, s66, s29
	s_ashr_i32 s29, s28, 31
	ds_read_b128 v[0:3], v195 offset:3072
	ds_read_b128 v[4:7], v195 offset:2048
	ds_read_b128 v[8:11], v195 offset:1024
	ds_read_b128 v[12:15], v195
	ds_read_b128 v[16:19], v203 offset:3072
	ds_read_b128 v[20:23], v203 offset:2048
	ds_read_b128 v[24:27], v203 offset:1024
	ds_read_b128 v[28:31], v203
	s_lshl_b64 s[36:37], s[28:29], 20
	s_add_u32 s36, s50, s36
	s_addc_u32 s37, s51, s37
	s_and_b64 s[38:39], s[4:5], exec
	s_cselect_b32 s29, s37, s45
	s_cselect_b32 s71, s36, s44
	s_ashr_i32 s31, s30, 31
	s_lshl_b64 s[38:39], s[30:31], 20
	s_add_u32 s38, s54, s38
	s_addc_u32 s39, s55, s39
	s_and_b64 s[48:49], s[4:5], exec
	s_cselect_b32 s31, s39, s47
	s_cselect_b32 s72, s38, s46
	s_add_u32 s48, s44, 0x80080
	s_addc_u32 s49, s45, 0
	s_add_i32 s73, s56, 0xc000
	v_lshl_add_u64 v[64:65], s[48:49], 0, v[176:177]
	s_mov_b32 m0, s73
	s_add_i32 s74, s56, 0xe000
	ds_read_b128 v[32:35], v211
	ds_read_b128 v[36:39], v211 offset:1024
	ds_read_b128 v[40:43], v211 offset:2048
	ds_read_b128 v[44:47], v211 offset:3072
	ds_read_b128 v[48:51], v211 offset:4096
	ds_read_b128 v[52:55], v211 offset:5120
	ds_read_b128 v[56:59], v211 offset:6144
	ds_read_b128 v[60:63], v211 offset:7168
	global_load_lds_dwordx4 v[64:65], off
	s_mov_b32 m0, s74
	v_lshl_add_u64 v[64:65], s[48:49], 0, v[178:179]
	global_load_lds_dwordx4 v[64:65], off
	s_waitcnt vmcnt(8)
	s_waitcnt lgkmcnt(0)
	s_barrier
	s_setprio 1
	s_waitcnt lgkmcnt(0)
	v_mfma_f32_16x16x32_bf16 v[88:91], v[28:31], v[56:59], 0
	v_mfma_f32_16x16x32_bf16 v[64:67], v[28:31], v[32:35], 0
	v_mfma_f32_16x16x32_bf16 v[68:71], v[20:23], v[32:35], 0
	v_mfma_f32_16x16x32_bf16 v[72:75], v[28:31], v[40:43], 0
	v_mfma_f32_16x16x32_bf16 v[76:79], v[20:23], v[40:43], 0
	v_mfma_f32_16x16x32_bf16 v[80:83], v[28:31], v[48:51], 0
	v_mfma_f32_16x16x32_bf16 v[84:87], v[20:23], v[48:51], 0
	v_mfma_f32_16x16x32_bf16 v[96:99], v[24:27], v[60:63], v[88:91]
	v_mfma_f32_16x16x32_bf16 v[88:91], v[20:23], v[56:59], 0
	v_mfma_f32_16x16x32_bf16 v[64:67], v[24:27], v[36:39], v[64:67]
	v_mfma_f32_16x16x32_bf16 v[68:71], v[16:19], v[36:39], v[68:71]
	v_mfma_f32_16x16x32_bf16 v[72:75], v[24:27], v[44:47], v[72:75]
	v_mfma_f32_16x16x32_bf16 v[76:79], v[16:19], v[44:47], v[76:79]
	v_mfma_f32_16x16x32_bf16 v[80:83], v[24:27], v[52:55], v[80:83]
	v_mfma_f32_16x16x32_bf16 v[84:87], v[16:19], v[52:55], v[84:87]
	v_mfma_f32_16x16x32_bf16 v[100:103], v[16:19], v[60:63], v[88:91]
	s_setprio 0
	s_setprio 1
	v_mfma_f32_16x16x32_bf16 v[88:91], v[12:15], v[32:35], 0
	v_mfma_f32_16x16x32_bf16 v[32:35], v[4:7], v[32:35], 0
	v_mfma_f32_16x16x32_bf16 v[112:115], v[8:11], v[36:39], v[88:91]
	v_mfma_f32_16x16x32_bf16 v[32:35], v[0:3], v[36:39], v[32:35]
	v_mfma_f32_16x16x32_bf16 v[36:39], v[12:15], v[40:43], 0
	v_mfma_f32_16x16x32_bf16 v[40:43], v[4:7], v[40:43], 0
	v_mfma_f32_16x16x32_bf16 v[36:39], v[8:11], v[44:47], v[36:39]
	v_mfma_f32_16x16x32_bf16 v[40:43], v[0:3], v[44:47], v[40:43]
	v_mfma_f32_16x16x32_bf16 v[44:47], v[12:15], v[48:51], 0
	v_mfma_f32_16x16x32_bf16 v[48:51], v[4:7], v[48:51], 0
	v_mfma_f32_16x16x32_bf16 v[44:47], v[8:11], v[52:55], v[44:47]
	v_mfma_f32_16x16x32_bf16 v[48:51], v[0:3], v[52:55], v[48:51]
	s_setprio 2
	s_barrier
	v_mfma_f32_16x16x32_bf16 v[52:55], v[12:15], v[56:59], 0
	v_mfma_f32_16x16x32_bf16 v[56:59], v[4:7], v[56:59], 0
	v_mfma_f32_16x16x32_bf16 v[52:55], v[8:11], v[60:63], v[52:55]
	v_mfma_f32_16x16x32_bf16 v[56:59], v[0:3], v[60:63], v[56:59]
	s_setprio 0
	s_add_i32 s75, s68, s43
	v_lshl_add_u64 v[174:175], s[46:47], 0, v[176:177]
	s_add_i32 s76, s75, 0x2000
	v_lshl_add_u64 v[128:129], v[174:175], 0, s[24:25]
	s_mov_b32 m0, s75
	v_lshl_add_u64 v[200:201], s[46:47], 0, v[178:179]
	s_add_u32 s48, s46, 0x80100
	ds_read_b128 v[60:63], v211 offset:16384
	ds_read_b128 v[88:91], v211 offset:17408
	ds_read_b128 v[92:95], v211 offset:18432
	ds_read_b128 v[104:107], v211 offset:19456
	ds_read_b128 v[108:111], v211 offset:20480
	ds_read_b128 v[116:119], v211 offset:21504
	ds_read_b128 v[120:123], v211 offset:22528
	ds_read_b128 v[124:127], v211 offset:23552
	global_load_lds_dwordx4 v[128:129], off
	v_lshl_add_u64 v[128:129], v[200:201], 0, s[24:25]
	s_mov_b32 m0, s76
	s_addc_u32 s49, s47, 0
	s_add_i32 s77, s67, s43
	global_load_lds_dwordx4 v[128:129], off
	v_lshl_add_u64 v[128:129], s[48:49], 0, v[176:177]
	s_mov_b32 m0, s77
	s_add_i32 s78, s77, 0x2000
	global_load_lds_dwordx4 v[128:129], off
	v_lshl_add_u64 v[128:129], s[48:49], 0, v[178:179]
	s_mov_b32 m0, s78
	v_lshl_add_u64 v[208:209], s[44:45], 0, v[176:177]
	global_load_lds_dwordx4 v[128:129], off
	v_lshl_add_u64 v[128:129], v[208:209], 0, s[24:25]
	s_mov_b32 m0, s56
	v_lshl_add_u64 v[252:253], s[44:45], 0, v[178:179]
	global_load_lds_dwordx4 v[128:129], off
	s_mov_b32 m0, s57
	v_lshl_add_u64 v[128:129], v[252:253], 0, s[24:25]
	global_load_lds_dwordx4 v[128:129], off
	s_waitcnt vmcnt(8)
	s_waitcnt lgkmcnt(0)
	s_barrier
	s_setprio 1
	s_waitcnt lgkmcnt(0)
	v_mfma_f32_16x16x32_bf16 v[134:137], v[20:23], v[60:63], 0
	v_mfma_f32_16x16x32_bf16 v[142:145], v[20:23], v[92:95], 0
	v_mfma_f32_16x16x32_bf16 v[150:153], v[20:23], v[108:111], 0
	v_mfma_f32_16x16x32_bf16 v[20:23], v[20:23], v[120:123], 0
	v_mfma_f32_16x16x32_bf16 v[128:131], v[28:31], v[60:63], 0
	v_mfma_f32_16x16x32_bf16 v[134:137], v[16:19], v[88:91], v[134:137]
	v_mfma_f32_16x16x32_bf16 v[138:141], v[28:31], v[92:95], 0
	v_mfma_f32_16x16x32_bf16 v[142:145], v[16:19], v[104:107], v[142:145]
	v_mfma_f32_16x16x32_bf16 v[146:149], v[28:31], v[108:111], 0
	v_mfma_f32_16x16x32_bf16 v[150:153], v[16:19], v[116:119], v[150:153]
	v_mfma_f32_16x16x32_bf16 v[28:31], v[28:31], v[120:123], 0
	v_mfma_f32_16x16x32_bf16 v[16:19], v[16:19], v[124:127], v[20:23]
	v_mfma_f32_16x16x32_bf16 v[130:133], v[24:27], v[88:91], v[128:131]
	v_mfma_f32_16x16x32_bf16 v[138:141], v[24:27], v[104:107], v[138:141]
	v_mfma_f32_16x16x32_bf16 v[146:149], v[24:27], v[116:119], v[146:149]
	v_mfma_f32_16x16x32_bf16 v[154:157], v[24:27], v[124:127], v[28:31]
	s_setprio 0
	s_setprio 1
	v_mfma_f32_16x16x32_bf16 v[24:27], v[4:7], v[60:63], 0
	v_mfma_f32_16x16x32_bf16 v[158:161], v[0:3], v[88:91], v[24:27]
	v_mfma_f32_16x16x32_bf16 v[24:27], v[12:15], v[92:95], 0
	v_mfma_f32_16x16x32_bf16 v[162:165], v[8:11], v[104:107], v[24:27]
	v_mfma_f32_16x16x32_bf16 v[24:27], v[4:7], v[92:95], 0
	v_mfma_f32_16x16x32_bf16 v[166:169], v[0:3], v[104:107], v[24:27]
	v_mfma_f32_16x16x32_bf16 v[24:27], v[12:15], v[108:111], 0
	v_mfma_f32_16x16x32_bf16 v[20:23], v[12:15], v[60:63], 0
	v_mfma_f32_16x16x32_bf16 v[170:173], v[8:11], v[116:119], v[24:27]
	v_mfma_f32_16x16x32_bf16 v[24:27], v[4:7], v[108:111], 0
	v_mfma_f32_16x16x32_bf16 v[4:7], v[4:7], v[120:123], 0
	v_mfma_f32_16x16x32_bf16 v[20:23], v[8:11], v[88:91], v[20:23]
	s_setprio 2
	s_barrier
	v_mfma_f32_16x16x32_bf16 v[190:193], v[0:3], v[116:119], v[24:27]
	v_mfma_f32_16x16x32_bf16 v[12:15], v[12:15], v[120:123], 0
	v_mfma_f32_16x16x32_bf16 v[0:3], v[0:3], v[124:127], v[4:7]
	v_mfma_f32_16x16x32_bf16 v[196:199], v[8:11], v[124:127], v[12:15]
	s_setprio 0
	s_add_i32 s79, 0, 0x18000
	s_add_i32 s81, 0, 0x1c000
	v_add_u32_e32 v128, s79, v189
	v_add_u32_e32 v129, s81, v189
	ds_read_b128 v[4:7], v128
	ds_read_b128 v[8:11], v128 offset:1024
	ds_read_b128 v[204:207], v128 offset:2048
	ds_read_b128 v[212:215], v128 offset:3072
	ds_read_b128 v[216:219], v129
	ds_read_b128 v[220:223], v129 offset:1024
	ds_read_b128 v[224:227], v129 offset:2048
	ds_read_b128 v[228:231], v129 offset:3072
	s_add_u32 s48, s44, 0x80100
	s_addc_u32 s49, s45, 0
	s_mov_b32 m0, s58
	v_lshl_add_u64 v[88:89], s[48:49], 0, v[176:177]
	ds_read_b128 v[12:15], v211 offset:32768
	ds_read_b128 v[24:27], v211 offset:33792
	ds_read_b128 v[28:31], v211 offset:34816
	ds_read_b128 v[60:63], v211 offset:35840
	ds_read_b128 v[232:235], v211 offset:36864
	ds_read_b128 v[236:239], v211 offset:37888
	ds_read_b128 v[240:243], v211 offset:38912
	ds_read_b128 v[244:247], v211 offset:39936
	global_load_lds_dwordx4 v[88:89], off
	s_mov_b32 m0, s59
	v_lshl_add_u64 v[88:89], s[48:49], 0, v[178:179]
	global_load_lds_dwordx4 v[88:89], off
	s_waitcnt vmcnt(8)
	s_waitcnt lgkmcnt(0)
	s_barrier
	s_setprio 1
	s_waitcnt lgkmcnt(0)
	v_mfma_f32_16x16x32_bf16 v[64:67], v[4:7], v[12:15], v[64:67]
	v_mfma_f32_16x16x32_bf16 v[124:127], v[8:11], v[24:27], v[64:67]
	v_mfma_f32_16x16x32_bf16 v[64:67], v[204:207], v[12:15], v[68:71]
	v_mfma_f32_16x16x32_bf16 v[120:123], v[212:215], v[24:27], v[64:67]
	v_mfma_f32_16x16x32_bf16 v[64:67], v[4:7], v[28:31], v[72:75]
	v_mfma_f32_16x16x32_bf16 v[108:111], v[8:11], v[60:63], v[64:67]
	v_mfma_f32_16x16x32_bf16 v[64:67], v[204:207], v[28:31], v[76:79]
	v_mfma_f32_16x16x32_bf16 v[104:107], v[212:215], v[60:63], v[64:67]
	v_mfma_f32_16x16x32_bf16 v[64:67], v[4:7], v[232:235], v[80:83]
	v_mfma_f32_16x16x32_bf16 v[92:95], v[8:11], v[236:239], v[64:67]
	v_mfma_f32_16x16x32_bf16 v[64:67], v[204:207], v[232:235], v[84:87]
	v_mfma_f32_16x16x32_bf16 v[88:91], v[212:215], v[236:239], v[64:67]
	v_mfma_f32_16x16x32_bf16 v[64:67], v[4:7], v[240:243], v[96:99]
	v_mfma_f32_16x16x32_bf16 v[76:79], v[8:11], v[244:247], v[64:67]
	v_mfma_f32_16x16x32_bf16 v[64:67], v[204:207], v[240:243], v[100:103]
	v_mfma_f32_16x16x32_bf16 v[72:75], v[212:215], v[244:247], v[64:67]
	s_setprio 0
	s_setprio 1
	v_mfma_f32_16x16x32_bf16 v[64:67], v[216:219], v[12:15], v[112:115]
	v_mfma_f32_16x16x32_bf16 v[12:15], v[224:227], v[12:15], v[32:35]
	v_mfma_f32_16x16x32_bf16 v[112:115], v[228:231], v[24:27], v[12:15]
	v_mfma_f32_16x16x32_bf16 v[12:15], v[216:219], v[28:31], v[36:39]
	v_mfma_f32_16x16x32_bf16 v[100:103], v[220:223], v[60:63], v[12:15]
	v_mfma_f32_16x16x32_bf16 v[12:15], v[224:227], v[28:31], v[40:43]
	v_mfma_f32_16x16x32_bf16 v[96:99], v[228:231], v[60:63], v[12:15]
	v_mfma_f32_16x16x32_bf16 v[12:15], v[216:219], v[232:235], v[44:47]
	v_mfma_f32_16x16x32_bf16 v[84:87], v[220:223], v[236:239], v[12:15]
	v_mfma_f32_16x16x32_bf16 v[12:15], v[224:227], v[232:235], v[48:51]
	v_mfma_f32_16x16x32_bf16 v[80:83], v[228:231], v[236:239], v[12:15]
	v_mfma_f32_16x16x32_bf16 v[12:15], v[216:219], v[240:243], v[52:55]
	s_setprio 2
	s_barrier
	v_mfma_f32_16x16x32_bf16 v[68:71], v[220:223], v[244:247], v[12:15]
	v_mfma_f32_16x16x32_bf16 v[12:15], v[224:227], v[240:243], v[56:59]
	v_mfma_f32_16x16x32_bf16 v[116:119], v[220:223], v[24:27], v[64:67]
	v_mfma_f32_16x16x32_bf16 v[64:67], v[228:231], v[244:247], v[12:15]
	s_setprio 0
	s_add_i32 s79, s79, s43
	s_add_i32 s80, s79, 0x2000
	s_nop 1
	v_lshl_add_u64 v[12:13], v[174:175], 0, s[26:27]
	s_mov_b32 m0, s79
	s_add_u32 s48, s46, 0x80180
	ds_read_b128 v[32:35], v211 offset:49152
	ds_read_b128 v[36:39], v211 offset:50176
	ds_read_b128 v[232:235], v211 offset:51200
	ds_read_b128 v[236:239], v211 offset:52224
	ds_read_b128 v[240:243], v211 offset:53248
	ds_read_b128 v[244:247], v211 offset:54272
	ds_read_b128 v[248:251], v211 offset:55296
	ds_read_b128 v[184:187], v211 offset:56320
	global_load_lds_dwordx4 v[12:13], off
	v_lshl_add_u64 v[12:13], v[200:201], 0, s[26:27]
	s_mov_b32 m0, s80
	s_addc_u32 s49, s47, 0
	s_add_i32 s81, s81, s43
	global_load_lds_dwordx4 v[12:13], off
	v_lshl_add_u64 v[12:13], s[48:49], 0, v[176:177]
	s_mov_b32 m0, s81
	s_add_i32 s82, s81, 0x2000
	global_load_lds_dwordx4 v[12:13], off
	s_mov_b32 m0, s82
	v_lshl_add_u64 v[12:13], s[48:49], 0, v[178:179]
	global_load_lds_dwordx4 v[12:13], off
	s_mov_b32 m0, s61
	v_lshl_add_u64 v[12:13], v[208:209], 0, s[26:27]
	global_load_lds_dwordx4 v[12:13], off
	s_mov_b32 m0, s62
	v_lshl_add_u64 v[12:13], v[252:253], 0, s[26:27]
	global_load_lds_dwordx4 v[12:13], off
	s_waitcnt vmcnt(8)
	s_waitcnt lgkmcnt(0)
	s_barrier
	s_setprio 1
	s_waitcnt lgkmcnt(0)
	v_mfma_f32_16x16x32_bf16 v[12:15], v[4:7], v[32:35], v[130:133]
	v_mfma_f32_16x16x32_bf16 v[60:63], v[8:11], v[36:39], v[12:15]
	v_mfma_f32_16x16x32_bf16 v[12:15], v[204:207], v[32:35], v[134:137]
	v_mfma_f32_16x16x32_bf16 v[56:59], v[212:215], v[36:39], v[12:15]
	v_mfma_f32_16x16x32_bf16 v[12:15], v[4:7], v[232:235], v[138:141]
	v_mfma_f32_16x16x32_bf16 v[44:47], v[8:11], v[236:239], v[12:15]
	v_mfma_f32_16x16x32_bf16 v[12:15], v[204:207], v[232:235], v[142:145]
	v_mfma_f32_16x16x32_bf16 v[40:43], v[212:215], v[236:239], v[12:15]
	v_mfma_f32_16x16x32_bf16 v[12:15], v[4:7], v[240:243], v[146:149]
	v_mfma_f32_16x16x32_bf16 v[28:31], v[8:11], v[244:247], v[12:15]
	v_mfma_f32_16x16x32_bf16 v[12:15], v[204:207], v[240:243], v[150:153]
	v_mfma_f32_16x16x32_bf16 v[4:7], v[4:7], v[248:251], v[154:157]
	v_mfma_f32_16x16x32_bf16 v[24:27], v[212:215], v[244:247], v[12:15]
	v_mfma_f32_16x16x32_bf16 v[12:15], v[8:11], v[184:187], v[4:7]
	v_mfma_f32_16x16x32_bf16 v[4:7], v[204:207], v[248:251], v[16:19]
	v_mfma_f32_16x16x32_bf16 v[8:11], v[212:215], v[184:187], v[4:7]
	s_setprio 0
	s_setprio 1
	v_mfma_f32_16x16x32_bf16 v[4:7], v[216:219], v[32:35], v[20:23]
	v_mfma_f32_16x16x32_bf16 v[52:55], v[220:223], v[36:39], v[4:7]
	v_mfma_f32_16x16x32_bf16 v[4:7], v[224:227], v[32:35], v[158:161]
	v_mfma_f32_16x16x32_bf16 v[48:51], v[228:231], v[36:39], v[4:7]
	v_mfma_f32_16x16x32_bf16 v[4:7], v[216:219], v[232:235], v[162:165]
	v_mfma_f32_16x16x32_bf16 v[36:39], v[220:223], v[236:239], v[4:7]
	v_mfma_f32_16x16x32_bf16 v[4:7], v[224:227], v[232:235], v[166:169]
	v_mfma_f32_16x16x32_bf16 v[32:35], v[228:231], v[236:239], v[4:7]
	v_mfma_f32_16x16x32_bf16 v[4:7], v[216:219], v[240:243], v[170:173]
	v_mfma_f32_16x16x32_bf16 v[20:23], v[220:223], v[244:247], v[4:7]
	v_mfma_f32_16x16x32_bf16 v[4:7], v[224:227], v[240:243], v[190:193]
	v_mfma_f32_16x16x32_bf16 v[16:19], v[228:231], v[244:247], v[4:7]
	s_setprio 2
	s_barrier
	v_mfma_f32_16x16x32_bf16 v[4:7], v[216:219], v[248:251], v[196:199]
	v_mfma_f32_16x16x32_bf16 v[0:3], v[224:227], v[248:251], v[0:3]
	v_mfma_f32_16x16x32_bf16 v[4:7], v[220:223], v[184:187], v[4:7]
	v_mfma_f32_16x16x32_bf16 v[0:3], v[228:231], v[184:187], v[0:3]
	s_setprio 0
	s_add_u32 s44, s44, 0x80180
	s_addc_u32 s45, s45, 0
	s_add_u32 s83, s46, 0x200
	s_addc_u32 s84, s47, 0
	s_mov_b32 s46, 0
	s_add_i32 s85, s46, 2
	s_and_b32 s47, s85, 6
	s_cmp_lg_u32 s47, 0
	s_cbranch_scc1 .LBB0_700
	s_branch .LBB0_699

.LBB0_700:
	ds_read_b128 v[130:133], v203
	ds_read_b128 v[134:137], v203 offset:1024
	ds_read_b128 v[138:141], v203 offset:2048
	ds_read_b128 v[142:145], v203 offset:3072
	ds_read_b128 v[146:149], v195
	ds_read_b128 v[150:153], v195 offset:1024
	ds_read_b128 v[154:157], v195 offset:2048
	ds_read_b128 v[158:161], v195 offset:3072
	s_add_u32 s47, s44, 0xfff80080
	s_addc_u32 s48, s45, -1
	s_cmp_eq_u32 s46, 28
	s_cselect_b32 s49, s29, s48
	s_cselect_b32 s48, s71, s47
	s_cselect_b32 s47, s31, s84
	s_cselect_b32 s46, s72, s83
	s_mov_b32 m0, s73
	v_lshl_add_u64 v[174:175], s[44:45], 0, v[180:181]
	ds_read_b128 v[162:165], v211
	ds_read_b128 v[166:169], v211 offset:1024
	ds_read_b128 v[170:173], v211 offset:2048
	ds_read_b128 v[184:187], v211 offset:3072
	ds_read_b128 v[190:193], v211 offset:4096
	ds_read_b128 v[196:199], v211 offset:5120
	ds_read_b128 v[204:207], v211 offset:6144
	ds_read_b128 v[212:215], v211 offset:7168
	global_load_lds_dwordx4 v[174:175], off
	s_mov_b32 m0, s74
	v_lshl_add_u64 v[174:175], s[44:45], 0, v[182:183]
	global_load_lds_dwordx4 v[174:175], off
	s_waitcnt vmcnt(8)
	s_waitcnt lgkmcnt(0)
	s_barrier
	s_setprio 1
	s_waitcnt lgkmcnt(0)
	v_mfma_f32_16x16x32_bf16 v[124:127], v[130:133], v[162:165], v[124:127]
	v_mfma_f32_16x16x32_bf16 v[120:123], v[138:141], v[162:165], v[120:123]
	v_mfma_f32_16x16x32_bf16 v[108:111], v[130:133], v[170:173], v[108:111]
	v_mfma_f32_16x16x32_bf16 v[104:107], v[138:141], v[170:173], v[104:107]
	v_mfma_f32_16x16x32_bf16 v[92:95], v[130:133], v[190:193], v[92:95]
	v_mfma_f32_16x16x32_bf16 v[88:91], v[138:141], v[190:193], v[88:91]
	v_mfma_f32_16x16x32_bf16 v[76:79], v[130:133], v[204:207], v[76:79]
	v_mfma_f32_16x16x32_bf16 v[72:75], v[138:141], v[204:207], v[72:75]
	v_mfma_f32_16x16x32_bf16 v[124:127], v[134:137], v[166:169], v[124:127]
	v_mfma_f32_16x16x32_bf16 v[120:123], v[142:145], v[166:169], v[120:123]
	v_mfma_f32_16x16x32_bf16 v[108:111], v[134:137], v[184:187], v[108:111]
	v_mfma_f32_16x16x32_bf16 v[104:107], v[142:145], v[184:187], v[104:107]
	v_mfma_f32_16x16x32_bf16 v[92:95], v[134:137], v[196:199], v[92:95]
	v_mfma_f32_16x16x32_bf16 v[88:91], v[142:145], v[196:199], v[88:91]
	v_mfma_f32_16x16x32_bf16 v[76:79], v[134:137], v[212:215], v[76:79]
	v_mfma_f32_16x16x32_bf16 v[72:75], v[142:145], v[212:215], v[72:75]
	s_setprio 0
	s_setprio 1
	v_mfma_f32_16x16x32_bf16 v[116:119], v[146:149], v[162:165], v[116:119]
	v_mfma_f32_16x16x32_bf16 v[112:115], v[154:157], v[162:165], v[112:115]
	v_mfma_f32_16x16x32_bf16 v[100:103], v[146:149], v[170:173], v[100:103]
	v_mfma_f32_16x16x32_bf16 v[96:99], v[154:157], v[170:173], v[96:99]
	v_mfma_f32_16x16x32_bf16 v[84:87], v[146:149], v[190:193], v[84:87]
	v_mfma_f32_16x16x32_bf16 v[80:83], v[154:157], v[190:193], v[80:83]
	v_mfma_f32_16x16x32_bf16 v[68:71], v[146:149], v[204:207], v[68:71]
	v_mfma_f32_16x16x32_bf16 v[64:67], v[154:157], v[204:207], v[64:67]
	v_mfma_f32_16x16x32_bf16 v[116:119], v[150:153], v[166:169], v[116:119]
	v_mfma_f32_16x16x32_bf16 v[112:115], v[158:161], v[166:169], v[112:115]
	v_mfma_f32_16x16x32_bf16 v[100:103], v[150:153], v[184:187], v[100:103]
	v_mfma_f32_16x16x32_bf16 v[96:99], v[158:161], v[184:187], v[96:99]
	s_setprio 2
	s_barrier
	v_mfma_f32_16x16x32_bf16 v[84:87], v[150:153], v[196:199], v[84:87]
	v_mfma_f32_16x16x32_bf16 v[80:83], v[158:161], v[196:199], v[80:83]
	v_mfma_f32_16x16x32_bf16 v[68:71], v[150:153], v[212:215], v[68:71]
	v_mfma_f32_16x16x32_bf16 v[64:67], v[158:161], v[212:215], v[64:67]
	s_setprio 0
	s_mov_b32 m0, s75
	v_lshl_add_u64 v[174:175], s[46:47], 0, v[176:177]
	s_add_u32 s86, s46, 0x80000
	ds_read_b128 v[162:165], v211 offset:16384
	ds_read_b128 v[166:169], v211 offset:17408
	ds_read_b128 v[170:173], v211 offset:18432
	ds_read_b128 v[184:187], v211 offset:19456
	ds_read_b128 v[190:193], v211 offset:20480
	ds_read_b128 v[196:199], v211 offset:21504
	ds_read_b128 v[204:207], v211 offset:22528
	ds_read_b128 v[212:215], v211 offset:23552
	global_load_lds_dwordx4 v[174:175], off
	v_lshl_add_u64 v[200:201], s[46:47], 0, v[178:179]
	s_mov_b32 m0, s76
	s_addc_u32 s87, s47, 0
	global_load_lds_dwordx4 v[200:201], off
	v_lshl_add_u64 v[208:209], s[86:87], 0, v[176:177]
	s_mov_b32 m0, s77
	v_lshl_add_u64 v[216:217], s[48:49], 0, v[178:179]
	global_load_lds_dwordx4 v[208:209], off
	s_mov_b32 m0, s78
	v_lshl_add_u64 v[208:209], s[86:87], 0, v[178:179]
	global_load_lds_dwordx4 v[208:209], off
	s_mov_b32 m0, s56
	v_lshl_add_u64 v[208:209], s[48:49], 0, v[176:177]
	global_load_lds_dwordx4 v[208:209], off
	s_mov_b32 m0, s57
	s_nop 0
	global_load_lds_dwordx4 v[216:217], off
	s_waitcnt vmcnt(8)
	s_waitcnt lgkmcnt(0)
	s_barrier
	s_setprio 1
	s_waitcnt lgkmcnt(0)
	v_mfma_f32_16x16x32_bf16 v[60:63], v[130:133], v[162:165], v[60:63]
	v_mfma_f32_16x16x32_bf16 v[56:59], v[138:141], v[162:165], v[56:59]
	v_mfma_f32_16x16x32_bf16 v[44:47], v[130:133], v[170:173], v[44:47]
	v_mfma_f32_16x16x32_bf16 v[40:43], v[138:141], v[170:173], v[40:43]
	v_mfma_f32_16x16x32_bf16 v[28:31], v[130:133], v[190:193], v[28:31]
	v_mfma_f32_16x16x32_bf16 v[24:27], v[138:141], v[190:193], v[24:27]
	v_mfma_f32_16x16x32_bf16 v[12:15], v[130:133], v[204:207], v[12:15]
	v_mfma_f32_16x16x32_bf16 v[8:11], v[138:141], v[204:207], v[8:11]
	v_mfma_f32_16x16x32_bf16 v[60:63], v[134:137], v[166:169], v[60:63]
	v_mfma_f32_16x16x32_bf16 v[56:59], v[142:145], v[166:169], v[56:59]
	v_mfma_f32_16x16x32_bf16 v[44:47], v[134:137], v[184:187], v[44:47]
	v_mfma_f32_16x16x32_bf16 v[40:43], v[142:145], v[184:187], v[40:43]
	v_mfma_f32_16x16x32_bf16 v[28:31], v[134:137], v[196:199], v[28:31]
	v_mfma_f32_16x16x32_bf16 v[24:27], v[142:145], v[196:199], v[24:27]
	v_mfma_f32_16x16x32_bf16 v[12:15], v[134:137], v[212:215], v[12:15]
	v_mfma_f32_16x16x32_bf16 v[8:11], v[142:145], v[212:215], v[8:11]
	s_setprio 0
	s_setprio 1
	v_mfma_f32_16x16x32_bf16 v[52:55], v[146:149], v[162:165], v[52:55]
	v_mfma_f32_16x16x32_bf16 v[48:51], v[154:157], v[162:165], v[48:51]
	v_mfma_f32_16x16x32_bf16 v[36:39], v[146:149], v[170:173], v[36:39]
	v_mfma_f32_16x16x32_bf16 v[32:35], v[154:157], v[170:173], v[32:35]
	v_mfma_f32_16x16x32_bf16 v[20:23], v[146:149], v[190:193], v[20:23]
	v_mfma_f32_16x16x32_bf16 v[16:19], v[154:157], v[190:193], v[16:19]
	v_mfma_f32_16x16x32_bf16 v[4:7], v[146:149], v[204:207], v[4:7]
	v_mfma_f32_16x16x32_bf16 v[0:3], v[154:157], v[204:207], v[0:3]
	v_mfma_f32_16x16x32_bf16 v[52:55], v[150:153], v[166:169], v[52:55]
	v_mfma_f32_16x16x32_bf16 v[48:51], v[158:161], v[166:169], v[48:51]
	v_mfma_f32_16x16x32_bf16 v[36:39], v[150:153], v[184:187], v[36:39]
	v_mfma_f32_16x16x32_bf16 v[32:35], v[158:161], v[184:187], v[32:35]
	s_setprio 2
	s_barrier
	v_mfma_f32_16x16x32_bf16 v[20:23], v[150:153], v[196:199], v[20:23]
	v_mfma_f32_16x16x32_bf16 v[16:19], v[158:161], v[196:199], v[16:19]
	v_mfma_f32_16x16x32_bf16 v[4:7], v[150:153], v[212:215], v[4:7]
	v_mfma_f32_16x16x32_bf16 v[0:3], v[158:161], v[212:215], v[0:3]
	s_setprio 0
	ds_read_b128 v[130:133], v128
	ds_read_b128 v[134:137], v128 offset:1024
	ds_read_b128 v[138:141], v128 offset:2048
	ds_read_b128 v[142:145], v128 offset:3072
	ds_read_b128 v[146:149], v129
	ds_read_b128 v[150:153], v129 offset:1024
	ds_read_b128 v[154:157], v129 offset:2048
	ds_read_b128 v[158:161], v129 offset:3072
	s_add_u32 s48, s48, 0x80000
	s_addc_u32 s49, s49, 0
	s_mov_b32 m0, s58
	v_lshl_add_u64 v[218:219], s[48:49], 0, v[176:177]
	ds_read_b128 v[162:165], v211 offset:32768
	ds_read_b128 v[166:169], v211 offset:33792
	ds_read_b128 v[170:173], v211 offset:34816
	ds_read_b128 v[184:187], v211 offset:35840
	ds_read_b128 v[190:193], v211 offset:36864
	ds_read_b128 v[196:199], v211 offset:37888
	ds_read_b128 v[204:207], v211 offset:38912
	ds_read_b128 v[212:215], v211 offset:39936
	global_load_lds_dwordx4 v[218:219], off
	s_mov_b32 m0, s59
	v_lshl_add_u64 v[218:219], s[48:49], 0, v[178:179]
	global_load_lds_dwordx4 v[218:219], off
	s_waitcnt vmcnt(8)
	s_waitcnt lgkmcnt(0)
	s_barrier
	s_setprio 1
	s_waitcnt lgkmcnt(0)
	v_mfma_f32_16x16x32_bf16 v[124:127], v[130:133], v[162:165], v[124:127]
	v_mfma_f32_16x16x32_bf16 v[120:123], v[138:141], v[162:165], v[120:123]
	v_mfma_f32_16x16x32_bf16 v[108:111], v[130:133], v[170:173], v[108:111]
	v_mfma_f32_16x16x32_bf16 v[104:107], v[138:141], v[170:173], v[104:107]
	v_mfma_f32_16x16x32_bf16 v[92:95], v[130:133], v[190:193], v[92:95]
	v_mfma_f32_16x16x32_bf16 v[88:91], v[138:141], v[190:193], v[88:91]
	v_mfma_f32_16x16x32_bf16 v[76:79], v[130:133], v[204:207], v[76:79]
	v_mfma_f32_16x16x32_bf16 v[72:75], v[138:141], v[204:207], v[72:75]
	v_mfma_f32_16x16x32_bf16 v[124:127], v[134:137], v[166:169], v[124:127]
	v_mfma_f32_16x16x32_bf16 v[120:123], v[142:145], v[166:169], v[120:123]
	v_mfma_f32_16x16x32_bf16 v[108:111], v[134:137], v[184:187], v[108:111]
	v_mfma_f32_16x16x32_bf16 v[104:107], v[142:145], v[184:187], v[104:107]
	v_mfma_f32_16x16x32_bf16 v[92:95], v[134:137], v[196:199], v[92:95]
	v_mfma_f32_16x16x32_bf16 v[88:91], v[142:145], v[196:199], v[88:91]
	v_mfma_f32_16x16x32_bf16 v[76:79], v[134:137], v[212:215], v[76:79]
	v_mfma_f32_16x16x32_bf16 v[72:75], v[142:145], v[212:215], v[72:75]
	s_setprio 0
	s_setprio 1
	v_mfma_f32_16x16x32_bf16 v[116:119], v[146:149], v[162:165], v[116:119]
	v_mfma_f32_16x16x32_bf16 v[112:115], v[154:157], v[162:165], v[112:115]
	v_mfma_f32_16x16x32_bf16 v[100:103], v[146:149], v[170:173], v[100:103]
	v_mfma_f32_16x16x32_bf16 v[96:99], v[154:157], v[170:173], v[96:99]
	v_mfma_f32_16x16x32_bf16 v[84:87], v[146:149], v[190:193], v[84:87]
	v_mfma_f32_16x16x32_bf16 v[80:83], v[154:157], v[190:193], v[80:83]
	v_mfma_f32_16x16x32_bf16 v[68:71], v[146:149], v[204:207], v[68:71]
	v_mfma_f32_16x16x32_bf16 v[64:67], v[154:157], v[204:207], v[64:67]
	v_mfma_f32_16x16x32_bf16 v[116:119], v[150:153], v[166:169], v[116:119]
	v_mfma_f32_16x16x32_bf16 v[112:115], v[158:161], v[166:169], v[112:115]
	v_mfma_f32_16x16x32_bf16 v[100:103], v[150:153], v[184:187], v[100:103]
	v_mfma_f32_16x16x32_bf16 v[96:99], v[158:161], v[184:187], v[96:99]
	s_setprio 2
	s_barrier
	v_mfma_f32_16x16x32_bf16 v[84:87], v[150:153], v[196:199], v[84:87]
	v_mfma_f32_16x16x32_bf16 v[80:83], v[158:161], v[196:199], v[80:83]
	v_mfma_f32_16x16x32_bf16 v[68:71], v[150:153], v[212:215], v[68:71]
	v_mfma_f32_16x16x32_bf16 v[64:67], v[158:161], v[212:215], v[64:67]
	s_setprio 0
	s_mov_b32 m0, s79
	v_lshl_add_u64 v[174:175], v[174:175], 0, s[20:21]
	s_add_u32 s46, s46, 0x80080
	ds_read_b128 v[162:165], v211 offset:49152
	ds_read_b128 v[166:169], v211 offset:50176
	ds_read_b128 v[170:173], v211 offset:51200
	ds_read_b128 v[184:187], v211 offset:52224
	ds_read_b128 v[190:193], v211 offset:53248
	ds_read_b128 v[196:199], v211 offset:54272
	ds_read_b128 v[204:207], v211 offset:55296
	ds_read_b128 v[212:215], v211 offset:56320
	global_load_lds_dwordx4 v[174:175], off
	v_lshl_add_u64 v[174:175], v[200:201], 0, s[20:21]
	s_mov_b32 m0, s80
	s_addc_u32 s47, s47, 0
	global_load_lds_dwordx4 v[174:175], off
	s_mov_b32 m0, s81
	v_lshl_add_u64 v[174:175], s[46:47], 0, v[176:177]
	global_load_lds_dwordx4 v[174:175], off
	s_mov_b32 m0, s82
	v_lshl_add_u64 v[174:175], s[46:47], 0, v[178:179]
	global_load_lds_dwordx4 v[174:175], off
	s_mov_b32 m0, s61
	v_lshl_add_u64 v[174:175], v[208:209], 0, s[20:21]
	global_load_lds_dwordx4 v[174:175], off
	s_mov_b32 m0, s62
	v_lshl_add_u64 v[174:175], v[216:217], 0, s[20:21]
	global_load_lds_dwordx4 v[174:175], off
	s_waitcnt vmcnt(8)
	s_waitcnt lgkmcnt(0)
	s_barrier
	s_setprio 1
	s_waitcnt lgkmcnt(0)
	v_mfma_f32_16x16x32_bf16 v[60:63], v[130:133], v[162:165], v[60:63]
	v_mfma_f32_16x16x32_bf16 v[56:59], v[138:141], v[162:165], v[56:59]
	v_mfma_f32_16x16x32_bf16 v[44:47], v[130:133], v[170:173], v[44:47]
	v_mfma_f32_16x16x32_bf16 v[40:43], v[138:141], v[170:173], v[40:43]
	v_mfma_f32_16x16x32_bf16 v[28:31], v[130:133], v[190:193], v[28:31]
	v_mfma_f32_16x16x32_bf16 v[24:27], v[138:141], v[190:193], v[24:27]
	v_mfma_f32_16x16x32_bf16 v[12:15], v[130:133], v[204:207], v[12:15]
	v_mfma_f32_16x16x32_bf16 v[8:11], v[138:141], v[204:207], v[8:11]
	v_mfma_f32_16x16x32_bf16 v[60:63], v[134:137], v[166:169], v[60:63]
	v_mfma_f32_16x16x32_bf16 v[56:59], v[142:145], v[166:169], v[56:59]
	v_mfma_f32_16x16x32_bf16 v[44:47], v[134:137], v[184:187], v[44:47]
	v_mfma_f32_16x16x32_bf16 v[40:43], v[142:145], v[184:187], v[40:43]
	v_mfma_f32_16x16x32_bf16 v[28:31], v[134:137], v[196:199], v[28:31]
	v_mfma_f32_16x16x32_bf16 v[24:27], v[142:145], v[196:199], v[24:27]
	v_mfma_f32_16x16x32_bf16 v[12:15], v[134:137], v[212:215], v[12:15]
	v_mfma_f32_16x16x32_bf16 v[8:11], v[142:145], v[212:215], v[8:11]
	s_setprio 0
	s_setprio 1
	v_mfma_f32_16x16x32_bf16 v[52:55], v[146:149], v[162:165], v[52:55]
	v_mfma_f32_16x16x32_bf16 v[48:51], v[154:157], v[162:165], v[48:51]
	v_mfma_f32_16x16x32_bf16 v[36:39], v[146:149], v[170:173], v[36:39]
	v_mfma_f32_16x16x32_bf16 v[32:35], v[154:157], v[170:173], v[32:35]
	v_mfma_f32_16x16x32_bf16 v[20:23], v[146:149], v[190:193], v[20:23]
	v_mfma_f32_16x16x32_bf16 v[16:19], v[154:157], v[190:193], v[16:19]
	v_mfma_f32_16x16x32_bf16 v[4:7], v[146:149], v[204:207], v[4:7]
	v_mfma_f32_16x16x32_bf16 v[0:3], v[154:157], v[204:207], v[0:3]
	v_mfma_f32_16x16x32_bf16 v[52:55], v[150:153], v[166:169], v[52:55]
	v_mfma_f32_16x16x32_bf16 v[48:51], v[158:161], v[166:169], v[48:51]
	v_mfma_f32_16x16x32_bf16 v[36:39], v[150:153], v[184:187], v[36:39]
	v_mfma_f32_16x16x32_bf16 v[32:35], v[158:161], v[184:187], v[32:35]
	s_setprio 2
	s_barrier
	v_mfma_f32_16x16x32_bf16 v[20:23], v[150:153], v[196:199], v[20:23]
	v_mfma_f32_16x16x32_bf16 v[16:19], v[158:161], v[196:199], v[16:19]
	v_mfma_f32_16x16x32_bf16 v[4:7], v[150:153], v[212:215], v[4:7]
	v_mfma_f32_16x16x32_bf16 v[0:3], v[158:161], v[212:215], v[0:3]
	s_setprio 0
	s_add_i32 s70, s70, 1
	s_add_u32 s44, s44, 0x100
	s_addc_u32 s45, s45, 0
	s_add_u32 s83, s83, 0x100
	s_addc_u32 s84, s84, 0
	s_cmp_gt_u32 s85, 29
	s_cbranch_scc0 .LBB0_698
	s_lshl_b32 s29, s41, 12
	s_and_b32 s29, s29, 0x1000
	s_add_i32 s29, s29, 0
	v_mbcnt_lo_u32_b32 v128, -1, 0
	v_mbcnt_hi_u32_b32 v128, -1, v128
	s_add_i32 s29, s29, s63
	v_lshlrev_b32_e32 v128, 4, v128
	s_add_i32 s29, s29, 0x20400
	v_and_b32_e32 v128, 0xf0, v128
	v_add_u32_e32 v128, s29, v128
	ds_read2_b32 v[214:215], v128 offset0:3 offset1:67
	ds_read2_b32 v[206:207], v128 offset0:131 offset1:195
	v_add_u32_e32 v128, 12, v128
	ds_read2st64_b32 v[196:197], v128 offset0:8 offset1:9
	ds_read2st64_b32 v[190:191], v128 offset0:10 offset1:11
	s_and_b64 vcc, exec, s[22:23]
	s_waitcnt lgkmcnt(0)
	v_mov_b32_e32 v210, v215
	v_mov_b32_e32 v202, v207
	v_mov_b32_e32 v194, v197
	v_mov_b32_e32 v188, v191
	s_cbranch_vccz .LBB0_703
	s_barrier

.LBB0_783:
	s_ashr_i32 s23, s22, 31
	s_lshl_b64 s[26:27], s[22:23], 19
	s_add_u32 s26, s43, s26
	s_addc_u32 s27, s44, s27
	s_and_b64 s[28:29], s[4:5], exec
	s_cselect_b32 s23, s27, s37
	s_cselect_b32 s31, s26, s36
	s_ashr_i32 s25, s24, 31
	s_lshl_b64 s[28:29], s[24:25], 19
	s_add_u32 s28, s45, s28
	s_addc_u32 s29, s46, s29
	s_and_b64 s[40:41], s[4:5], exec
	s_cselect_b32 s25, s29, s39
	s_cselect_b32 s62, s28, s38
	s_add_u32 s36, s36, 0x40080
	s_addc_u32 s37, s37, 0
	s_add_u32 s63, s38, 0x100
	s_addc_u32 s64, s39, 0
	s_mov_b32 s65, -2
	ds_read_b128 v[144:147], v163
	ds_read_b128 v[148:151], v163 offset:1024
	ds_read_b128 v[152:155], v163 offset:2048
	ds_read_b128 v[156:159], v163 offset:3072
	ds_read_b128 v[168:171], v164
	ds_read_b128 v[172:175], v164 offset:1024
	ds_read_b128 v[176:179], v164 offset:2048
	ds_read_b128 v[180:183], v164 offset:3072
	s_add_u32 s38, s36, 0xfffc0080
	s_addc_u32 s39, s37, -1
	s_cmp_eq_u32 s65, 12
	s_cselect_b32 s41, s23, s39
	s_cselect_b32 s40, s31, s38
	s_cselect_b32 s39, s25, s64
	s_cselect_b32 s38, s62, s63
	v_lshl_add_u64 v[160:161], s[36:37], 0, v[136:137]
	s_add_i32 m0, s50, 0xc000
	ds_read_b128 v[184:187], v165
	ds_read_b128 v[188:191], v165 offset:1024
	ds_read_b128 v[192:195], v165 offset:2048
	ds_read_b128 v[196:199], v165 offset:3072
	ds_read_b128 v[200:203], v165 offset:4096
	ds_read_b128 v[204:207], v165 offset:5120
	ds_read_b128 v[208:211], v165 offset:6144
	ds_read_b128 v[212:215], v165 offset:7168
	global_load_lds_dwordx4 v[160:161], off
	s_add_i32 m0, s50, 0xe000
	v_lshl_add_u64 v[160:161], s[36:37], 0, v[138:139]
	global_load_lds_dwordx4 v[160:161], off
	s_waitcnt vmcnt(8)
	s_waitcnt lgkmcnt(0)
	s_barrier
	s_setprio 1
	s_waitcnt lgkmcnt(0)
	v_mfma_f32_16x16x32_bf16 v[124:127], v[144:147], v[184:187], 0
	v_mfma_f32_16x16x32_bf16 v[120:123], v[152:155], v[184:187], 0
	v_mfma_f32_16x16x32_bf16 v[108:111], v[144:147], v[192:195], 0
	v_mfma_f32_16x16x32_bf16 v[104:107], v[152:155], v[192:195], 0
	v_mfma_f32_16x16x32_bf16 v[92:95], v[144:147], v[200:203], 0
	v_mfma_f32_16x16x32_bf16 v[88:91], v[152:155], v[200:203], 0
	v_mfma_f32_16x16x32_bf16 v[76:79], v[144:147], v[208:211], 0
	v_mfma_f32_16x16x32_bf16 v[72:75], v[152:155], v[208:211], 0
	v_mfma_f32_16x16x32_bf16 v[124:127], v[148:151], v[188:191], v[124:127]
	v_mfma_f32_16x16x32_bf16 v[120:123], v[156:159], v[188:191], v[120:123]
	v_mfma_f32_16x16x32_bf16 v[108:111], v[148:151], v[196:199], v[108:111]
	v_mfma_f32_16x16x32_bf16 v[104:107], v[156:159], v[196:199], v[104:107]
	v_mfma_f32_16x16x32_bf16 v[92:95], v[148:151], v[204:207], v[92:95]
	v_mfma_f32_16x16x32_bf16 v[88:91], v[156:159], v[204:207], v[88:91]
	v_mfma_f32_16x16x32_bf16 v[76:79], v[148:151], v[212:215], v[76:79]
	v_mfma_f32_16x16x32_bf16 v[72:75], v[156:159], v[212:215], v[72:75]
	s_setprio 0
	s_setprio 1
	v_mfma_f32_16x16x32_bf16 v[116:119], v[168:171], v[184:187], 0
	v_mfma_f32_16x16x32_bf16 v[112:115], v[176:179], v[184:187], 0
	v_mfma_f32_16x16x32_bf16 v[100:103], v[168:171], v[192:195], 0
	v_mfma_f32_16x16x32_bf16 v[96:99], v[176:179], v[192:195], 0
	v_mfma_f32_16x16x32_bf16 v[84:87], v[168:171], v[200:203], 0
	v_mfma_f32_16x16x32_bf16 v[80:83], v[176:179], v[200:203], 0
	v_mfma_f32_16x16x32_bf16 v[68:71], v[168:171], v[208:211], 0
	v_mfma_f32_16x16x32_bf16 v[64:67], v[176:179], v[208:211], 0
	v_mfma_f32_16x16x32_bf16 v[116:119], v[172:175], v[188:191], v[116:119]
	v_mfma_f32_16x16x32_bf16 v[112:115], v[180:183], v[188:191], v[112:115]
	v_mfma_f32_16x16x32_bf16 v[100:103], v[172:175], v[196:199], v[100:103]
	v_mfma_f32_16x16x32_bf16 v[96:99], v[180:183], v[196:199], v[96:99]
	s_setprio 2
	s_barrier
	v_mfma_f32_16x16x32_bf16 v[84:87], v[172:175], v[204:207], v[84:87]
	v_mfma_f32_16x16x32_bf16 v[80:83], v[180:183], v[204:207], v[80:83]
	v_mfma_f32_16x16x32_bf16 v[68:71], v[172:175], v[212:215], v[68:71]
	v_mfma_f32_16x16x32_bf16 v[64:67], v[180:183], v[212:215], v[64:67]
	s_setprio 0
	s_add_i32 s66, s59, s47
	v_lshl_add_u64 v[160:161], s[38:39], 0, v[132:133]
	s_mov_b32 m0, s66
	ds_read_b128 v[184:187], v165 offset:16384
	ds_read_b128 v[188:191], v165 offset:17408
	ds_read_b128 v[192:195], v165 offset:18432
	ds_read_b128 v[196:199], v165 offset:19456
	ds_read_b128 v[200:203], v165 offset:20480
	ds_read_b128 v[204:207], v165 offset:21504
	ds_read_b128 v[208:211], v165 offset:22528
	ds_read_b128 v[212:215], v165 offset:23552
	global_load_lds_dwordx4 v[160:161], off
	s_add_i32 m0, s66, 0x2000
	s_add_u32 s66, s38, 0x40000
	v_lshl_add_u64 v[216:217], s[38:39], 0, v[128:129]
	s_addc_u32 s67, s39, 0
	s_add_i32 s68, s60, s47
	global_load_lds_dwordx4 v[216:217], off
	v_lshl_add_u64 v[218:219], s[66:67], 0, v[132:133]
	s_mov_b32 m0, s68
	v_lshl_add_u64 v[220:221], s[40:41], 0, v[130:131]
	global_load_lds_dwordx4 v[218:219], off
	s_add_i32 m0, s68, 0x2000
	v_lshl_add_u64 v[218:219], s[66:67], 0, v[128:129]
	global_load_lds_dwordx4 v[218:219], off
	s_mov_b32 m0, s50
	v_lshl_add_u64 v[218:219], s[40:41], 0, v[134:135]
	global_load_lds_dwordx4 v[218:219], off
	s_mov_b32 m0, s51
	s_nop 0
	global_load_lds_dwordx4 v[220:221], off
	s_waitcnt vmcnt(8)
	s_waitcnt lgkmcnt(0)
	s_barrier
	s_setprio 1
	s_waitcnt lgkmcnt(0)
	v_mfma_f32_16x16x32_bf16 v[60:63], v[144:147], v[184:187], 0
	v_mfma_f32_16x16x32_bf16 v[56:59], v[152:155], v[184:187], 0
	v_mfma_f32_16x16x32_bf16 v[44:47], v[144:147], v[192:195], 0
	v_mfma_f32_16x16x32_bf16 v[40:43], v[152:155], v[192:195], 0
	v_mfma_f32_16x16x32_bf16 v[28:31], v[144:147], v[200:203], 0
	v_mfma_f32_16x16x32_bf16 v[24:27], v[152:155], v[200:203], 0
	v_mfma_f32_16x16x32_bf16 v[12:15], v[144:147], v[208:211], 0
	v_mfma_f32_16x16x32_bf16 v[8:11], v[152:155], v[208:211], 0
	v_mfma_f32_16x16x32_bf16 v[60:63], v[148:151], v[188:191], v[60:63]
	v_mfma_f32_16x16x32_bf16 v[56:59], v[156:159], v[188:191], v[56:59]
	v_mfma_f32_16x16x32_bf16 v[44:47], v[148:151], v[196:199], v[44:47]
	v_mfma_f32_16x16x32_bf16 v[40:43], v[156:159], v[196:199], v[40:43]
	v_mfma_f32_16x16x32_bf16 v[28:31], v[148:151], v[204:207], v[28:31]
	v_mfma_f32_16x16x32_bf16 v[24:27], v[156:159], v[204:207], v[24:27]
	v_mfma_f32_16x16x32_bf16 v[12:15], v[148:151], v[212:215], v[12:15]
	v_mfma_f32_16x16x32_bf16 v[8:11], v[156:159], v[212:215], v[8:11]
	s_setprio 0
	s_setprio 1
	v_mfma_f32_16x16x32_bf16 v[52:55], v[168:171], v[184:187], 0
	v_mfma_f32_16x16x32_bf16 v[48:51], v[176:179], v[184:187], 0
	v_mfma_f32_16x16x32_bf16 v[36:39], v[168:171], v[192:195], 0
	v_mfma_f32_16x16x32_bf16 v[32:35], v[176:179], v[192:195], 0
	v_mfma_f32_16x16x32_bf16 v[20:23], v[168:171], v[200:203], 0
	v_mfma_f32_16x16x32_bf16 v[16:19], v[176:179], v[200:203], 0
	v_mfma_f32_16x16x32_bf16 v[4:7], v[168:171], v[208:211], 0
	v_mfma_f32_16x16x32_bf16 v[0:3], v[176:179], v[208:211], 0
	v_mfma_f32_16x16x32_bf16 v[52:55], v[172:175], v[188:191], v[52:55]
	v_mfma_f32_16x16x32_bf16 v[48:51], v[180:183], v[188:191], v[48:51]
	v_mfma_f32_16x16x32_bf16 v[36:39], v[172:175], v[196:199], v[36:39]
	v_mfma_f32_16x16x32_bf16 v[32:35], v[180:183], v[196:199], v[32:35]
	s_setprio 2
	s_barrier
	v_mfma_f32_16x16x32_bf16 v[20:23], v[172:175], v[204:207], v[20:23]
	v_mfma_f32_16x16x32_bf16 v[16:19], v[180:183], v[204:207], v[16:19]
	v_mfma_f32_16x16x32_bf16 v[4:7], v[172:175], v[212:215], v[4:7]
	v_mfma_f32_16x16x32_bf16 v[0:3], v[180:183], v[212:215], v[0:3]
	s_setprio 0
	s_add_i32 s66, 0, 0x18000
	s_add_i32 s67, 0, 0x1c000
	v_add_u32_e32 v156, s66, v162
	v_add_u32_e32 v167, s67, v162
	ds_read_b128 v[144:147], v156
	ds_read_b128 v[148:151], v156 offset:1024
	ds_read_b128 v[152:155], v156 offset:2048
	ds_read_b128 v[156:159], v156 offset:3072
	ds_read_b128 v[168:171], v167
	ds_read_b128 v[172:175], v167 offset:1024
	ds_read_b128 v[176:179], v167 offset:2048
	ds_read_b128 v[180:183], v167 offset:3072
	s_add_u32 s40, s40, 0x40000
	s_addc_u32 s41, s41, 0
	s_mov_b32 m0, s54
	v_lshl_add_u64 v[222:223], s[40:41], 0, v[134:135]
	ds_read_b128 v[184:187], v165 offset:32768
	ds_read_b128 v[188:191], v165 offset:33792
	ds_read_b128 v[192:195], v165 offset:34816
	ds_read_b128 v[196:199], v165 offset:35840
	ds_read_b128 v[200:203], v165 offset:36864
	ds_read_b128 v[204:207], v165 offset:37888
	ds_read_b128 v[208:211], v165 offset:38912
	ds_read_b128 v[212:215], v165 offset:39936
	global_load_lds_dwordx4 v[222:223], off
	s_mov_b32 m0, s55
	v_lshl_add_u64 v[222:223], s[40:41], 0, v[130:131]
	global_load_lds_dwordx4 v[222:223], off
	s_waitcnt vmcnt(8)
	s_waitcnt lgkmcnt(0)
	s_barrier
	s_setprio 1
	s_waitcnt lgkmcnt(0)
	v_mfma_f32_16x16x32_bf16 v[124:127], v[144:147], v[184:187], v[124:127]
	v_mfma_f32_16x16x32_bf16 v[120:123], v[152:155], v[184:187], v[120:123]
	v_mfma_f32_16x16x32_bf16 v[108:111], v[144:147], v[192:195], v[108:111]
	v_mfma_f32_16x16x32_bf16 v[104:107], v[152:155], v[192:195], v[104:107]
	v_mfma_f32_16x16x32_bf16 v[92:95], v[144:147], v[200:203], v[92:95]
	v_mfma_f32_16x16x32_bf16 v[88:91], v[152:155], v[200:203], v[88:91]
	v_mfma_f32_16x16x32_bf16 v[76:79], v[144:147], v[208:211], v[76:79]
	v_mfma_f32_16x16x32_bf16 v[72:75], v[152:155], v[208:211], v[72:75]
	v_mfma_f32_16x16x32_bf16 v[124:127], v[148:151], v[188:191], v[124:127]
	v_mfma_f32_16x16x32_bf16 v[120:123], v[156:159], v[188:191], v[120:123]
	v_mfma_f32_16x16x32_bf16 v[108:111], v[148:151], v[196:199], v[108:111]
	v_mfma_f32_16x16x32_bf16 v[104:107], v[156:159], v[196:199], v[104:107]
	v_mfma_f32_16x16x32_bf16 v[92:95], v[148:151], v[204:207], v[92:95]
	v_mfma_f32_16x16x32_bf16 v[88:91], v[156:159], v[204:207], v[88:91]
	v_mfma_f32_16x16x32_bf16 v[76:79], v[148:151], v[212:215], v[76:79]
	v_mfma_f32_16x16x32_bf16 v[72:75], v[156:159], v[212:215], v[72:75]
	s_setprio 0
	s_setprio 1
	v_mfma_f32_16x16x32_bf16 v[116:119], v[168:171], v[184:187], v[116:119]
	v_mfma_f32_16x16x32_bf16 v[112:115], v[176:179], v[184:187], v[112:115]
	v_mfma_f32_16x16x32_bf16 v[100:103], v[168:171], v[192:195], v[100:103]
	v_mfma_f32_16x16x32_bf16 v[96:99], v[176:179], v[192:195], v[96:99]
	v_mfma_f32_16x16x32_bf16 v[84:87], v[168:171], v[200:203], v[84:87]
	v_mfma_f32_16x16x32_bf16 v[80:83], v[176:179], v[200:203], v[80:83]
	v_mfma_f32_16x16x32_bf16 v[68:71], v[168:171], v[208:211], v[68:71]
	v_mfma_f32_16x16x32_bf16 v[64:67], v[176:179], v[208:211], v[64:67]
	v_mfma_f32_16x16x32_bf16 v[116:119], v[172:175], v[188:191], v[116:119]
	v_mfma_f32_16x16x32_bf16 v[112:115], v[180:183], v[188:191], v[112:115]
	v_mfma_f32_16x16x32_bf16 v[100:103], v[172:175], v[196:199], v[100:103]
	v_mfma_f32_16x16x32_bf16 v[96:99], v[180:183], v[196:199], v[96:99]
	s_setprio 2
	s_barrier
	v_mfma_f32_16x16x32_bf16 v[84:87], v[172:175], v[204:207], v[84:87]
	v_mfma_f32_16x16x32_bf16 v[80:83], v[180:183], v[204:207], v[80:83]
	v_mfma_f32_16x16x32_bf16 v[68:71], v[172:175], v[212:215], v[68:71]
	v_mfma_f32_16x16x32_bf16 v[64:67], v[180:183], v[212:215], v[64:67]
	s_setprio 0
	s_add_i32 s40, s66, s47
	v_lshl_add_u64 v[160:161], v[160:161], 0, s[16:17]
	s_mov_b32 m0, s40
	ds_read_b128 v[184:187], v165 offset:49152
	ds_read_b128 v[188:191], v165 offset:50176
	ds_read_b128 v[192:195], v165 offset:51200
	ds_read_b128 v[196:199], v165 offset:52224
	ds_read_b128 v[200:203], v165 offset:53248
	ds_read_b128 v[204:207], v165 offset:54272
	ds_read_b128 v[208:211], v165 offset:55296
	ds_read_b128 v[212:215], v165 offset:56320
	global_load_lds_dwordx4 v[160:161], off
	s_add_i32 m0, s40, 0x2000
	s_add_u32 s38, s38, 0x40080
	v_lshl_add_u64 v[160:161], v[216:217], 0, s[16:17]
	s_addc_u32 s39, s39, 0
	s_add_i32 s40, s67, s47
	global_load_lds_dwordx4 v[160:161], off
	s_mov_b32 m0, s40
	v_lshl_add_u64 v[160:161], s[38:39], 0, v[132:133]
	global_load_lds_dwordx4 v[160:161], off
	s_add_i32 m0, s40, 0x2000
	v_lshl_add_u64 v[160:161], s[38:39], 0, v[128:129]
	global_load_lds_dwordx4 v[160:161], off
	s_mov_b32 m0, s57
	v_lshl_add_u64 v[160:161], v[218:219], 0, s[16:17]
	global_load_lds_dwordx4 v[160:161], off
	s_mov_b32 m0, s58
	v_lshl_add_u64 v[160:161], v[220:221], 0, s[16:17]
	global_load_lds_dwordx4 v[160:161], off
	s_waitcnt vmcnt(8)
	s_waitcnt lgkmcnt(0)
	s_barrier
	s_setprio 1
	s_waitcnt lgkmcnt(0)
	v_mfma_f32_16x16x32_bf16 v[60:63], v[144:147], v[184:187], v[60:63]
	v_mfma_f32_16x16x32_bf16 v[56:59], v[152:155], v[184:187], v[56:59]
	v_mfma_f32_16x16x32_bf16 v[44:47], v[144:147], v[192:195], v[44:47]
	v_mfma_f32_16x16x32_bf16 v[40:43], v[152:155], v[192:195], v[40:43]
	v_mfma_f32_16x16x32_bf16 v[28:31], v[144:147], v[200:203], v[28:31]
	v_mfma_f32_16x16x32_bf16 v[24:27], v[152:155], v[200:203], v[24:27]
	v_mfma_f32_16x16x32_bf16 v[12:15], v[144:147], v[208:211], v[12:15]
	v_mfma_f32_16x16x32_bf16 v[8:11], v[152:155], v[208:211], v[8:11]
	v_mfma_f32_16x16x32_bf16 v[60:63], v[148:151], v[188:191], v[60:63]
	v_mfma_f32_16x16x32_bf16 v[56:59], v[156:159], v[188:191], v[56:59]
	v_mfma_f32_16x16x32_bf16 v[44:47], v[148:151], v[196:199], v[44:47]
	v_mfma_f32_16x16x32_bf16 v[40:43], v[156:159], v[196:199], v[40:43]
	v_mfma_f32_16x16x32_bf16 v[28:31], v[148:151], v[204:207], v[28:31]
	v_mfma_f32_16x16x32_bf16 v[24:27], v[156:159], v[204:207], v[24:27]
	v_mfma_f32_16x16x32_bf16 v[12:15], v[148:151], v[212:215], v[12:15]
	v_mfma_f32_16x16x32_bf16 v[8:11], v[156:159], v[212:215], v[8:11]
	s_setprio 0
	s_setprio 1
	v_mfma_f32_16x16x32_bf16 v[52:55], v[168:171], v[184:187], v[52:55]
	v_mfma_f32_16x16x32_bf16 v[48:51], v[176:179], v[184:187], v[48:51]
	v_mfma_f32_16x16x32_bf16 v[36:39], v[168:171], v[192:195], v[36:39]
	v_mfma_f32_16x16x32_bf16 v[32:35], v[176:179], v[192:195], v[32:35]
	v_mfma_f32_16x16x32_bf16 v[20:23], v[168:171], v[200:203], v[20:23]
	v_mfma_f32_16x16x32_bf16 v[16:19], v[176:179], v[200:203], v[16:19]
	v_mfma_f32_16x16x32_bf16 v[4:7], v[168:171], v[208:211], v[4:7]
	v_mfma_f32_16x16x32_bf16 v[0:3], v[176:179], v[208:211], v[0:3]
	v_mfma_f32_16x16x32_bf16 v[52:55], v[172:175], v[188:191], v[52:55]
	v_mfma_f32_16x16x32_bf16 v[48:51], v[180:183], v[188:191], v[48:51]
	v_mfma_f32_16x16x32_bf16 v[36:39], v[172:175], v[196:199], v[36:39]
	v_mfma_f32_16x16x32_bf16 v[32:35], v[180:183], v[196:199], v[32:35]
	s_setprio 2
	s_barrier
	v_mfma_f32_16x16x32_bf16 v[20:23], v[172:175], v[204:207], v[20:23]
	v_mfma_f32_16x16x32_bf16 v[16:19], v[180:183], v[204:207], v[16:19]
	v_mfma_f32_16x16x32_bf16 v[4:7], v[172:175], v[212:215], v[4:7]
	v_mfma_f32_16x16x32_bf16 v[0:3], v[180:183], v[212:215], v[0:3]
	s_setprio 0
	s_add_i32 s65, s65, 2
	s_add_u32 s36, s36, 0x100
	s_addc_u32 s37, s37, 0
	s_add_u32 s63, s63, 0x100
	s_addc_u32 s64, s64, 0
	s_cmp_gt_u32 s65, 13
.LBB0_784:
	ds_read_b128 v[144:147], v163
	ds_read_b128 v[148:151], v163 offset:1024
	ds_read_b128 v[152:155], v163 offset:2048
	ds_read_b128 v[156:159], v163 offset:3072
	ds_read_b128 v[168:171], v164
	ds_read_b128 v[172:175], v164 offset:1024
	ds_read_b128 v[176:179], v164 offset:2048
	ds_read_b128 v[180:183], v164 offset:3072
	s_add_u32 s38, s36, 0xfffc0080
	s_addc_u32 s39, s37, -1
	s_cmp_eq_u32 s65, 12
	s_cselect_b32 s41, s23, s39
	s_cselect_b32 s40, s31, s38
	s_cselect_b32 s39, s25, s64
	s_cselect_b32 s38, s62, s63
	v_lshl_add_u64 v[160:161], s[36:37], 0, v[136:137]
	s_add_i32 m0, s50, 0xc000
	ds_read_b128 v[184:187], v165
	ds_read_b128 v[188:191], v165 offset:1024
	ds_read_b128 v[192:195], v165 offset:2048
	ds_read_b128 v[196:199], v165 offset:3072
	ds_read_b128 v[200:203], v165 offset:4096
	ds_read_b128 v[204:207], v165 offset:5120
	ds_read_b128 v[208:211], v165 offset:6144
	ds_read_b128 v[212:215], v165 offset:7168
	global_load_lds_dwordx4 v[160:161], off
	s_add_i32 m0, s50, 0xe000
	v_lshl_add_u64 v[160:161], s[36:37], 0, v[138:139]
	global_load_lds_dwordx4 v[160:161], off
	s_waitcnt vmcnt(8)
	s_waitcnt lgkmcnt(0)
	s_barrier
	s_setprio 1
	s_waitcnt lgkmcnt(0)
	v_mfma_f32_16x16x32_bf16 v[124:127], v[144:147], v[184:187], v[124:127]
	v_mfma_f32_16x16x32_bf16 v[120:123], v[152:155], v[184:187], v[120:123]
	v_mfma_f32_16x16x32_bf16 v[108:111], v[144:147], v[192:195], v[108:111]
	v_mfma_f32_16x16x32_bf16 v[104:107], v[152:155], v[192:195], v[104:107]
	v_mfma_f32_16x16x32_bf16 v[92:95], v[144:147], v[200:203], v[92:95]
	v_mfma_f32_16x16x32_bf16 v[88:91], v[152:155], v[200:203], v[88:91]
	v_mfma_f32_16x16x32_bf16 v[76:79], v[144:147], v[208:211], v[76:79]
	v_mfma_f32_16x16x32_bf16 v[72:75], v[152:155], v[208:211], v[72:75]
	v_mfma_f32_16x16x32_bf16 v[124:127], v[148:151], v[188:191], v[124:127]
	v_mfma_f32_16x16x32_bf16 v[120:123], v[156:159], v[188:191], v[120:123]
	v_mfma_f32_16x16x32_bf16 v[108:111], v[148:151], v[196:199], v[108:111]
	v_mfma_f32_16x16x32_bf16 v[104:107], v[156:159], v[196:199], v[104:107]
	v_mfma_f32_16x16x32_bf16 v[92:95], v[148:151], v[204:207], v[92:95]
	v_mfma_f32_16x16x32_bf16 v[88:91], v[156:159], v[204:207], v[88:91]
	v_mfma_f32_16x16x32_bf16 v[76:79], v[148:151], v[212:215], v[76:79]
	v_mfma_f32_16x16x32_bf16 v[72:75], v[156:159], v[212:215], v[72:75]
	s_setprio 0
	s_setprio 1
	v_mfma_f32_16x16x32_bf16 v[116:119], v[168:171], v[184:187], v[116:119]
	v_mfma_f32_16x16x32_bf16 v[112:115], v[176:179], v[184:187], v[112:115]
	v_mfma_f32_16x16x32_bf16 v[100:103], v[168:171], v[192:195], v[100:103]
	v_mfma_f32_16x16x32_bf16 v[96:99], v[176:179], v[192:195], v[96:99]
	v_mfma_f32_16x16x32_bf16 v[84:87], v[168:171], v[200:203], v[84:87]
	v_mfma_f32_16x16x32_bf16 v[80:83], v[176:179], v[200:203], v[80:83]
	v_mfma_f32_16x16x32_bf16 v[68:71], v[168:171], v[208:211], v[68:71]
	v_mfma_f32_16x16x32_bf16 v[64:67], v[176:179], v[208:211], v[64:67]
	v_mfma_f32_16x16x32_bf16 v[116:119], v[172:175], v[188:191], v[116:119]
	v_mfma_f32_16x16x32_bf16 v[112:115], v[180:183], v[188:191], v[112:115]
	v_mfma_f32_16x16x32_bf16 v[100:103], v[172:175], v[196:199], v[100:103]
	v_mfma_f32_16x16x32_bf16 v[96:99], v[180:183], v[196:199], v[96:99]
	s_setprio 2
	s_barrier
	v_mfma_f32_16x16x32_bf16 v[84:87], v[172:175], v[204:207], v[84:87]
	v_mfma_f32_16x16x32_bf16 v[80:83], v[180:183], v[204:207], v[80:83]
	v_mfma_f32_16x16x32_bf16 v[68:71], v[172:175], v[212:215], v[68:71]
	v_mfma_f32_16x16x32_bf16 v[64:67], v[180:183], v[212:215], v[64:67]
	s_setprio 0
	s_add_i32 s66, s59, s47
	v_lshl_add_u64 v[160:161], s[38:39], 0, v[132:133]
	s_mov_b32 m0, s66
	ds_read_b128 v[184:187], v165 offset:16384
	ds_read_b128 v[188:191], v165 offset:17408
	ds_read_b128 v[192:195], v165 offset:18432
	ds_read_b128 v[196:199], v165 offset:19456
	ds_read_b128 v[200:203], v165 offset:20480
	ds_read_b128 v[204:207], v165 offset:21504
	ds_read_b128 v[208:211], v165 offset:22528
	ds_read_b128 v[212:215], v165 offset:23552
	global_load_lds_dwordx4 v[160:161], off
	s_add_i32 m0, s66, 0x2000
	s_add_u32 s66, s38, 0x40000
	v_lshl_add_u64 v[216:217], s[38:39], 0, v[128:129]
	s_addc_u32 s67, s39, 0
	s_add_i32 s68, s60, s47
	global_load_lds_dwordx4 v[216:217], off
	v_lshl_add_u64 v[218:219], s[66:67], 0, v[132:133]
	s_mov_b32 m0, s68
	v_lshl_add_u64 v[220:221], s[40:41], 0, v[130:131]
	global_load_lds_dwordx4 v[218:219], off
	s_add_i32 m0, s68, 0x2000
	v_lshl_add_u64 v[218:219], s[66:67], 0, v[128:129]
	global_load_lds_dwordx4 v[218:219], off
	s_mov_b32 m0, s50
	v_lshl_add_u64 v[218:219], s[40:41], 0, v[134:135]
	global_load_lds_dwordx4 v[218:219], off
	s_mov_b32 m0, s51
	s_nop 0
	global_load_lds_dwordx4 v[220:221], off
	s_waitcnt vmcnt(8)
	s_waitcnt lgkmcnt(0)
	s_barrier
	s_setprio 1
	s_waitcnt lgkmcnt(0)
	v_mfma_f32_16x16x32_bf16 v[60:63], v[144:147], v[184:187], v[60:63]
	v_mfma_f32_16x16x32_bf16 v[56:59], v[152:155], v[184:187], v[56:59]
	v_mfma_f32_16x16x32_bf16 v[44:47], v[144:147], v[192:195], v[44:47]
	v_mfma_f32_16x16x32_bf16 v[40:43], v[152:155], v[192:195], v[40:43]
	v_mfma_f32_16x16x32_bf16 v[28:31], v[144:147], v[200:203], v[28:31]
	v_mfma_f32_16x16x32_bf16 v[24:27], v[152:155], v[200:203], v[24:27]
	v_mfma_f32_16x16x32_bf16 v[12:15], v[144:147], v[208:211], v[12:15]
	v_mfma_f32_16x16x32_bf16 v[8:11], v[152:155], v[208:211], v[8:11]
	v_mfma_f32_16x16x32_bf16 v[60:63], v[148:151], v[188:191], v[60:63]
	v_mfma_f32_16x16x32_bf16 v[56:59], v[156:159], v[188:191], v[56:59]
	v_mfma_f32_16x16x32_bf16 v[44:47], v[148:151], v[196:199], v[44:47]
	v_mfma_f32_16x16x32_bf16 v[40:43], v[156:159], v[196:199], v[40:43]
	v_mfma_f32_16x16x32_bf16 v[28:31], v[148:151], v[204:207], v[28:31]
	v_mfma_f32_16x16x32_bf16 v[24:27], v[156:159], v[204:207], v[24:27]
	v_mfma_f32_16x16x32_bf16 v[12:15], v[148:151], v[212:215], v[12:15]
	v_mfma_f32_16x16x32_bf16 v[8:11], v[156:159], v[212:215], v[8:11]
	s_setprio 0
	s_setprio 1
	v_mfma_f32_16x16x32_bf16 v[52:55], v[168:171], v[184:187], v[52:55]
	v_mfma_f32_16x16x32_bf16 v[48:51], v[176:179], v[184:187], v[48:51]
	v_mfma_f32_16x16x32_bf16 v[36:39], v[168:171], v[192:195], v[36:39]
	v_mfma_f32_16x16x32_bf16 v[32:35], v[176:179], v[192:195], v[32:35]
	v_mfma_f32_16x16x32_bf16 v[20:23], v[168:171], v[200:203], v[20:23]
	v_mfma_f32_16x16x32_bf16 v[16:19], v[176:179], v[200:203], v[16:19]
	v_mfma_f32_16x16x32_bf16 v[4:7], v[168:171], v[208:211], v[4:7]
	v_mfma_f32_16x16x32_bf16 v[0:3], v[176:179], v[208:211], v[0:3]
	v_mfma_f32_16x16x32_bf16 v[52:55], v[172:175], v[188:191], v[52:55]
	v_mfma_f32_16x16x32_bf16 v[48:51], v[180:183], v[188:191], v[48:51]
	v_mfma_f32_16x16x32_bf16 v[36:39], v[172:175], v[196:199], v[36:39]
	v_mfma_f32_16x16x32_bf16 v[32:35], v[180:183], v[196:199], v[32:35]
	s_setprio 2
	s_barrier
	v_mfma_f32_16x16x32_bf16 v[20:23], v[172:175], v[204:207], v[20:23]
	v_mfma_f32_16x16x32_bf16 v[16:19], v[180:183], v[204:207], v[16:19]
	v_mfma_f32_16x16x32_bf16 v[4:7], v[172:175], v[212:215], v[4:7]
	v_mfma_f32_16x16x32_bf16 v[0:3], v[180:183], v[212:215], v[0:3]
	s_setprio 0
	s_add_i32 s66, 0, 0x18000
	s_add_i32 s67, 0, 0x1c000
	v_add_u32_e32 v156, s66, v162
	v_add_u32_e32 v167, s67, v162
	ds_read_b128 v[144:147], v156
	ds_read_b128 v[148:151], v156 offset:1024
	ds_read_b128 v[152:155], v156 offset:2048
	ds_read_b128 v[156:159], v156 offset:3072
	ds_read_b128 v[168:171], v167
	ds_read_b128 v[172:175], v167 offset:1024
	ds_read_b128 v[176:179], v167 offset:2048
	ds_read_b128 v[180:183], v167 offset:3072
	s_add_u32 s40, s40, 0x40000
	s_addc_u32 s41, s41, 0
	s_mov_b32 m0, s54
	v_lshl_add_u64 v[222:223], s[40:41], 0, v[134:135]
	ds_read_b128 v[184:187], v165 offset:32768
	ds_read_b128 v[188:191], v165 offset:33792
	ds_read_b128 v[192:195], v165 offset:34816
	ds_read_b128 v[196:199], v165 offset:35840
	ds_read_b128 v[200:203], v165 offset:36864
	ds_read_b128 v[204:207], v165 offset:37888
	ds_read_b128 v[208:211], v165 offset:38912
	ds_read_b128 v[212:215], v165 offset:39936
	global_load_lds_dwordx4 v[222:223], off
	s_mov_b32 m0, s55
	v_lshl_add_u64 v[222:223], s[40:41], 0, v[130:131]
	global_load_lds_dwordx4 v[222:223], off
	s_waitcnt vmcnt(8)
	s_waitcnt lgkmcnt(0)
	s_barrier
	s_setprio 1
	s_waitcnt lgkmcnt(0)
	v_mfma_f32_16x16x32_bf16 v[124:127], v[144:147], v[184:187], v[124:127]
	v_mfma_f32_16x16x32_bf16 v[120:123], v[152:155], v[184:187], v[120:123]
	v_mfma_f32_16x16x32_bf16 v[108:111], v[144:147], v[192:195], v[108:111]
	v_mfma_f32_16x16x32_bf16 v[104:107], v[152:155], v[192:195], v[104:107]
	v_mfma_f32_16x16x32_bf16 v[92:95], v[144:147], v[200:203], v[92:95]
	v_mfma_f32_16x16x32_bf16 v[88:91], v[152:155], v[200:203], v[88:91]
	v_mfma_f32_16x16x32_bf16 v[76:79], v[144:147], v[208:211], v[76:79]
	v_mfma_f32_16x16x32_bf16 v[72:75], v[152:155], v[208:211], v[72:75]
	v_mfma_f32_16x16x32_bf16 v[124:127], v[148:151], v[188:191], v[124:127]
	v_mfma_f32_16x16x32_bf16 v[120:123], v[156:159], v[188:191], v[120:123]
	v_mfma_f32_16x16x32_bf16 v[108:111], v[148:151], v[196:199], v[108:111]
	v_mfma_f32_16x16x32_bf16 v[104:107], v[156:159], v[196:199], v[104:107]
	v_mfma_f32_16x16x32_bf16 v[92:95], v[148:151], v[204:207], v[92:95]
	v_mfma_f32_16x16x32_bf16 v[88:91], v[156:159], v[204:207], v[88:91]
	v_mfma_f32_16x16x32_bf16 v[76:79], v[148:151], v[212:215], v[76:79]
	v_mfma_f32_16x16x32_bf16 v[72:75], v[156:159], v[212:215], v[72:75]
	s_setprio 0
	s_setprio 1
	v_mfma_f32_16x16x32_bf16 v[116:119], v[168:171], v[184:187], v[116:119]
	v_mfma_f32_16x16x32_bf16 v[112:115], v[176:179], v[184:187], v[112:115]
	v_mfma_f32_16x16x32_bf16 v[100:103], v[168:171], v[192:195], v[100:103]
	v_mfma_f32_16x16x32_bf16 v[96:99], v[176:179], v[192:195], v[96:99]
	v_mfma_f32_16x16x32_bf16 v[84:87], v[168:171], v[200:203], v[84:87]
	v_mfma_f32_16x16x32_bf16 v[80:83], v[176:179], v[200:203], v[80:83]
	v_mfma_f32_16x16x32_bf16 v[68:71], v[168:171], v[208:211], v[68:71]
	v_mfma_f32_16x16x32_bf16 v[64:67], v[176:179], v[208:211], v[64:67]
	v_mfma_f32_16x16x32_bf16 v[116:119], v[172:175], v[188:191], v[116:119]
	v_mfma_f32_16x16x32_bf16 v[112:115], v[180:183], v[188:191], v[112:115]
	v_mfma_f32_16x16x32_bf16 v[100:103], v[172:175], v[196:199], v[100:103]
	v_mfma_f32_16x16x32_bf16 v[96:99], v[180:183], v[196:199], v[96:99]
	s_setprio 2
	s_barrier
	v_mfma_f32_16x16x32_bf16 v[84:87], v[172:175], v[204:207], v[84:87]
	v_mfma_f32_16x16x32_bf16 v[80:83], v[180:183], v[204:207], v[80:83]
	v_mfma_f32_16x16x32_bf16 v[68:71], v[172:175], v[212:215], v[68:71]
	v_mfma_f32_16x16x32_bf16 v[64:67], v[180:183], v[212:215], v[64:67]
	s_setprio 0
	s_add_i32 s40, s66, s47
	v_lshl_add_u64 v[160:161], v[160:161], 0, s[16:17]
	s_mov_b32 m0, s40
	ds_read_b128 v[184:187], v165 offset:49152
	ds_read_b128 v[188:191], v165 offset:50176
	ds_read_b128 v[192:195], v165 offset:51200
	ds_read_b128 v[196:199], v165 offset:52224
	ds_read_b128 v[200:203], v165 offset:53248
	ds_read_b128 v[204:207], v165 offset:54272
	ds_read_b128 v[208:211], v165 offset:55296
	ds_read_b128 v[212:215], v165 offset:56320
	global_load_lds_dwordx4 v[160:161], off
	s_add_i32 m0, s40, 0x2000
	s_add_u32 s38, s38, 0x40080
	v_lshl_add_u64 v[160:161], v[216:217], 0, s[16:17]
	s_addc_u32 s39, s39, 0
	s_add_i32 s40, s67, s47
	global_load_lds_dwordx4 v[160:161], off
	s_mov_b32 m0, s40
	v_lshl_add_u64 v[160:161], s[38:39], 0, v[132:133]
	global_load_lds_dwordx4 v[160:161], off
	s_add_i32 m0, s40, 0x2000
	v_lshl_add_u64 v[160:161], s[38:39], 0, v[128:129]
	global_load_lds_dwordx4 v[160:161], off
	s_mov_b32 m0, s57
	v_lshl_add_u64 v[160:161], v[218:219], 0, s[16:17]
	global_load_lds_dwordx4 v[160:161], off
	s_mov_b32 m0, s58
	v_lshl_add_u64 v[160:161], v[220:221], 0, s[16:17]
	global_load_lds_dwordx4 v[160:161], off
	s_waitcnt vmcnt(8)
	s_waitcnt lgkmcnt(0)
	s_barrier
	s_setprio 1
	s_waitcnt lgkmcnt(0)
	v_mfma_f32_16x16x32_bf16 v[60:63], v[144:147], v[184:187], v[60:63]
	v_mfma_f32_16x16x32_bf16 v[56:59], v[152:155], v[184:187], v[56:59]
	v_mfma_f32_16x16x32_bf16 v[44:47], v[144:147], v[192:195], v[44:47]
	v_mfma_f32_16x16x32_bf16 v[40:43], v[152:155], v[192:195], v[40:43]
	v_mfma_f32_16x16x32_bf16 v[28:31], v[144:147], v[200:203], v[28:31]
	v_mfma_f32_16x16x32_bf16 v[24:27], v[152:155], v[200:203], v[24:27]
	v_mfma_f32_16x16x32_bf16 v[12:15], v[144:147], v[208:211], v[12:15]
	v_mfma_f32_16x16x32_bf16 v[8:11], v[152:155], v[208:211], v[8:11]
	v_mfma_f32_16x16x32_bf16 v[60:63], v[148:151], v[188:191], v[60:63]
	v_mfma_f32_16x16x32_bf16 v[56:59], v[156:159], v[188:191], v[56:59]
	v_mfma_f32_16x16x32_bf16 v[44:47], v[148:151], v[196:199], v[44:47]
	v_mfma_f32_16x16x32_bf16 v[40:43], v[156:159], v[196:199], v[40:43]
	v_mfma_f32_16x16x32_bf16 v[28:31], v[148:151], v[204:207], v[28:31]
	v_mfma_f32_16x16x32_bf16 v[24:27], v[156:159], v[204:207], v[24:27]
	v_mfma_f32_16x16x32_bf16 v[12:15], v[148:151], v[212:215], v[12:15]
	v_mfma_f32_16x16x32_bf16 v[8:11], v[156:159], v[212:215], v[8:11]
	s_setprio 0
	s_setprio 1
	v_mfma_f32_16x16x32_bf16 v[52:55], v[168:171], v[184:187], v[52:55]
	v_mfma_f32_16x16x32_bf16 v[48:51], v[176:179], v[184:187], v[48:51]
	v_mfma_f32_16x16x32_bf16 v[36:39], v[168:171], v[192:195], v[36:39]
	v_mfma_f32_16x16x32_bf16 v[32:35], v[176:179], v[192:195], v[32:35]
	v_mfma_f32_16x16x32_bf16 v[20:23], v[168:171], v[200:203], v[20:23]
	v_mfma_f32_16x16x32_bf16 v[16:19], v[176:179], v[200:203], v[16:19]
	v_mfma_f32_16x16x32_bf16 v[4:7], v[168:171], v[208:211], v[4:7]
	v_mfma_f32_16x16x32_bf16 v[0:3], v[176:179], v[208:211], v[0:3]
	v_mfma_f32_16x16x32_bf16 v[52:55], v[172:175], v[188:191], v[52:55]
	v_mfma_f32_16x16x32_bf16 v[48:51], v[180:183], v[188:191], v[48:51]
	v_mfma_f32_16x16x32_bf16 v[36:39], v[172:175], v[196:199], v[36:39]
	v_mfma_f32_16x16x32_bf16 v[32:35], v[180:183], v[196:199], v[32:35]
	s_setprio 2
	s_barrier
	v_mfma_f32_16x16x32_bf16 v[20:23], v[172:175], v[204:207], v[20:23]
	v_mfma_f32_16x16x32_bf16 v[16:19], v[180:183], v[204:207], v[16:19]
	v_mfma_f32_16x16x32_bf16 v[4:7], v[172:175], v[212:215], v[4:7]
	v_mfma_f32_16x16x32_bf16 v[0:3], v[180:183], v[212:215], v[0:3]
	s_setprio 0
	s_add_i32 s65, s65, 2
	s_add_u32 s36, s36, 0x100
	s_addc_u32 s37, s37, 0
	s_add_u32 s63, s63, 0x100
	s_addc_u32 s64, s64, 0
	s_cmp_gt_u32 s65, 13
	s_cbranch_scc0 .LBB0_784

.LBB0_865:
	s_add_u32 s62, s28, 0x100
	s_addc_u32 s63, s29, 0
	s_mov_b32 s64, -2
	ds_read_b128 v[120:123], v233
	ds_read_b128 v[124:127], v233 offset:1024
	ds_read_b128 v[136:139], v233 offset:2048
	ds_read_b128 v[140:143], v233 offset:3072
	ds_read_b128 v[144:147], v234
	ds_read_b128 v[148:151], v234 offset:1024
	ds_read_b128 v[152:155], v234 offset:2048
	ds_read_b128 v[156:159], v234 offset:3072
	s_add_u32 s28, s26, 0x100
	s_addc_u32 s29, s27, 0
	s_cmp_eq_u32 s64, 40
	s_cselect_b32 s37, s7, s29
	s_cselect_b32 s36, s6, s28
	s_cselect_b32 s31, s25, s63
	s_cselect_b32 s30, s24, s62
	v_lshl_add_u64 v[208:209], s[26:27], 0, v[192:193]
	s_add_i32 m0, s44, 0xc000
	ds_read_b128 v[160:163], v235
	ds_read_b128 v[164:167], v235 offset:1024
	ds_read_b128 v[168:171], v235 offset:2048
	ds_read_b128 v[172:175], v235 offset:3072
	ds_read_b128 v[176:179], v235 offset:4096
	ds_read_b128 v[180:183], v235 offset:5120
	ds_read_b128 v[200:203], v235 offset:6144
	ds_read_b128 v[204:207], v235 offset:7168
	global_load_lds_dwordx4 v[208:209], off
	s_add_i32 m0, s44, 0xe000
	v_lshl_add_u64 v[208:209], s[26:27], 0, v[194:195]
	global_load_lds_dwordx4 v[208:209], off
	s_waitcnt vmcnt(8)
	s_waitcnt lgkmcnt(0)
	s_barrier
	s_setprio 1
	s_waitcnt lgkmcnt(0)
	v_mfma_f32_16x16x32_bf16 v[132:135], v[120:123], v[160:163], 0
	v_mfma_f32_16x16x32_bf16 v[128:131], v[136:139], v[160:163], 0
	v_mfma_f32_16x16x32_bf16 v[108:111], v[120:123], v[168:171], 0
	v_mfma_f32_16x16x32_bf16 v[104:107], v[136:139], v[168:171], 0
	v_mfma_f32_16x16x32_bf16 v[92:95], v[120:123], v[176:179], 0
	v_mfma_f32_16x16x32_bf16 v[88:91], v[136:139], v[176:179], 0
	v_mfma_f32_16x16x32_bf16 v[76:79], v[120:123], v[200:203], 0
	v_mfma_f32_16x16x32_bf16 v[72:75], v[136:139], v[200:203], 0
	v_mfma_f32_16x16x32_bf16 v[132:135], v[124:127], v[164:167], v[132:135]
	v_mfma_f32_16x16x32_bf16 v[128:131], v[140:143], v[164:167], v[128:131]
	v_mfma_f32_16x16x32_bf16 v[108:111], v[124:127], v[172:175], v[108:111]
	v_mfma_f32_16x16x32_bf16 v[104:107], v[140:143], v[172:175], v[104:107]
	v_mfma_f32_16x16x32_bf16 v[92:95], v[124:127], v[180:183], v[92:95]
	v_mfma_f32_16x16x32_bf16 v[88:91], v[140:143], v[180:183], v[88:91]
	v_mfma_f32_16x16x32_bf16 v[76:79], v[124:127], v[204:207], v[76:79]
	v_mfma_f32_16x16x32_bf16 v[72:75], v[140:143], v[204:207], v[72:75]
	s_setprio 0
	s_setprio 1
	v_mfma_f32_16x16x32_bf16 v[116:119], v[144:147], v[160:163], 0
	v_mfma_f32_16x16x32_bf16 v[112:115], v[152:155], v[160:163], 0
	v_mfma_f32_16x16x32_bf16 v[100:103], v[144:147], v[168:171], 0
	v_mfma_f32_16x16x32_bf16 v[96:99], v[152:155], v[168:171], 0
	v_mfma_f32_16x16x32_bf16 v[84:87], v[144:147], v[176:179], 0
	v_mfma_f32_16x16x32_bf16 v[80:83], v[152:155], v[176:179], 0
	v_mfma_f32_16x16x32_bf16 v[68:71], v[144:147], v[200:203], 0
	v_mfma_f32_16x16x32_bf16 v[64:67], v[152:155], v[200:203], 0
	v_mfma_f32_16x16x32_bf16 v[116:119], v[148:151], v[164:167], v[116:119]
	v_mfma_f32_16x16x32_bf16 v[112:115], v[156:159], v[164:167], v[112:115]
	v_mfma_f32_16x16x32_bf16 v[100:103], v[148:151], v[172:175], v[100:103]
	v_mfma_f32_16x16x32_bf16 v[96:99], v[156:159], v[172:175], v[96:99]
	s_setprio 2
	s_barrier
	v_mfma_f32_16x16x32_bf16 v[84:87], v[148:151], v[180:183], v[84:87]
	v_mfma_f32_16x16x32_bf16 v[80:83], v[156:159], v[180:183], v[80:83]
	v_mfma_f32_16x16x32_bf16 v[68:71], v[148:151], v[204:207], v[68:71]
	v_mfma_f32_16x16x32_bf16 v[64:67], v[156:159], v[204:207], v[64:67]
	s_setprio 0
	s_add_i32 s26, s56, s43
	v_lshl_add_u64 v[208:209], s[30:31], 0, v[186:187]
	s_mov_b32 m0, s26
	ds_read_b128 v[160:163], v235 offset:16384
	ds_read_b128 v[164:167], v235 offset:17408
	ds_read_b128 v[168:171], v235 offset:18432
	ds_read_b128 v[172:175], v235 offset:19456
	ds_read_b128 v[176:179], v235 offset:20480
	ds_read_b128 v[180:183], v235 offset:21504
	ds_read_b128 v[200:203], v235 offset:22528
	ds_read_b128 v[204:207], v235 offset:23552
	global_load_lds_dwordx4 v[208:209], off
	s_add_i32 m0, s26, 0x2000
	s_add_u32 s26, s30, 0xb0000
	v_lshl_add_u64 v[210:211], s[30:31], 0, v[190:191]
	s_addc_u32 s27, s31, 0
	s_add_i32 s65, s57, s43
	global_load_lds_dwordx4 v[210:211], off
	v_lshl_add_u64 v[212:213], s[26:27], 0, v[186:187]
	s_mov_b32 m0, s65
	v_lshl_add_u64 v[214:215], s[36:37], 0, v[188:189]
	global_load_lds_dwordx4 v[212:213], off
	s_add_i32 m0, s65, 0x2000
	v_lshl_add_u64 v[212:213], s[26:27], 0, v[190:191]
	global_load_lds_dwordx4 v[212:213], off
	s_mov_b32 m0, s44
	v_lshl_add_u64 v[212:213], s[36:37], 0, v[184:185]
	global_load_lds_dwordx4 v[212:213], off
	s_mov_b32 m0, s45
	s_nop 0
	global_load_lds_dwordx4 v[214:215], off
	s_waitcnt vmcnt(8)
	s_waitcnt lgkmcnt(0)
	s_barrier
	s_setprio 1
	s_waitcnt lgkmcnt(0)
	v_mfma_f32_16x16x32_bf16 v[60:63], v[120:123], v[160:163], 0
	v_mfma_f32_16x16x32_bf16 v[56:59], v[136:139], v[160:163], 0
	v_mfma_f32_16x16x32_bf16 v[44:47], v[120:123], v[168:171], 0
	v_mfma_f32_16x16x32_bf16 v[40:43], v[136:139], v[168:171], 0
	v_mfma_f32_16x16x32_bf16 v[28:31], v[120:123], v[176:179], 0
	v_mfma_f32_16x16x32_bf16 v[24:27], v[136:139], v[176:179], 0
	v_mfma_f32_16x16x32_bf16 v[12:15], v[120:123], v[200:203], 0
	v_mfma_f32_16x16x32_bf16 v[8:11], v[136:139], v[200:203], 0
	v_mfma_f32_16x16x32_bf16 v[60:63], v[124:127], v[164:167], v[60:63]
	v_mfma_f32_16x16x32_bf16 v[56:59], v[140:143], v[164:167], v[56:59]
	v_mfma_f32_16x16x32_bf16 v[44:47], v[124:127], v[172:175], v[44:47]
	v_mfma_f32_16x16x32_bf16 v[40:43], v[140:143], v[172:175], v[40:43]
	v_mfma_f32_16x16x32_bf16 v[28:31], v[124:127], v[180:183], v[28:31]
	v_mfma_f32_16x16x32_bf16 v[24:27], v[140:143], v[180:183], v[24:27]
	v_mfma_f32_16x16x32_bf16 v[12:15], v[124:127], v[204:207], v[12:15]
	v_mfma_f32_16x16x32_bf16 v[8:11], v[140:143], v[204:207], v[8:11]
	s_setprio 0
	s_setprio 1
	v_mfma_f32_16x16x32_bf16 v[52:55], v[144:147], v[160:163], 0
	v_mfma_f32_16x16x32_bf16 v[48:51], v[152:155], v[160:163], 0
	v_mfma_f32_16x16x32_bf16 v[36:39], v[144:147], v[168:171], 0
	v_mfma_f32_16x16x32_bf16 v[32:35], v[152:155], v[168:171], 0
	v_mfma_f32_16x16x32_bf16 v[20:23], v[144:147], v[176:179], 0
	v_mfma_f32_16x16x32_bf16 v[16:19], v[152:155], v[176:179], 0
	v_mfma_f32_16x16x32_bf16 v[4:7], v[144:147], v[200:203], 0
	v_mfma_f32_16x16x32_bf16 v[0:3], v[152:155], v[200:203], 0
	v_mfma_f32_16x16x32_bf16 v[52:55], v[148:151], v[164:167], v[52:55]
	v_mfma_f32_16x16x32_bf16 v[48:51], v[156:159], v[164:167], v[48:51]
	v_mfma_f32_16x16x32_bf16 v[36:39], v[148:151], v[172:175], v[36:39]
	v_mfma_f32_16x16x32_bf16 v[32:35], v[156:159], v[172:175], v[32:35]
	s_setprio 2
	s_barrier
	v_mfma_f32_16x16x32_bf16 v[20:23], v[148:151], v[180:183], v[20:23]
	v_mfma_f32_16x16x32_bf16 v[16:19], v[156:159], v[180:183], v[16:19]
	v_mfma_f32_16x16x32_bf16 v[4:7], v[148:151], v[204:207], v[4:7]
	v_mfma_f32_16x16x32_bf16 v[0:3], v[156:159], v[204:207], v[0:3]
	s_setprio 0
	s_add_i32 s65, 0, 0x18000
	s_add_i32 s66, 0, 0x1c000
	v_add_u32_e32 v140, s65, v232
	v_add_u32_e32 v156, s66, v232
	ds_read_b128 v[120:123], v140
	ds_read_b128 v[124:127], v140 offset:1024
	ds_read_b128 v[136:139], v140 offset:2048
	ds_read_b128 v[140:143], v140 offset:3072
	ds_read_b128 v[144:147], v156
	ds_read_b128 v[148:151], v156 offset:1024
	ds_read_b128 v[152:155], v156 offset:2048
	ds_read_b128 v[156:159], v156 offset:3072
	s_add_u32 s26, s36, 0xb0000
	s_addc_u32 s27, s37, 0
	s_mov_b32 m0, s46
	v_lshl_add_u64 v[216:217], s[26:27], 0, v[184:185]
	ds_read_b128 v[160:163], v235 offset:32768
	ds_read_b128 v[164:167], v235 offset:33792
	ds_read_b128 v[168:171], v235 offset:34816
	ds_read_b128 v[172:175], v235 offset:35840
	ds_read_b128 v[176:179], v235 offset:36864
	ds_read_b128 v[180:183], v235 offset:37888
	ds_read_b128 v[200:203], v235 offset:38912
	ds_read_b128 v[204:207], v235 offset:39936
	global_load_lds_dwordx4 v[216:217], off
	s_mov_b32 m0, s47
	v_lshl_add_u64 v[216:217], s[26:27], 0, v[188:189]
	global_load_lds_dwordx4 v[216:217], off
	s_waitcnt vmcnt(8)
	s_waitcnt lgkmcnt(0)
	s_barrier
	s_setprio 1
	s_waitcnt lgkmcnt(0)
	v_mfma_f32_16x16x32_bf16 v[132:135], v[120:123], v[160:163], v[132:135]
	v_mfma_f32_16x16x32_bf16 v[128:131], v[136:139], v[160:163], v[128:131]
	v_mfma_f32_16x16x32_bf16 v[108:111], v[120:123], v[168:171], v[108:111]
	v_mfma_f32_16x16x32_bf16 v[104:107], v[136:139], v[168:171], v[104:107]
	v_mfma_f32_16x16x32_bf16 v[92:95], v[120:123], v[176:179], v[92:95]
	v_mfma_f32_16x16x32_bf16 v[88:91], v[136:139], v[176:179], v[88:91]
	v_mfma_f32_16x16x32_bf16 v[76:79], v[120:123], v[200:203], v[76:79]
	v_mfma_f32_16x16x32_bf16 v[72:75], v[136:139], v[200:203], v[72:75]
	v_mfma_f32_16x16x32_bf16 v[132:135], v[124:127], v[164:167], v[132:135]
	v_mfma_f32_16x16x32_bf16 v[128:131], v[140:143], v[164:167], v[128:131]
	v_mfma_f32_16x16x32_bf16 v[108:111], v[124:127], v[172:175], v[108:111]
	v_mfma_f32_16x16x32_bf16 v[104:107], v[140:143], v[172:175], v[104:107]
	v_mfma_f32_16x16x32_bf16 v[92:95], v[124:127], v[180:183], v[92:95]
	v_mfma_f32_16x16x32_bf16 v[88:91], v[140:143], v[180:183], v[88:91]
	v_mfma_f32_16x16x32_bf16 v[76:79], v[124:127], v[204:207], v[76:79]
	v_mfma_f32_16x16x32_bf16 v[72:75], v[140:143], v[204:207], v[72:75]
	s_setprio 0
	s_setprio 1
	v_mfma_f32_16x16x32_bf16 v[116:119], v[144:147], v[160:163], v[116:119]
	v_mfma_f32_16x16x32_bf16 v[112:115], v[152:155], v[160:163], v[112:115]
	v_mfma_f32_16x16x32_bf16 v[100:103], v[144:147], v[168:171], v[100:103]
	v_mfma_f32_16x16x32_bf16 v[96:99], v[152:155], v[168:171], v[96:99]
	v_mfma_f32_16x16x32_bf16 v[84:87], v[144:147], v[176:179], v[84:87]
	v_mfma_f32_16x16x32_bf16 v[80:83], v[152:155], v[176:179], v[80:83]
	v_mfma_f32_16x16x32_bf16 v[68:71], v[144:147], v[200:203], v[68:71]
	v_mfma_f32_16x16x32_bf16 v[64:67], v[152:155], v[200:203], v[64:67]
	v_mfma_f32_16x16x32_bf16 v[116:119], v[148:151], v[164:167], v[116:119]
	v_mfma_f32_16x16x32_bf16 v[112:115], v[156:159], v[164:167], v[112:115]
	v_mfma_f32_16x16x32_bf16 v[100:103], v[148:151], v[172:175], v[100:103]
	v_mfma_f32_16x16x32_bf16 v[96:99], v[156:159], v[172:175], v[96:99]
	s_setprio 2
	s_barrier
	v_mfma_f32_16x16x32_bf16 v[84:87], v[148:151], v[180:183], v[84:87]
	v_mfma_f32_16x16x32_bf16 v[80:83], v[156:159], v[180:183], v[80:83]
	v_mfma_f32_16x16x32_bf16 v[68:71], v[148:151], v[204:207], v[68:71]
	v_mfma_f32_16x16x32_bf16 v[64:67], v[156:159], v[204:207], v[64:67]
	s_setprio 0
	s_add_i32 s26, s65, s43
	v_lshl_add_u64 v[208:209], v[208:209], 0, s[20:21]
	s_mov_b32 m0, s26
	ds_read_b128 v[160:163], v235 offset:49152
	ds_read_b128 v[164:167], v235 offset:50176
	ds_read_b128 v[168:171], v235 offset:51200
	ds_read_b128 v[172:175], v235 offset:52224
	ds_read_b128 v[176:179], v235 offset:53248
	ds_read_b128 v[180:183], v235 offset:54272
	ds_read_b128 v[200:203], v235 offset:55296
	ds_read_b128 v[204:207], v235 offset:56320
	global_load_lds_dwordx4 v[208:209], off
	s_add_i32 m0, s26, 0x2000
	s_add_u32 s26, s30, 0xb0080
	v_lshl_add_u64 v[208:209], v[210:211], 0, s[20:21]
	s_addc_u32 s27, s31, 0
	s_add_i32 s30, s66, s43
	global_load_lds_dwordx4 v[208:209], off
	s_mov_b32 m0, s30
	v_lshl_add_u64 v[208:209], s[26:27], 0, v[186:187]
	global_load_lds_dwordx4 v[208:209], off
	s_add_i32 m0, s30, 0x2000
	v_lshl_add_u64 v[208:209], s[26:27], 0, v[190:191]
	global_load_lds_dwordx4 v[208:209], off
	s_mov_b32 m0, s49
	v_lshl_add_u64 v[208:209], v[212:213], 0, s[20:21]
	global_load_lds_dwordx4 v[208:209], off
	s_mov_b32 m0, s50
	v_lshl_add_u64 v[208:209], v[214:215], 0, s[20:21]
	global_load_lds_dwordx4 v[208:209], off
	s_waitcnt vmcnt(8)
	s_waitcnt lgkmcnt(0)
	s_barrier
	s_setprio 1
	s_waitcnt lgkmcnt(0)
	v_mfma_f32_16x16x32_bf16 v[60:63], v[120:123], v[160:163], v[60:63]
	v_mfma_f32_16x16x32_bf16 v[56:59], v[136:139], v[160:163], v[56:59]
	v_mfma_f32_16x16x32_bf16 v[44:47], v[120:123], v[168:171], v[44:47]
	v_mfma_f32_16x16x32_bf16 v[40:43], v[136:139], v[168:171], v[40:43]
	v_mfma_f32_16x16x32_bf16 v[28:31], v[120:123], v[176:179], v[28:31]
	v_mfma_f32_16x16x32_bf16 v[24:27], v[136:139], v[176:179], v[24:27]
	v_mfma_f32_16x16x32_bf16 v[12:15], v[120:123], v[200:203], v[12:15]
	v_mfma_f32_16x16x32_bf16 v[8:11], v[136:139], v[200:203], v[8:11]
	v_mfma_f32_16x16x32_bf16 v[60:63], v[124:127], v[164:167], v[60:63]
	v_mfma_f32_16x16x32_bf16 v[56:59], v[140:143], v[164:167], v[56:59]
	v_mfma_f32_16x16x32_bf16 v[44:47], v[124:127], v[172:175], v[44:47]
	v_mfma_f32_16x16x32_bf16 v[40:43], v[140:143], v[172:175], v[40:43]
	v_mfma_f32_16x16x32_bf16 v[28:31], v[124:127], v[180:183], v[28:31]
	v_mfma_f32_16x16x32_bf16 v[24:27], v[140:143], v[180:183], v[24:27]
	v_mfma_f32_16x16x32_bf16 v[12:15], v[124:127], v[204:207], v[12:15]
	v_mfma_f32_16x16x32_bf16 v[8:11], v[140:143], v[204:207], v[8:11]
	s_setprio 0
	s_setprio 1
	v_mfma_f32_16x16x32_bf16 v[52:55], v[144:147], v[160:163], v[52:55]
	v_mfma_f32_16x16x32_bf16 v[48:51], v[152:155], v[160:163], v[48:51]
	v_mfma_f32_16x16x32_bf16 v[36:39], v[144:147], v[168:171], v[36:39]
	v_mfma_f32_16x16x32_bf16 v[32:35], v[152:155], v[168:171], v[32:35]
	v_mfma_f32_16x16x32_bf16 v[20:23], v[144:147], v[176:179], v[20:23]
	v_mfma_f32_16x16x32_bf16 v[16:19], v[152:155], v[176:179], v[16:19]
	v_mfma_f32_16x16x32_bf16 v[4:7], v[144:147], v[200:203], v[4:7]
	v_mfma_f32_16x16x32_bf16 v[0:3], v[152:155], v[200:203], v[0:3]
	v_mfma_f32_16x16x32_bf16 v[52:55], v[148:151], v[164:167], v[52:55]
	v_mfma_f32_16x16x32_bf16 v[48:51], v[156:159], v[164:167], v[48:51]
	v_mfma_f32_16x16x32_bf16 v[36:39], v[148:151], v[172:175], v[36:39]
	v_mfma_f32_16x16x32_bf16 v[32:35], v[156:159], v[172:175], v[32:35]
	s_setprio 2
	s_barrier
	v_mfma_f32_16x16x32_bf16 v[20:23], v[148:151], v[180:183], v[20:23]
	v_mfma_f32_16x16x32_bf16 v[16:19], v[156:159], v[180:183], v[16:19]
	v_mfma_f32_16x16x32_bf16 v[4:7], v[148:151], v[204:207], v[4:7]
	v_mfma_f32_16x16x32_bf16 v[0:3], v[156:159], v[204:207], v[0:3]
	s_setprio 0
	s_add_i32 s64, s64, 2
	s_add_u32 s62, s62, 0x100
	s_addc_u32 s63, s63, 0
	s_cmp_gt_u32 s64, 41
	s_mov_b64 s[26:27], s[28:29]
.LBB0_866:
	ds_read_b128 v[120:123], v233
	ds_read_b128 v[124:127], v233 offset:1024
	ds_read_b128 v[136:139], v233 offset:2048
	ds_read_b128 v[140:143], v233 offset:3072
	ds_read_b128 v[144:147], v234
	ds_read_b128 v[148:151], v234 offset:1024
	ds_read_b128 v[152:155], v234 offset:2048
	ds_read_b128 v[156:159], v234 offset:3072
	s_add_u32 s28, s26, 0x100
	s_addc_u32 s29, s27, 0
	s_cmp_eq_u32 s64, 40
	s_cselect_b32 s37, s7, s29
	s_cselect_b32 s36, s6, s28
	s_cselect_b32 s31, s25, s63
	s_cselect_b32 s30, s24, s62
	v_lshl_add_u64 v[208:209], s[26:27], 0, v[192:193]
	s_add_i32 m0, s44, 0xc000
	ds_read_b128 v[160:163], v235
	ds_read_b128 v[164:167], v235 offset:1024
	ds_read_b128 v[168:171], v235 offset:2048
	ds_read_b128 v[172:175], v235 offset:3072
	ds_read_b128 v[176:179], v235 offset:4096
	ds_read_b128 v[180:183], v235 offset:5120
	ds_read_b128 v[200:203], v235 offset:6144
	ds_read_b128 v[204:207], v235 offset:7168
	global_load_lds_dwordx4 v[208:209], off
	s_add_i32 m0, s44, 0xe000
	v_lshl_add_u64 v[208:209], s[26:27], 0, v[194:195]
	global_load_lds_dwordx4 v[208:209], off
	s_waitcnt vmcnt(8)
	s_waitcnt lgkmcnt(0)
	s_barrier
	s_setprio 1
	s_waitcnt lgkmcnt(0)
	v_mfma_f32_16x16x32_bf16 v[132:135], v[120:123], v[160:163], v[132:135]
	v_mfma_f32_16x16x32_bf16 v[128:131], v[136:139], v[160:163], v[128:131]
	v_mfma_f32_16x16x32_bf16 v[108:111], v[120:123], v[168:171], v[108:111]
	v_mfma_f32_16x16x32_bf16 v[104:107], v[136:139], v[168:171], v[104:107]
	v_mfma_f32_16x16x32_bf16 v[92:95], v[120:123], v[176:179], v[92:95]
	v_mfma_f32_16x16x32_bf16 v[88:91], v[136:139], v[176:179], v[88:91]
	v_mfma_f32_16x16x32_bf16 v[76:79], v[120:123], v[200:203], v[76:79]
	v_mfma_f32_16x16x32_bf16 v[72:75], v[136:139], v[200:203], v[72:75]
	v_mfma_f32_16x16x32_bf16 v[132:135], v[124:127], v[164:167], v[132:135]
	v_mfma_f32_16x16x32_bf16 v[128:131], v[140:143], v[164:167], v[128:131]
	v_mfma_f32_16x16x32_bf16 v[108:111], v[124:127], v[172:175], v[108:111]
	v_mfma_f32_16x16x32_bf16 v[104:107], v[140:143], v[172:175], v[104:107]
	v_mfma_f32_16x16x32_bf16 v[92:95], v[124:127], v[180:183], v[92:95]
	v_mfma_f32_16x16x32_bf16 v[88:91], v[140:143], v[180:183], v[88:91]
	v_mfma_f32_16x16x32_bf16 v[76:79], v[124:127], v[204:207], v[76:79]
	v_mfma_f32_16x16x32_bf16 v[72:75], v[140:143], v[204:207], v[72:75]
	s_setprio 0
	s_setprio 1
	v_mfma_f32_16x16x32_bf16 v[116:119], v[144:147], v[160:163], v[116:119]
	v_mfma_f32_16x16x32_bf16 v[112:115], v[152:155], v[160:163], v[112:115]
	v_mfma_f32_16x16x32_bf16 v[100:103], v[144:147], v[168:171], v[100:103]
	v_mfma_f32_16x16x32_bf16 v[96:99], v[152:155], v[168:171], v[96:99]
	v_mfma_f32_16x16x32_bf16 v[84:87], v[144:147], v[176:179], v[84:87]
	v_mfma_f32_16x16x32_bf16 v[80:83], v[152:155], v[176:179], v[80:83]
	v_mfma_f32_16x16x32_bf16 v[68:71], v[144:147], v[200:203], v[68:71]
	v_mfma_f32_16x16x32_bf16 v[64:67], v[152:155], v[200:203], v[64:67]
	v_mfma_f32_16x16x32_bf16 v[116:119], v[148:151], v[164:167], v[116:119]
	v_mfma_f32_16x16x32_bf16 v[112:115], v[156:159], v[164:167], v[112:115]
	v_mfma_f32_16x16x32_bf16 v[100:103], v[148:151], v[172:175], v[100:103]
	v_mfma_f32_16x16x32_bf16 v[96:99], v[156:159], v[172:175], v[96:99]
	s_setprio 2
	s_barrier
	v_mfma_f32_16x16x32_bf16 v[84:87], v[148:151], v[180:183], v[84:87]
	v_mfma_f32_16x16x32_bf16 v[80:83], v[156:159], v[180:183], v[80:83]
	v_mfma_f32_16x16x32_bf16 v[68:71], v[148:151], v[204:207], v[68:71]
	v_mfma_f32_16x16x32_bf16 v[64:67], v[156:159], v[204:207], v[64:67]
	s_setprio 0
	s_add_i32 s26, s56, s43
	v_lshl_add_u64 v[208:209], s[30:31], 0, v[186:187]
	s_mov_b32 m0, s26
	ds_read_b128 v[160:163], v235 offset:16384
	ds_read_b128 v[164:167], v235 offset:17408
	ds_read_b128 v[168:171], v235 offset:18432
	ds_read_b128 v[172:175], v235 offset:19456
	ds_read_b128 v[176:179], v235 offset:20480
	ds_read_b128 v[180:183], v235 offset:21504
	ds_read_b128 v[200:203], v235 offset:22528
	ds_read_b128 v[204:207], v235 offset:23552
	global_load_lds_dwordx4 v[208:209], off
	s_add_i32 m0, s26, 0x2000
	s_add_u32 s26, s30, 0xb0000
	v_lshl_add_u64 v[210:211], s[30:31], 0, v[190:191]
	s_addc_u32 s27, s31, 0
	s_add_i32 s65, s57, s43
	global_load_lds_dwordx4 v[210:211], off
	v_lshl_add_u64 v[212:213], s[26:27], 0, v[186:187]
	s_mov_b32 m0, s65
	v_lshl_add_u64 v[214:215], s[36:37], 0, v[188:189]
	global_load_lds_dwordx4 v[212:213], off
	s_add_i32 m0, s65, 0x2000
	v_lshl_add_u64 v[212:213], s[26:27], 0, v[190:191]
	global_load_lds_dwordx4 v[212:213], off
	s_mov_b32 m0, s44
	v_lshl_add_u64 v[212:213], s[36:37], 0, v[184:185]
	global_load_lds_dwordx4 v[212:213], off
	s_mov_b32 m0, s45
	s_nop 0
	global_load_lds_dwordx4 v[214:215], off
	s_waitcnt vmcnt(8)
	s_waitcnt lgkmcnt(0)
	s_barrier
	s_setprio 1
	s_waitcnt lgkmcnt(0)
	v_mfma_f32_16x16x32_bf16 v[60:63], v[120:123], v[160:163], v[60:63]
	v_mfma_f32_16x16x32_bf16 v[56:59], v[136:139], v[160:163], v[56:59]
	v_mfma_f32_16x16x32_bf16 v[44:47], v[120:123], v[168:171], v[44:47]
	v_mfma_f32_16x16x32_bf16 v[40:43], v[136:139], v[168:171], v[40:43]
	v_mfma_f32_16x16x32_bf16 v[28:31], v[120:123], v[176:179], v[28:31]
	v_mfma_f32_16x16x32_bf16 v[24:27], v[136:139], v[176:179], v[24:27]
	v_mfma_f32_16x16x32_bf16 v[12:15], v[120:123], v[200:203], v[12:15]
	v_mfma_f32_16x16x32_bf16 v[8:11], v[136:139], v[200:203], v[8:11]
	v_mfma_f32_16x16x32_bf16 v[60:63], v[124:127], v[164:167], v[60:63]
	v_mfma_f32_16x16x32_bf16 v[56:59], v[140:143], v[164:167], v[56:59]
	v_mfma_f32_16x16x32_bf16 v[44:47], v[124:127], v[172:175], v[44:47]
	v_mfma_f32_16x16x32_bf16 v[40:43], v[140:143], v[172:175], v[40:43]
	v_mfma_f32_16x16x32_bf16 v[28:31], v[124:127], v[180:183], v[28:31]
	v_mfma_f32_16x16x32_bf16 v[24:27], v[140:143], v[180:183], v[24:27]
	v_mfma_f32_16x16x32_bf16 v[12:15], v[124:127], v[204:207], v[12:15]
	v_mfma_f32_16x16x32_bf16 v[8:11], v[140:143], v[204:207], v[8:11]
	s_setprio 0
	s_setprio 1
	v_mfma_f32_16x16x32_bf16 v[52:55], v[144:147], v[160:163], v[52:55]
	v_mfma_f32_16x16x32_bf16 v[48:51], v[152:155], v[160:163], v[48:51]
	v_mfma_f32_16x16x32_bf16 v[36:39], v[144:147], v[168:171], v[36:39]
	v_mfma_f32_16x16x32_bf16 v[32:35], v[152:155], v[168:171], v[32:35]
	v_mfma_f32_16x16x32_bf16 v[20:23], v[144:147], v[176:179], v[20:23]
	v_mfma_f32_16x16x32_bf16 v[16:19], v[152:155], v[176:179], v[16:19]
	v_mfma_f32_16x16x32_bf16 v[4:7], v[144:147], v[200:203], v[4:7]
	v_mfma_f32_16x16x32_bf16 v[0:3], v[152:155], v[200:203], v[0:3]
	v_mfma_f32_16x16x32_bf16 v[52:55], v[148:151], v[164:167], v[52:55]
	v_mfma_f32_16x16x32_bf16 v[48:51], v[156:159], v[164:167], v[48:51]
	v_mfma_f32_16x16x32_bf16 v[36:39], v[148:151], v[172:175], v[36:39]
	v_mfma_f32_16x16x32_bf16 v[32:35], v[156:159], v[172:175], v[32:35]
	s_setprio 2
	s_barrier
	v_mfma_f32_16x16x32_bf16 v[20:23], v[148:151], v[180:183], v[20:23]
	v_mfma_f32_16x16x32_bf16 v[16:19], v[156:159], v[180:183], v[16:19]
	v_mfma_f32_16x16x32_bf16 v[4:7], v[148:151], v[204:207], v[4:7]
	v_mfma_f32_16x16x32_bf16 v[0:3], v[156:159], v[204:207], v[0:3]
	s_setprio 0
	s_add_i32 s65, 0, 0x18000
	s_add_i32 s66, 0, 0x1c000
	v_add_u32_e32 v140, s65, v232
	v_add_u32_e32 v156, s66, v232
	ds_read_b128 v[120:123], v140
	ds_read_b128 v[124:127], v140 offset:1024
	ds_read_b128 v[136:139], v140 offset:2048
	ds_read_b128 v[140:143], v140 offset:3072
	ds_read_b128 v[144:147], v156
	ds_read_b128 v[148:151], v156 offset:1024
	ds_read_b128 v[152:155], v156 offset:2048
	ds_read_b128 v[156:159], v156 offset:3072
	s_add_u32 s26, s36, 0xb0000
	s_addc_u32 s27, s37, 0
	s_mov_b32 m0, s46
	v_lshl_add_u64 v[216:217], s[26:27], 0, v[184:185]
	ds_read_b128 v[160:163], v235 offset:32768
	ds_read_b128 v[164:167], v235 offset:33792
	ds_read_b128 v[168:171], v235 offset:34816
	ds_read_b128 v[172:175], v235 offset:35840
	ds_read_b128 v[176:179], v235 offset:36864
	ds_read_b128 v[180:183], v235 offset:37888
	ds_read_b128 v[200:203], v235 offset:38912
	ds_read_b128 v[204:207], v235 offset:39936
	global_load_lds_dwordx4 v[216:217], off
	s_mov_b32 m0, s47
	v_lshl_add_u64 v[216:217], s[26:27], 0, v[188:189]
	global_load_lds_dwordx4 v[216:217], off
	s_waitcnt vmcnt(8)
	s_waitcnt lgkmcnt(0)
	s_barrier
	s_setprio 1
	s_waitcnt lgkmcnt(0)
	v_mfma_f32_16x16x32_bf16 v[132:135], v[120:123], v[160:163], v[132:135]
	v_mfma_f32_16x16x32_bf16 v[128:131], v[136:139], v[160:163], v[128:131]
	v_mfma_f32_16x16x32_bf16 v[108:111], v[120:123], v[168:171], v[108:111]
	v_mfma_f32_16x16x32_bf16 v[104:107], v[136:139], v[168:171], v[104:107]
	v_mfma_f32_16x16x32_bf16 v[92:95], v[120:123], v[176:179], v[92:95]
	v_mfma_f32_16x16x32_bf16 v[88:91], v[136:139], v[176:179], v[88:91]
	v_mfma_f32_16x16x32_bf16 v[76:79], v[120:123], v[200:203], v[76:79]
	v_mfma_f32_16x16x32_bf16 v[72:75], v[136:139], v[200:203], v[72:75]
	v_mfma_f32_16x16x32_bf16 v[132:135], v[124:127], v[164:167], v[132:135]
	v_mfma_f32_16x16x32_bf16 v[128:131], v[140:143], v[164:167], v[128:131]
	v_mfma_f32_16x16x32_bf16 v[108:111], v[124:127], v[172:175], v[108:111]
	v_mfma_f32_16x16x32_bf16 v[104:107], v[140:143], v[172:175], v[104:107]
	v_mfma_f32_16x16x32_bf16 v[92:95], v[124:127], v[180:183], v[92:95]
	v_mfma_f32_16x16x32_bf16 v[88:91], v[140:143], v[180:183], v[88:91]
	v_mfma_f32_16x16x32_bf16 v[76:79], v[124:127], v[204:207], v[76:79]
	v_mfma_f32_16x16x32_bf16 v[72:75], v[140:143], v[204:207], v[72:75]
	s_setprio 0
	s_setprio 1
	v_mfma_f32_16x16x32_bf16 v[116:119], v[144:147], v[160:163], v[116:119]
	v_mfma_f32_16x16x32_bf16 v[112:115], v[152:155], v[160:163], v[112:115]
	v_mfma_f32_16x16x32_bf16 v[100:103], v[144:147], v[168:171], v[100:103]
	v_mfma_f32_16x16x32_bf16 v[96:99], v[152:155], v[168:171], v[96:99]
	v_mfma_f32_16x16x32_bf16 v[84:87], v[144:147], v[176:179], v[84:87]
	v_mfma_f32_16x16x32_bf16 v[80:83], v[152:155], v[176:179], v[80:83]
	v_mfma_f32_16x16x32_bf16 v[68:71], v[144:147], v[200:203], v[68:71]
	v_mfma_f32_16x16x32_bf16 v[64:67], v[152:155], v[200:203], v[64:67]
	v_mfma_f32_16x16x32_bf16 v[116:119], v[148:151], v[164:167], v[116:119]
	v_mfma_f32_16x16x32_bf16 v[112:115], v[156:159], v[164:167], v[112:115]
	v_mfma_f32_16x16x32_bf16 v[100:103], v[148:151], v[172:175], v[100:103]
	v_mfma_f32_16x16x32_bf16 v[96:99], v[156:159], v[172:175], v[96:99]
	s_setprio 2
	s_barrier
	v_mfma_f32_16x16x32_bf16 v[84:87], v[148:151], v[180:183], v[84:87]
	v_mfma_f32_16x16x32_bf16 v[80:83], v[156:159], v[180:183], v[80:83]
	v_mfma_f32_16x16x32_bf16 v[68:71], v[148:151], v[204:207], v[68:71]
	v_mfma_f32_16x16x32_bf16 v[64:67], v[156:159], v[204:207], v[64:67]
	s_setprio 0
	s_add_i32 s26, s65, s43
	v_lshl_add_u64 v[208:209], v[208:209], 0, s[20:21]
	s_mov_b32 m0, s26
	ds_read_b128 v[160:163], v235 offset:49152
	ds_read_b128 v[164:167], v235 offset:50176
	ds_read_b128 v[168:171], v235 offset:51200
	ds_read_b128 v[172:175], v235 offset:52224
	ds_read_b128 v[176:179], v235 offset:53248
	ds_read_b128 v[180:183], v235 offset:54272
	ds_read_b128 v[200:203], v235 offset:55296
	ds_read_b128 v[204:207], v235 offset:56320
	global_load_lds_dwordx4 v[208:209], off
	s_add_i32 m0, s26, 0x2000
	s_add_u32 s26, s30, 0xb0080
	v_lshl_add_u64 v[208:209], v[210:211], 0, s[20:21]
	s_addc_u32 s27, s31, 0
	s_add_i32 s30, s66, s43
	global_load_lds_dwordx4 v[208:209], off
	s_mov_b32 m0, s30
	v_lshl_add_u64 v[208:209], s[26:27], 0, v[186:187]
	global_load_lds_dwordx4 v[208:209], off
	s_add_i32 m0, s30, 0x2000
	v_lshl_add_u64 v[208:209], s[26:27], 0, v[190:191]
	global_load_lds_dwordx4 v[208:209], off
	s_mov_b32 m0, s49
	v_lshl_add_u64 v[208:209], v[212:213], 0, s[20:21]
	global_load_lds_dwordx4 v[208:209], off
	s_mov_b32 m0, s50
	v_lshl_add_u64 v[208:209], v[214:215], 0, s[20:21]
	global_load_lds_dwordx4 v[208:209], off
	s_waitcnt vmcnt(8)
	s_waitcnt lgkmcnt(0)
	s_barrier
	s_setprio 1
	s_waitcnt lgkmcnt(0)
	v_mfma_f32_16x16x32_bf16 v[60:63], v[120:123], v[160:163], v[60:63]
	v_mfma_f32_16x16x32_bf16 v[56:59], v[136:139], v[160:163], v[56:59]
	v_mfma_f32_16x16x32_bf16 v[44:47], v[120:123], v[168:171], v[44:47]
	v_mfma_f32_16x16x32_bf16 v[40:43], v[136:139], v[168:171], v[40:43]
	v_mfma_f32_16x16x32_bf16 v[28:31], v[120:123], v[176:179], v[28:31]
	v_mfma_f32_16x16x32_bf16 v[24:27], v[136:139], v[176:179], v[24:27]
	v_mfma_f32_16x16x32_bf16 v[12:15], v[120:123], v[200:203], v[12:15]
	v_mfma_f32_16x16x32_bf16 v[8:11], v[136:139], v[200:203], v[8:11]
	v_mfma_f32_16x16x32_bf16 v[60:63], v[124:127], v[164:167], v[60:63]
	v_mfma_f32_16x16x32_bf16 v[56:59], v[140:143], v[164:167], v[56:59]
	v_mfma_f32_16x16x32_bf16 v[44:47], v[124:127], v[172:175], v[44:47]
	v_mfma_f32_16x16x32_bf16 v[40:43], v[140:143], v[172:175], v[40:43]
	v_mfma_f32_16x16x32_bf16 v[28:31], v[124:127], v[180:183], v[28:31]
	v_mfma_f32_16x16x32_bf16 v[24:27], v[140:143], v[180:183], v[24:27]
	v_mfma_f32_16x16x32_bf16 v[12:15], v[124:127], v[204:207], v[12:15]
	v_mfma_f32_16x16x32_bf16 v[8:11], v[140:143], v[204:207], v[8:11]
	s_setprio 0
	s_setprio 1
	v_mfma_f32_16x16x32_bf16 v[52:55], v[144:147], v[160:163], v[52:55]
	v_mfma_f32_16x16x32_bf16 v[48:51], v[152:155], v[160:163], v[48:51]
	v_mfma_f32_16x16x32_bf16 v[36:39], v[144:147], v[168:171], v[36:39]
	v_mfma_f32_16x16x32_bf16 v[32:35], v[152:155], v[168:171], v[32:35]
	v_mfma_f32_16x16x32_bf16 v[20:23], v[144:147], v[176:179], v[20:23]
	v_mfma_f32_16x16x32_bf16 v[16:19], v[152:155], v[176:179], v[16:19]
	v_mfma_f32_16x16x32_bf16 v[4:7], v[144:147], v[200:203], v[4:7]
	v_mfma_f32_16x16x32_bf16 v[0:3], v[152:155], v[200:203], v[0:3]
	v_mfma_f32_16x16x32_bf16 v[52:55], v[148:151], v[164:167], v[52:55]
	v_mfma_f32_16x16x32_bf16 v[48:51], v[156:159], v[164:167], v[48:51]
	v_mfma_f32_16x16x32_bf16 v[36:39], v[148:151], v[172:175], v[36:39]
	v_mfma_f32_16x16x32_bf16 v[32:35], v[156:159], v[172:175], v[32:35]
	s_setprio 2
	s_barrier
	v_mfma_f32_16x16x32_bf16 v[20:23], v[148:151], v[180:183], v[20:23]
	v_mfma_f32_16x16x32_bf16 v[16:19], v[156:159], v[180:183], v[16:19]
	v_mfma_f32_16x16x32_bf16 v[4:7], v[148:151], v[204:207], v[4:7]
	v_mfma_f32_16x16x32_bf16 v[0:3], v[156:159], v[204:207], v[0:3]
	s_setprio 0
	s_add_i32 s64, s64, 2
	s_add_u32 s62, s62, 0x100
	s_addc_u32 s63, s63, 0
	s_cmp_gt_u32 s64, 41
	s_mov_b64 s[26:27], s[28:29]
	s_cbranch_scc0 .LBB0_866

.LBB0_951:
	s_ashr_i32 s27, s26, 31
	s_lshl_b64 s[30:31], s[26:27], 19
	s_add_u32 s30, s47, s30
	s_addc_u32 s31, s48, s31
	s_and_b64 s[36:37], s[4:5], exec
	s_cselect_b32 s27, s31, s7
	s_cselect_b32 s39, s30, s6
	s_ashr_i32 s29, s28, 31
	s_lshl_b64 s[36:37], s[28:29], 19
	s_add_u32 s36, s49, s36
	s_addc_u32 s37, s50, s37
	s_and_b64 s[44:45], s[4:5], exec
	s_cselect_b32 s29, s37, s41
	s_cselect_b32 s43, s36, s40
	s_add_u32 s6, s6, 0x40080
	s_addc_u32 s7, s7, 0
	s_add_u32 s71, s40, 0x100
	s_addc_u32 s72, s41, 0
	s_mov_b32 s73, -2
	ds_read_b128 v[144:147], v179
	ds_read_b128 v[148:151], v179 offset:1024
	ds_read_b128 v[152:155], v179 offset:2048
	ds_read_b128 v[156:159], v179 offset:3072
	ds_read_b128 v[160:163], v180
	ds_read_b128 v[164:167], v180 offset:1024
	ds_read_b128 v[168:171], v180 offset:2048
	ds_read_b128 v[172:175], v180 offset:3072
	s_add_u32 s40, s6, 0xfffc0080
	s_addc_u32 s41, s7, -1
	s_cmp_eq_u32 s73, 12
	s_cselect_b32 s45, s27, s41
	s_cselect_b32 s44, s39, s40
	s_cselect_b32 s41, s29, s72
	s_cselect_b32 s40, s43, s71
	v_lshl_add_u64 v[176:177], s[6:7], 0, v[136:137]
	s_add_i32 m0, s54, 0xc000
	ds_read_b128 v[184:187], v181
	ds_read_b128 v[188:191], v181 offset:1024
	ds_read_b128 v[192:195], v181 offset:2048
	ds_read_b128 v[196:199], v181 offset:3072
	ds_read_b128 v[200:203], v181 offset:4096
	ds_read_b128 v[204:207], v181 offset:5120
	ds_read_b128 v[208:211], v181 offset:6144
	ds_read_b128 v[212:215], v181 offset:7168
	global_load_lds_dwordx4 v[176:177], off
	s_add_i32 m0, s54, 0xe000
	v_lshl_add_u64 v[176:177], s[6:7], 0, v[138:139]
	global_load_lds_dwordx4 v[176:177], off
	s_waitcnt vmcnt(8)
	s_waitcnt lgkmcnt(0)
	s_barrier
	s_setprio 1
	s_waitcnt lgkmcnt(0)
	v_mfma_f32_16x16x32_bf16 v[124:127], v[144:147], v[184:187], 0
	v_mfma_f32_16x16x32_bf16 v[120:123], v[152:155], v[184:187], 0
	v_mfma_f32_16x16x32_bf16 v[108:111], v[144:147], v[192:195], 0
	v_mfma_f32_16x16x32_bf16 v[104:107], v[152:155], v[192:195], 0
	v_mfma_f32_16x16x32_bf16 v[92:95], v[144:147], v[200:203], 0
	v_mfma_f32_16x16x32_bf16 v[88:91], v[152:155], v[200:203], 0
	v_mfma_f32_16x16x32_bf16 v[76:79], v[144:147], v[208:211], 0
	v_mfma_f32_16x16x32_bf16 v[72:75], v[152:155], v[208:211], 0
	v_mfma_f32_16x16x32_bf16 v[124:127], v[148:151], v[188:191], v[124:127]
	v_mfma_f32_16x16x32_bf16 v[120:123], v[156:159], v[188:191], v[120:123]
	v_mfma_f32_16x16x32_bf16 v[108:111], v[148:151], v[196:199], v[108:111]
	v_mfma_f32_16x16x32_bf16 v[104:107], v[156:159], v[196:199], v[104:107]
	v_mfma_f32_16x16x32_bf16 v[92:95], v[148:151], v[204:207], v[92:95]
	v_mfma_f32_16x16x32_bf16 v[88:91], v[156:159], v[204:207], v[88:91]
	v_mfma_f32_16x16x32_bf16 v[76:79], v[148:151], v[212:215], v[76:79]
	v_mfma_f32_16x16x32_bf16 v[72:75], v[156:159], v[212:215], v[72:75]
	s_setprio 0
	s_setprio 1
	v_mfma_f32_16x16x32_bf16 v[116:119], v[160:163], v[184:187], 0
	v_mfma_f32_16x16x32_bf16 v[112:115], v[168:171], v[184:187], 0
	v_mfma_f32_16x16x32_bf16 v[100:103], v[160:163], v[192:195], 0
	v_mfma_f32_16x16x32_bf16 v[96:99], v[168:171], v[192:195], 0
	v_mfma_f32_16x16x32_bf16 v[84:87], v[160:163], v[200:203], 0
	v_mfma_f32_16x16x32_bf16 v[80:83], v[168:171], v[200:203], 0
	v_mfma_f32_16x16x32_bf16 v[68:71], v[160:163], v[208:211], 0
	v_mfma_f32_16x16x32_bf16 v[64:67], v[168:171], v[208:211], 0
	v_mfma_f32_16x16x32_bf16 v[116:119], v[164:167], v[188:191], v[116:119]
	v_mfma_f32_16x16x32_bf16 v[112:115], v[172:175], v[188:191], v[112:115]
	v_mfma_f32_16x16x32_bf16 v[100:103], v[164:167], v[196:199], v[100:103]
	v_mfma_f32_16x16x32_bf16 v[96:99], v[172:175], v[196:199], v[96:99]
	s_setprio 2
	s_barrier
	v_mfma_f32_16x16x32_bf16 v[84:87], v[164:167], v[204:207], v[84:87]
	v_mfma_f32_16x16x32_bf16 v[80:83], v[172:175], v[204:207], v[80:83]
	v_mfma_f32_16x16x32_bf16 v[68:71], v[164:167], v[212:215], v[68:71]
	v_mfma_f32_16x16x32_bf16 v[64:67], v[172:175], v[212:215], v[64:67]
	s_setprio 0
	s_add_i32 s74, s69, s51
	v_lshl_add_u64 v[176:177], s[40:41], 0, v[130:131]
	s_mov_b32 m0, s74
	ds_read_b128 v[184:187], v181 offset:16384
	ds_read_b128 v[188:191], v181 offset:17408
	ds_read_b128 v[192:195], v181 offset:18432
	ds_read_b128 v[196:199], v181 offset:19456
	ds_read_b128 v[200:203], v181 offset:20480
	ds_read_b128 v[204:207], v181 offset:21504
	ds_read_b128 v[208:211], v181 offset:22528
	ds_read_b128 v[212:215], v181 offset:23552
	global_load_lds_dwordx4 v[176:177], off
	s_add_i32 m0, s74, 0x2000
	s_add_u32 s74, s40, 0x40000
	v_lshl_add_u64 v[216:217], s[40:41], 0, v[134:135]
	s_addc_u32 s75, s41, 0
	s_add_i32 s76, s70, s51
	global_load_lds_dwordx4 v[216:217], off
	v_lshl_add_u64 v[218:219], s[74:75], 0, v[130:131]
	s_mov_b32 m0, s76
	v_lshl_add_u64 v[220:221], s[44:45], 0, v[132:133]
	global_load_lds_dwordx4 v[218:219], off
	s_add_i32 m0, s76, 0x2000
	v_lshl_add_u64 v[218:219], s[74:75], 0, v[134:135]
	global_load_lds_dwordx4 v[218:219], off
	s_mov_b32 m0, s54
	v_lshl_add_u64 v[218:219], s[44:45], 0, v[128:129]
	global_load_lds_dwordx4 v[218:219], off
	s_mov_b32 m0, s55
	s_nop 0
	global_load_lds_dwordx4 v[220:221], off
	s_waitcnt vmcnt(8)
	s_waitcnt lgkmcnt(0)
	s_barrier
	s_setprio 1
	s_waitcnt lgkmcnt(0)
	v_mfma_f32_16x16x32_bf16 v[60:63], v[144:147], v[184:187], 0
	v_mfma_f32_16x16x32_bf16 v[56:59], v[152:155], v[184:187], 0
	v_mfma_f32_16x16x32_bf16 v[44:47], v[144:147], v[192:195], 0
	v_mfma_f32_16x16x32_bf16 v[40:43], v[152:155], v[192:195], 0
	v_mfma_f32_16x16x32_bf16 v[28:31], v[144:147], v[200:203], 0
	v_mfma_f32_16x16x32_bf16 v[24:27], v[152:155], v[200:203], 0
	v_mfma_f32_16x16x32_bf16 v[12:15], v[144:147], v[208:211], 0
	v_mfma_f32_16x16x32_bf16 v[8:11], v[152:155], v[208:211], 0
	v_mfma_f32_16x16x32_bf16 v[60:63], v[148:151], v[188:191], v[60:63]
	v_mfma_f32_16x16x32_bf16 v[56:59], v[156:159], v[188:191], v[56:59]
	v_mfma_f32_16x16x32_bf16 v[44:47], v[148:151], v[196:199], v[44:47]
	v_mfma_f32_16x16x32_bf16 v[40:43], v[156:159], v[196:199], v[40:43]
	v_mfma_f32_16x16x32_bf16 v[28:31], v[148:151], v[204:207], v[28:31]
	v_mfma_f32_16x16x32_bf16 v[24:27], v[156:159], v[204:207], v[24:27]
	v_mfma_f32_16x16x32_bf16 v[12:15], v[148:151], v[212:215], v[12:15]
	v_mfma_f32_16x16x32_bf16 v[8:11], v[156:159], v[212:215], v[8:11]
	s_setprio 0
	s_setprio 1
	v_mfma_f32_16x16x32_bf16 v[52:55], v[160:163], v[184:187], 0
	v_mfma_f32_16x16x32_bf16 v[48:51], v[168:171], v[184:187], 0
	v_mfma_f32_16x16x32_bf16 v[36:39], v[160:163], v[192:195], 0
	v_mfma_f32_16x16x32_bf16 v[32:35], v[168:171], v[192:195], 0
	v_mfma_f32_16x16x32_bf16 v[20:23], v[160:163], v[200:203], 0
	v_mfma_f32_16x16x32_bf16 v[16:19], v[168:171], v[200:203], 0
	v_mfma_f32_16x16x32_bf16 v[4:7], v[160:163], v[208:211], 0
	v_mfma_f32_16x16x32_bf16 v[0:3], v[168:171], v[208:211], 0
	v_mfma_f32_16x16x32_bf16 v[52:55], v[164:167], v[188:191], v[52:55]
	v_mfma_f32_16x16x32_bf16 v[48:51], v[172:175], v[188:191], v[48:51]
	v_mfma_f32_16x16x32_bf16 v[36:39], v[164:167], v[196:199], v[36:39]
	v_mfma_f32_16x16x32_bf16 v[32:35], v[172:175], v[196:199], v[32:35]
	s_setprio 2
	s_barrier
	v_mfma_f32_16x16x32_bf16 v[20:23], v[164:167], v[204:207], v[20:23]
	v_mfma_f32_16x16x32_bf16 v[16:19], v[172:175], v[204:207], v[16:19]
	v_mfma_f32_16x16x32_bf16 v[4:7], v[164:167], v[212:215], v[4:7]
	v_mfma_f32_16x16x32_bf16 v[0:3], v[172:175], v[212:215], v[0:3]
	s_setprio 0
	s_add_i32 s74, 0, 0x18000
	s_add_i32 s75, 0, 0x1c000
	v_add_u32_e32 v156, s74, v178
	v_add_u32_e32 v172, s75, v178
	ds_read_b128 v[144:147], v156
	ds_read_b128 v[148:151], v156 offset:1024
	ds_read_b128 v[152:155], v156 offset:2048
	ds_read_b128 v[156:159], v156 offset:3072
	ds_read_b128 v[160:163], v172
	ds_read_b128 v[164:167], v172 offset:1024
	ds_read_b128 v[168:171], v172 offset:2048
	ds_read_b128 v[172:175], v172 offset:3072
	s_add_u32 s44, s44, 0x40000
	s_addc_u32 s45, s45, 0
	s_mov_b32 m0, s56
	v_lshl_add_u64 v[222:223], s[44:45], 0, v[128:129]
	ds_read_b128 v[184:187], v181 offset:32768
	ds_read_b128 v[188:191], v181 offset:33792
	ds_read_b128 v[192:195], v181 offset:34816
	ds_read_b128 v[196:199], v181 offset:35840
	ds_read_b128 v[200:203], v181 offset:36864
	ds_read_b128 v[204:207], v181 offset:37888
	ds_read_b128 v[208:211], v181 offset:38912
	ds_read_b128 v[212:215], v181 offset:39936
	global_load_lds_dwordx4 v[222:223], off
	s_mov_b32 m0, s57
	v_lshl_add_u64 v[222:223], s[44:45], 0, v[132:133]
	global_load_lds_dwordx4 v[222:223], off
	s_waitcnt vmcnt(8)
	s_waitcnt lgkmcnt(0)
	s_barrier
	s_setprio 1
	s_waitcnt lgkmcnt(0)
	v_mfma_f32_16x16x32_bf16 v[124:127], v[144:147], v[184:187], v[124:127]
	v_mfma_f32_16x16x32_bf16 v[120:123], v[152:155], v[184:187], v[120:123]
	v_mfma_f32_16x16x32_bf16 v[108:111], v[144:147], v[192:195], v[108:111]
	v_mfma_f32_16x16x32_bf16 v[104:107], v[152:155], v[192:195], v[104:107]
	v_mfma_f32_16x16x32_bf16 v[92:95], v[144:147], v[200:203], v[92:95]
	v_mfma_f32_16x16x32_bf16 v[88:91], v[152:155], v[200:203], v[88:91]
	v_mfma_f32_16x16x32_bf16 v[76:79], v[144:147], v[208:211], v[76:79]
	v_mfma_f32_16x16x32_bf16 v[72:75], v[152:155], v[208:211], v[72:75]
	v_mfma_f32_16x16x32_bf16 v[124:127], v[148:151], v[188:191], v[124:127]
	v_mfma_f32_16x16x32_bf16 v[120:123], v[156:159], v[188:191], v[120:123]
	v_mfma_f32_16x16x32_bf16 v[108:111], v[148:151], v[196:199], v[108:111]
	v_mfma_f32_16x16x32_bf16 v[104:107], v[156:159], v[196:199], v[104:107]
	v_mfma_f32_16x16x32_bf16 v[92:95], v[148:151], v[204:207], v[92:95]
	v_mfma_f32_16x16x32_bf16 v[88:91], v[156:159], v[204:207], v[88:91]
	v_mfma_f32_16x16x32_bf16 v[76:79], v[148:151], v[212:215], v[76:79]
	v_mfma_f32_16x16x32_bf16 v[72:75], v[156:159], v[212:215], v[72:75]
	s_setprio 0
	s_setprio 1
	v_mfma_f32_16x16x32_bf16 v[116:119], v[160:163], v[184:187], v[116:119]
	v_mfma_f32_16x16x32_bf16 v[112:115], v[168:171], v[184:187], v[112:115]
	v_mfma_f32_16x16x32_bf16 v[100:103], v[160:163], v[192:195], v[100:103]
	v_mfma_f32_16x16x32_bf16 v[96:99], v[168:171], v[192:195], v[96:99]
	v_mfma_f32_16x16x32_bf16 v[84:87], v[160:163], v[200:203], v[84:87]
	v_mfma_f32_16x16x32_bf16 v[80:83], v[168:171], v[200:203], v[80:83]
	v_mfma_f32_16x16x32_bf16 v[68:71], v[160:163], v[208:211], v[68:71]
	v_mfma_f32_16x16x32_bf16 v[64:67], v[168:171], v[208:211], v[64:67]
	v_mfma_f32_16x16x32_bf16 v[116:119], v[164:167], v[188:191], v[116:119]
	v_mfma_f32_16x16x32_bf16 v[112:115], v[172:175], v[188:191], v[112:115]
	v_mfma_f32_16x16x32_bf16 v[100:103], v[164:167], v[196:199], v[100:103]
	v_mfma_f32_16x16x32_bf16 v[96:99], v[172:175], v[196:199], v[96:99]
	s_setprio 2
	s_barrier
	v_mfma_f32_16x16x32_bf16 v[84:87], v[164:167], v[204:207], v[84:87]
	v_mfma_f32_16x16x32_bf16 v[80:83], v[172:175], v[204:207], v[80:83]
	v_mfma_f32_16x16x32_bf16 v[68:71], v[164:167], v[212:215], v[68:71]
	v_mfma_f32_16x16x32_bf16 v[64:67], v[172:175], v[212:215], v[64:67]
	s_setprio 0
	s_add_i32 s44, s74, s51
	v_lshl_add_u64 v[176:177], v[176:177], 0, s[22:23]
	s_mov_b32 m0, s44
	ds_read_b128 v[184:187], v181 offset:49152
	ds_read_b128 v[188:191], v181 offset:50176
	ds_read_b128 v[192:195], v181 offset:51200
	ds_read_b128 v[196:199], v181 offset:52224
	ds_read_b128 v[200:203], v181 offset:53248
	ds_read_b128 v[204:207], v181 offset:54272
	ds_read_b128 v[208:211], v181 offset:55296
	ds_read_b128 v[212:215], v181 offset:56320
	global_load_lds_dwordx4 v[176:177], off
	s_add_i32 m0, s44, 0x2000
	s_add_u32 s40, s40, 0x40080
	v_lshl_add_u64 v[176:177], v[216:217], 0, s[22:23]
	s_addc_u32 s41, s41, 0
	s_add_i32 s44, s75, s51
	global_load_lds_dwordx4 v[176:177], off
	s_mov_b32 m0, s44
	v_lshl_add_u64 v[176:177], s[40:41], 0, v[130:131]
	global_load_lds_dwordx4 v[176:177], off
	s_add_i32 m0, s44, 0x2000
	v_lshl_add_u64 v[176:177], s[40:41], 0, v[134:135]
	global_load_lds_dwordx4 v[176:177], off
	s_mov_b32 m0, s64
	v_lshl_add_u64 v[176:177], v[218:219], 0, s[22:23]
	global_load_lds_dwordx4 v[176:177], off
	s_mov_b32 m0, s65
	v_lshl_add_u64 v[176:177], v[220:221], 0, s[22:23]
	global_load_lds_dwordx4 v[176:177], off
	s_waitcnt vmcnt(8)
	s_waitcnt lgkmcnt(0)
	s_barrier
	s_setprio 1
	s_waitcnt lgkmcnt(0)
	v_mfma_f32_16x16x32_bf16 v[60:63], v[144:147], v[184:187], v[60:63]
	v_mfma_f32_16x16x32_bf16 v[56:59], v[152:155], v[184:187], v[56:59]
	v_mfma_f32_16x16x32_bf16 v[44:47], v[144:147], v[192:195], v[44:47]
	v_mfma_f32_16x16x32_bf16 v[40:43], v[152:155], v[192:195], v[40:43]
	v_mfma_f32_16x16x32_bf16 v[28:31], v[144:147], v[200:203], v[28:31]
	v_mfma_f32_16x16x32_bf16 v[24:27], v[152:155], v[200:203], v[24:27]
	v_mfma_f32_16x16x32_bf16 v[12:15], v[144:147], v[208:211], v[12:15]
	v_mfma_f32_16x16x32_bf16 v[8:11], v[152:155], v[208:211], v[8:11]
	v_mfma_f32_16x16x32_bf16 v[60:63], v[148:151], v[188:191], v[60:63]
	v_mfma_f32_16x16x32_bf16 v[56:59], v[156:159], v[188:191], v[56:59]
	v_mfma_f32_16x16x32_bf16 v[44:47], v[148:151], v[196:199], v[44:47]
	v_mfma_f32_16x16x32_bf16 v[40:43], v[156:159], v[196:199], v[40:43]
	v_mfma_f32_16x16x32_bf16 v[28:31], v[148:151], v[204:207], v[28:31]
	v_mfma_f32_16x16x32_bf16 v[24:27], v[156:159], v[204:207], v[24:27]
	v_mfma_f32_16x16x32_bf16 v[12:15], v[148:151], v[212:215], v[12:15]
	v_mfma_f32_16x16x32_bf16 v[8:11], v[156:159], v[212:215], v[8:11]
	s_setprio 0
	s_setprio 1
	v_mfma_f32_16x16x32_bf16 v[52:55], v[160:163], v[184:187], v[52:55]
	v_mfma_f32_16x16x32_bf16 v[48:51], v[168:171], v[184:187], v[48:51]
	v_mfma_f32_16x16x32_bf16 v[36:39], v[160:163], v[192:195], v[36:39]
	v_mfma_f32_16x16x32_bf16 v[32:35], v[168:171], v[192:195], v[32:35]
	v_mfma_f32_16x16x32_bf16 v[20:23], v[160:163], v[200:203], v[20:23]
	v_mfma_f32_16x16x32_bf16 v[16:19], v[168:171], v[200:203], v[16:19]
	v_mfma_f32_16x16x32_bf16 v[4:7], v[160:163], v[208:211], v[4:7]
	v_mfma_f32_16x16x32_bf16 v[0:3], v[168:171], v[208:211], v[0:3]
	v_mfma_f32_16x16x32_bf16 v[52:55], v[164:167], v[188:191], v[52:55]
	v_mfma_f32_16x16x32_bf16 v[48:51], v[172:175], v[188:191], v[48:51]
	v_mfma_f32_16x16x32_bf16 v[36:39], v[164:167], v[196:199], v[36:39]
	v_mfma_f32_16x16x32_bf16 v[32:35], v[172:175], v[196:199], v[32:35]
	s_setprio 2
	s_barrier
	v_mfma_f32_16x16x32_bf16 v[20:23], v[164:167], v[204:207], v[20:23]
	v_mfma_f32_16x16x32_bf16 v[16:19], v[172:175], v[204:207], v[16:19]
	v_mfma_f32_16x16x32_bf16 v[4:7], v[164:167], v[212:215], v[4:7]
	v_mfma_f32_16x16x32_bf16 v[0:3], v[172:175], v[212:215], v[0:3]
	s_setprio 0
	s_add_i32 s73, s73, 2
	s_add_u32 s6, s6, 0x100
	s_addc_u32 s7, s7, 0
	s_add_u32 s71, s71, 0x100
	s_addc_u32 s72, s72, 0
	s_cmp_gt_u32 s73, 13
.LBB0_952:
	ds_read_b128 v[144:147], v179
	ds_read_b128 v[148:151], v179 offset:1024
	ds_read_b128 v[152:155], v179 offset:2048
	ds_read_b128 v[156:159], v179 offset:3072
	ds_read_b128 v[160:163], v180
	ds_read_b128 v[164:167], v180 offset:1024
	ds_read_b128 v[168:171], v180 offset:2048
	ds_read_b128 v[172:175], v180 offset:3072
	s_add_u32 s40, s6, 0xfffc0080
	s_addc_u32 s41, s7, -1
	s_cmp_eq_u32 s73, 12
	s_cselect_b32 s45, s27, s41
	s_cselect_b32 s44, s39, s40
	s_cselect_b32 s41, s29, s72
	s_cselect_b32 s40, s43, s71
	v_lshl_add_u64 v[176:177], s[6:7], 0, v[136:137]
	s_add_i32 m0, s54, 0xc000
	ds_read_b128 v[184:187], v181
	ds_read_b128 v[188:191], v181 offset:1024
	ds_read_b128 v[192:195], v181 offset:2048
	ds_read_b128 v[196:199], v181 offset:3072
	ds_read_b128 v[200:203], v181 offset:4096
	ds_read_b128 v[204:207], v181 offset:5120
	ds_read_b128 v[208:211], v181 offset:6144
	ds_read_b128 v[212:215], v181 offset:7168
	global_load_lds_dwordx4 v[176:177], off
	s_add_i32 m0, s54, 0xe000
	v_lshl_add_u64 v[176:177], s[6:7], 0, v[138:139]
	global_load_lds_dwordx4 v[176:177], off
	s_waitcnt vmcnt(8)
	s_waitcnt lgkmcnt(0)
	s_barrier
	s_setprio 1
	s_waitcnt lgkmcnt(0)
	v_mfma_f32_16x16x32_bf16 v[124:127], v[144:147], v[184:187], v[124:127]
	v_mfma_f32_16x16x32_bf16 v[120:123], v[152:155], v[184:187], v[120:123]
	v_mfma_f32_16x16x32_bf16 v[108:111], v[144:147], v[192:195], v[108:111]
	v_mfma_f32_16x16x32_bf16 v[104:107], v[152:155], v[192:195], v[104:107]
	v_mfma_f32_16x16x32_bf16 v[92:95], v[144:147], v[200:203], v[92:95]
	v_mfma_f32_16x16x32_bf16 v[88:91], v[152:155], v[200:203], v[88:91]
	v_mfma_f32_16x16x32_bf16 v[76:79], v[144:147], v[208:211], v[76:79]
	v_mfma_f32_16x16x32_bf16 v[72:75], v[152:155], v[208:211], v[72:75]
	v_mfma_f32_16x16x32_bf16 v[124:127], v[148:151], v[188:191], v[124:127]
	v_mfma_f32_16x16x32_bf16 v[120:123], v[156:159], v[188:191], v[120:123]
	v_mfma_f32_16x16x32_bf16 v[108:111], v[148:151], v[196:199], v[108:111]
	v_mfma_f32_16x16x32_bf16 v[104:107], v[156:159], v[196:199], v[104:107]
	v_mfma_f32_16x16x32_bf16 v[92:95], v[148:151], v[204:207], v[92:95]
	v_mfma_f32_16x16x32_bf16 v[88:91], v[156:159], v[204:207], v[88:91]
	v_mfma_f32_16x16x32_bf16 v[76:79], v[148:151], v[212:215], v[76:79]
	v_mfma_f32_16x16x32_bf16 v[72:75], v[156:159], v[212:215], v[72:75]
	s_setprio 0
	s_setprio 1
	v_mfma_f32_16x16x32_bf16 v[116:119], v[160:163], v[184:187], v[116:119]
	v_mfma_f32_16x16x32_bf16 v[112:115], v[168:171], v[184:187], v[112:115]
	v_mfma_f32_16x16x32_bf16 v[100:103], v[160:163], v[192:195], v[100:103]
	v_mfma_f32_16x16x32_bf16 v[96:99], v[168:171], v[192:195], v[96:99]
	v_mfma_f32_16x16x32_bf16 v[84:87], v[160:163], v[200:203], v[84:87]
	v_mfma_f32_16x16x32_bf16 v[80:83], v[168:171], v[200:203], v[80:83]
	v_mfma_f32_16x16x32_bf16 v[68:71], v[160:163], v[208:211], v[68:71]
	v_mfma_f32_16x16x32_bf16 v[64:67], v[168:171], v[208:211], v[64:67]
	v_mfma_f32_16x16x32_bf16 v[116:119], v[164:167], v[188:191], v[116:119]
	v_mfma_f32_16x16x32_bf16 v[112:115], v[172:175], v[188:191], v[112:115]
	v_mfma_f32_16x16x32_bf16 v[100:103], v[164:167], v[196:199], v[100:103]
	v_mfma_f32_16x16x32_bf16 v[96:99], v[172:175], v[196:199], v[96:99]
	s_setprio 2
	s_barrier
	v_mfma_f32_16x16x32_bf16 v[84:87], v[164:167], v[204:207], v[84:87]
	v_mfma_f32_16x16x32_bf16 v[80:83], v[172:175], v[204:207], v[80:83]
	v_mfma_f32_16x16x32_bf16 v[68:71], v[164:167], v[212:215], v[68:71]
	v_mfma_f32_16x16x32_bf16 v[64:67], v[172:175], v[212:215], v[64:67]
	s_setprio 0
	s_add_i32 s74, s69, s51
	v_lshl_add_u64 v[176:177], s[40:41], 0, v[130:131]
	s_mov_b32 m0, s74
	ds_read_b128 v[184:187], v181 offset:16384
	ds_read_b128 v[188:191], v181 offset:17408
	ds_read_b128 v[192:195], v181 offset:18432
	ds_read_b128 v[196:199], v181 offset:19456
	ds_read_b128 v[200:203], v181 offset:20480
	ds_read_b128 v[204:207], v181 offset:21504
	ds_read_b128 v[208:211], v181 offset:22528
	ds_read_b128 v[212:215], v181 offset:23552
	global_load_lds_dwordx4 v[176:177], off
	s_add_i32 m0, s74, 0x2000
	s_add_u32 s74, s40, 0x40000
	v_lshl_add_u64 v[216:217], s[40:41], 0, v[134:135]
	s_addc_u32 s75, s41, 0
	s_add_i32 s76, s70, s51
	global_load_lds_dwordx4 v[216:217], off
	v_lshl_add_u64 v[218:219], s[74:75], 0, v[130:131]
	s_mov_b32 m0, s76
	v_lshl_add_u64 v[220:221], s[44:45], 0, v[132:133]
	global_load_lds_dwordx4 v[218:219], off
	s_add_i32 m0, s76, 0x2000
	v_lshl_add_u64 v[218:219], s[74:75], 0, v[134:135]
	global_load_lds_dwordx4 v[218:219], off
	s_mov_b32 m0, s54
	v_lshl_add_u64 v[218:219], s[44:45], 0, v[128:129]
	global_load_lds_dwordx4 v[218:219], off
	s_mov_b32 m0, s55
	s_nop 0
	global_load_lds_dwordx4 v[220:221], off
	s_waitcnt vmcnt(8)
	s_waitcnt lgkmcnt(0)
	s_barrier
	s_setprio 1
	s_waitcnt lgkmcnt(0)
	v_mfma_f32_16x16x32_bf16 v[60:63], v[144:147], v[184:187], v[60:63]
	v_mfma_f32_16x16x32_bf16 v[56:59], v[152:155], v[184:187], v[56:59]
	v_mfma_f32_16x16x32_bf16 v[44:47], v[144:147], v[192:195], v[44:47]
	v_mfma_f32_16x16x32_bf16 v[40:43], v[152:155], v[192:195], v[40:43]
	v_mfma_f32_16x16x32_bf16 v[28:31], v[144:147], v[200:203], v[28:31]
	v_mfma_f32_16x16x32_bf16 v[24:27], v[152:155], v[200:203], v[24:27]
	v_mfma_f32_16x16x32_bf16 v[12:15], v[144:147], v[208:211], v[12:15]
	v_mfma_f32_16x16x32_bf16 v[8:11], v[152:155], v[208:211], v[8:11]
	v_mfma_f32_16x16x32_bf16 v[60:63], v[148:151], v[188:191], v[60:63]
	v_mfma_f32_16x16x32_bf16 v[56:59], v[156:159], v[188:191], v[56:59]
	v_mfma_f32_16x16x32_bf16 v[44:47], v[148:151], v[196:199], v[44:47]
	v_mfma_f32_16x16x32_bf16 v[40:43], v[156:159], v[196:199], v[40:43]
	v_mfma_f32_16x16x32_bf16 v[28:31], v[148:151], v[204:207], v[28:31]
	v_mfma_f32_16x16x32_bf16 v[24:27], v[156:159], v[204:207], v[24:27]
	v_mfma_f32_16x16x32_bf16 v[12:15], v[148:151], v[212:215], v[12:15]
	v_mfma_f32_16x16x32_bf16 v[8:11], v[156:159], v[212:215], v[8:11]
	s_setprio 0
	s_setprio 1
	v_mfma_f32_16x16x32_bf16 v[52:55], v[160:163], v[184:187], v[52:55]
	v_mfma_f32_16x16x32_bf16 v[48:51], v[168:171], v[184:187], v[48:51]
	v_mfma_f32_16x16x32_bf16 v[36:39], v[160:163], v[192:195], v[36:39]
	v_mfma_f32_16x16x32_bf16 v[32:35], v[168:171], v[192:195], v[32:35]
	v_mfma_f32_16x16x32_bf16 v[20:23], v[160:163], v[200:203], v[20:23]
	v_mfma_f32_16x16x32_bf16 v[16:19], v[168:171], v[200:203], v[16:19]
	v_mfma_f32_16x16x32_bf16 v[4:7], v[160:163], v[208:211], v[4:7]
	v_mfma_f32_16x16x32_bf16 v[0:3], v[168:171], v[208:211], v[0:3]
	v_mfma_f32_16x16x32_bf16 v[52:55], v[164:167], v[188:191], v[52:55]
	v_mfma_f32_16x16x32_bf16 v[48:51], v[172:175], v[188:191], v[48:51]
	v_mfma_f32_16x16x32_bf16 v[36:39], v[164:167], v[196:199], v[36:39]
	v_mfma_f32_16x16x32_bf16 v[32:35], v[172:175], v[196:199], v[32:35]
	s_setprio 2
	s_barrier
	v_mfma_f32_16x16x32_bf16 v[20:23], v[164:167], v[204:207], v[20:23]
	v_mfma_f32_16x16x32_bf16 v[16:19], v[172:175], v[204:207], v[16:19]
	v_mfma_f32_16x16x32_bf16 v[4:7], v[164:167], v[212:215], v[4:7]
	v_mfma_f32_16x16x32_bf16 v[0:3], v[172:175], v[212:215], v[0:3]
	s_setprio 0
	s_add_i32 s74, 0, 0x18000
	s_add_i32 s75, 0, 0x1c000
	v_add_u32_e32 v156, s74, v178
	v_add_u32_e32 v172, s75, v178
	ds_read_b128 v[144:147], v156
	ds_read_b128 v[148:151], v156 offset:1024
	ds_read_b128 v[152:155], v156 offset:2048
	ds_read_b128 v[156:159], v156 offset:3072
	ds_read_b128 v[160:163], v172
	ds_read_b128 v[164:167], v172 offset:1024
	ds_read_b128 v[168:171], v172 offset:2048
	ds_read_b128 v[172:175], v172 offset:3072
	s_add_u32 s44, s44, 0x40000
	s_addc_u32 s45, s45, 0
	s_mov_b32 m0, s56
	v_lshl_add_u64 v[222:223], s[44:45], 0, v[128:129]
	ds_read_b128 v[184:187], v181 offset:32768
	ds_read_b128 v[188:191], v181 offset:33792
	ds_read_b128 v[192:195], v181 offset:34816
	ds_read_b128 v[196:199], v181 offset:35840
	ds_read_b128 v[200:203], v181 offset:36864
	ds_read_b128 v[204:207], v181 offset:37888
	ds_read_b128 v[208:211], v181 offset:38912
	ds_read_b128 v[212:215], v181 offset:39936
	global_load_lds_dwordx4 v[222:223], off
	s_mov_b32 m0, s57
	v_lshl_add_u64 v[222:223], s[44:45], 0, v[132:133]
	global_load_lds_dwordx4 v[222:223], off
	s_waitcnt vmcnt(8)
	s_waitcnt lgkmcnt(0)
	s_barrier
	s_setprio 1
	s_waitcnt lgkmcnt(0)
	v_mfma_f32_16x16x32_bf16 v[124:127], v[144:147], v[184:187], v[124:127]
	v_mfma_f32_16x16x32_bf16 v[120:123], v[152:155], v[184:187], v[120:123]
	v_mfma_f32_16x16x32_bf16 v[108:111], v[144:147], v[192:195], v[108:111]
	v_mfma_f32_16x16x32_bf16 v[104:107], v[152:155], v[192:195], v[104:107]
	v_mfma_f32_16x16x32_bf16 v[92:95], v[144:147], v[200:203], v[92:95]
	v_mfma_f32_16x16x32_bf16 v[88:91], v[152:155], v[200:203], v[88:91]
	v_mfma_f32_16x16x32_bf16 v[76:79], v[144:147], v[208:211], v[76:79]
	v_mfma_f32_16x16x32_bf16 v[72:75], v[152:155], v[208:211], v[72:75]
	v_mfma_f32_16x16x32_bf16 v[124:127], v[148:151], v[188:191], v[124:127]
	v_mfma_f32_16x16x32_bf16 v[120:123], v[156:159], v[188:191], v[120:123]
	v_mfma_f32_16x16x32_bf16 v[108:111], v[148:151], v[196:199], v[108:111]
	v_mfma_f32_16x16x32_bf16 v[104:107], v[156:159], v[196:199], v[104:107]
	v_mfma_f32_16x16x32_bf16 v[92:95], v[148:151], v[204:207], v[92:95]
	v_mfma_f32_16x16x32_bf16 v[88:91], v[156:159], v[204:207], v[88:91]
	v_mfma_f32_16x16x32_bf16 v[76:79], v[148:151], v[212:215], v[76:79]
	v_mfma_f32_16x16x32_bf16 v[72:75], v[156:159], v[212:215], v[72:75]
	s_setprio 0
	s_setprio 1
	v_mfma_f32_16x16x32_bf16 v[116:119], v[160:163], v[184:187], v[116:119]
	v_mfma_f32_16x16x32_bf16 v[112:115], v[168:171], v[184:187], v[112:115]
	v_mfma_f32_16x16x32_bf16 v[100:103], v[160:163], v[192:195], v[100:103]
	v_mfma_f32_16x16x32_bf16 v[96:99], v[168:171], v[192:195], v[96:99]
	v_mfma_f32_16x16x32_bf16 v[84:87], v[160:163], v[200:203], v[84:87]
	v_mfma_f32_16x16x32_bf16 v[80:83], v[168:171], v[200:203], v[80:83]
	v_mfma_f32_16x16x32_bf16 v[68:71], v[160:163], v[208:211], v[68:71]
	v_mfma_f32_16x16x32_bf16 v[64:67], v[168:171], v[208:211], v[64:67]
	v_mfma_f32_16x16x32_bf16 v[116:119], v[164:167], v[188:191], v[116:119]
	v_mfma_f32_16x16x32_bf16 v[112:115], v[172:175], v[188:191], v[112:115]
	v_mfma_f32_16x16x32_bf16 v[100:103], v[164:167], v[196:199], v[100:103]
	v_mfma_f32_16x16x32_bf16 v[96:99], v[172:175], v[196:199], v[96:99]
	s_setprio 2
	s_barrier
	v_mfma_f32_16x16x32_bf16 v[84:87], v[164:167], v[204:207], v[84:87]
	v_mfma_f32_16x16x32_bf16 v[80:83], v[172:175], v[204:207], v[80:83]
	v_mfma_f32_16x16x32_bf16 v[68:71], v[164:167], v[212:215], v[68:71]
	v_mfma_f32_16x16x32_bf16 v[64:67], v[172:175], v[212:215], v[64:67]
	s_setprio 0
	s_add_i32 s44, s74, s51
	v_lshl_add_u64 v[176:177], v[176:177], 0, s[22:23]
	s_mov_b32 m0, s44
	ds_read_b128 v[184:187], v181 offset:49152
	ds_read_b128 v[188:191], v181 offset:50176
	ds_read_b128 v[192:195], v181 offset:51200
	ds_read_b128 v[196:199], v181 offset:52224
	ds_read_b128 v[200:203], v181 offset:53248
	ds_read_b128 v[204:207], v181 offset:54272
	ds_read_b128 v[208:211], v181 offset:55296
	ds_read_b128 v[212:215], v181 offset:56320
	global_load_lds_dwordx4 v[176:177], off
	s_add_i32 m0, s44, 0x2000
	s_add_u32 s40, s40, 0x40080
	v_lshl_add_u64 v[176:177], v[216:217], 0, s[22:23]
	s_addc_u32 s41, s41, 0
	s_add_i32 s44, s75, s51
	global_load_lds_dwordx4 v[176:177], off
	s_mov_b32 m0, s44
	v_lshl_add_u64 v[176:177], s[40:41], 0, v[130:131]
	global_load_lds_dwordx4 v[176:177], off
	s_add_i32 m0, s44, 0x2000
	v_lshl_add_u64 v[176:177], s[40:41], 0, v[134:135]
	global_load_lds_dwordx4 v[176:177], off
	s_mov_b32 m0, s64
	v_lshl_add_u64 v[176:177], v[218:219], 0, s[22:23]
	global_load_lds_dwordx4 v[176:177], off
	s_mov_b32 m0, s65
	v_lshl_add_u64 v[176:177], v[220:221], 0, s[22:23]
	global_load_lds_dwordx4 v[176:177], off
	s_waitcnt vmcnt(8)
	s_waitcnt lgkmcnt(0)
	s_barrier
	s_setprio 1
	s_waitcnt lgkmcnt(0)
	v_mfma_f32_16x16x32_bf16 v[60:63], v[144:147], v[184:187], v[60:63]
	v_mfma_f32_16x16x32_bf16 v[56:59], v[152:155], v[184:187], v[56:59]
	v_mfma_f32_16x16x32_bf16 v[44:47], v[144:147], v[192:195], v[44:47]
	v_mfma_f32_16x16x32_bf16 v[40:43], v[152:155], v[192:195], v[40:43]
	v_mfma_f32_16x16x32_bf16 v[28:31], v[144:147], v[200:203], v[28:31]
	v_mfma_f32_16x16x32_bf16 v[24:27], v[152:155], v[200:203], v[24:27]
	v_mfma_f32_16x16x32_bf16 v[12:15], v[144:147], v[208:211], v[12:15]
	v_mfma_f32_16x16x32_bf16 v[8:11], v[152:155], v[208:211], v[8:11]
	v_mfma_f32_16x16x32_bf16 v[60:63], v[148:151], v[188:191], v[60:63]
	v_mfma_f32_16x16x32_bf16 v[56:59], v[156:159], v[188:191], v[56:59]
	v_mfma_f32_16x16x32_bf16 v[44:47], v[148:151], v[196:199], v[44:47]
	v_mfma_f32_16x16x32_bf16 v[40:43], v[156:159], v[196:199], v[40:43]
	v_mfma_f32_16x16x32_bf16 v[28:31], v[148:151], v[204:207], v[28:31]
	v_mfma_f32_16x16x32_bf16 v[24:27], v[156:159], v[204:207], v[24:27]
	v_mfma_f32_16x16x32_bf16 v[12:15], v[148:151], v[212:215], v[12:15]
	v_mfma_f32_16x16x32_bf16 v[8:11], v[156:159], v[212:215], v[8:11]
	s_setprio 0
	s_setprio 1
	v_mfma_f32_16x16x32_bf16 v[52:55], v[160:163], v[184:187], v[52:55]
	v_mfma_f32_16x16x32_bf16 v[48:51], v[168:171], v[184:187], v[48:51]
	v_mfma_f32_16x16x32_bf16 v[36:39], v[160:163], v[192:195], v[36:39]
	v_mfma_f32_16x16x32_bf16 v[32:35], v[168:171], v[192:195], v[32:35]
	v_mfma_f32_16x16x32_bf16 v[20:23], v[160:163], v[200:203], v[20:23]
	v_mfma_f32_16x16x32_bf16 v[16:19], v[168:171], v[200:203], v[16:19]
	v_mfma_f32_16x16x32_bf16 v[4:7], v[160:163], v[208:211], v[4:7]
	v_mfma_f32_16x16x32_bf16 v[0:3], v[168:171], v[208:211], v[0:3]
	v_mfma_f32_16x16x32_bf16 v[52:55], v[164:167], v[188:191], v[52:55]
	v_mfma_f32_16x16x32_bf16 v[48:51], v[172:175], v[188:191], v[48:51]
	v_mfma_f32_16x16x32_bf16 v[36:39], v[164:167], v[196:199], v[36:39]
	v_mfma_f32_16x16x32_bf16 v[32:35], v[172:175], v[196:199], v[32:35]
	s_setprio 2
	s_barrier
	v_mfma_f32_16x16x32_bf16 v[20:23], v[164:167], v[204:207], v[20:23]
	v_mfma_f32_16x16x32_bf16 v[16:19], v[172:175], v[204:207], v[16:19]
	v_mfma_f32_16x16x32_bf16 v[4:7], v[164:167], v[212:215], v[4:7]
	v_mfma_f32_16x16x32_bf16 v[0:3], v[172:175], v[212:215], v[0:3]
	s_setprio 0
	s_add_i32 s73, s73, 2
	s_add_u32 s6, s6, 0x100
	s_addc_u32 s7, s7, 0
	s_add_u32 s71, s71, 0x100
	s_addc_u32 s72, s72, 0
	s_cmp_gt_u32 s73, 13
	s_cbranch_scc0 .LBB0_952

.LBB0_1145:
	s_ashr_i32 s23, s22, 31
	s_lshl_b64 s[26:27], s[22:23], 19
	s_add_u32 s26, s45, s26
	s_addc_u32 s27, s46, s27
	s_and_b64 s[28:29], s[4:5], exec
	s_cselect_b32 s23, s27, s39
	s_cselect_b32 s31, s26, s38
	s_ashr_i32 s25, s24, 31
	s_lshl_b64 s[28:29], s[24:25], 19
	s_add_u32 s28, s47, s28
	s_addc_u32 s29, s48, s29
	s_and_b64 s[42:43], s[4:5], exec
	s_cselect_b32 s25, s29, s41
	s_cselect_b32 s37, s28, s40
	s_add_u32 s38, s38, 0x40080
	s_addc_u32 s39, s39, 0
	s_add_u32 s64, s40, 0x100
	s_addc_u32 s65, s41, 0
	s_mov_b32 s66, -2
	ds_read_b128 v[120:123], v233
	ds_read_b128 v[132:135], v233 offset:1024
	ds_read_b128 v[136:139], v233 offset:2048
	ds_read_b128 v[140:143], v233 offset:3072
	ds_read_b128 v[144:147], v234
	ds_read_b128 v[148:151], v234 offset:1024
	ds_read_b128 v[152:155], v234 offset:2048
	ds_read_b128 v[156:159], v234 offset:3072
	s_add_u32 s40, s38, 0xfffc0080
	s_addc_u32 s41, s39, -1
	s_cmp_eq_u32 s66, 12
	s_cselect_b32 s43, s23, s41
	s_cselect_b32 s42, s31, s40
	s_cselect_b32 s41, s25, s65
	s_cselect_b32 s40, s37, s64
	v_lshl_add_u64 v[208:209], s[38:39], 0, v[192:193]
	s_add_i32 m0, s50, 0xc000
	ds_read_b128 v[160:163], v235
	ds_read_b128 v[164:167], v235 offset:1024
	ds_read_b128 v[168:171], v235 offset:2048
	ds_read_b128 v[172:175], v235 offset:3072
	ds_read_b128 v[176:179], v235 offset:4096
	ds_read_b128 v[180:183], v235 offset:5120
	ds_read_b128 v[200:203], v235 offset:6144
	ds_read_b128 v[204:207], v235 offset:7168
	global_load_lds_dwordx4 v[208:209], off
	s_add_i32 m0, s50, 0xe000
	v_lshl_add_u64 v[208:209], s[38:39], 0, v[194:195]
	global_load_lds_dwordx4 v[208:209], off
	s_waitcnt vmcnt(8)
	s_waitcnt lgkmcnt(0)
	s_barrier
	s_setprio 1
	s_waitcnt lgkmcnt(0)
	v_mfma_f32_16x16x32_bf16 v[128:131], v[120:123], v[160:163], 0
	v_mfma_f32_16x16x32_bf16 v[124:127], v[136:139], v[160:163], 0
	v_mfma_f32_16x16x32_bf16 v[108:111], v[120:123], v[168:171], 0
	v_mfma_f32_16x16x32_bf16 v[104:107], v[136:139], v[168:171], 0
	v_mfma_f32_16x16x32_bf16 v[92:95], v[120:123], v[176:179], 0
	v_mfma_f32_16x16x32_bf16 v[88:91], v[136:139], v[176:179], 0
	v_mfma_f32_16x16x32_bf16 v[76:79], v[120:123], v[200:203], 0
	v_mfma_f32_16x16x32_bf16 v[72:75], v[136:139], v[200:203], 0
	v_mfma_f32_16x16x32_bf16 v[128:131], v[132:135], v[164:167], v[128:131]
	v_mfma_f32_16x16x32_bf16 v[124:127], v[140:143], v[164:167], v[124:127]
	v_mfma_f32_16x16x32_bf16 v[108:111], v[132:135], v[172:175], v[108:111]
	v_mfma_f32_16x16x32_bf16 v[104:107], v[140:143], v[172:175], v[104:107]
	v_mfma_f32_16x16x32_bf16 v[92:95], v[132:135], v[180:183], v[92:95]
	v_mfma_f32_16x16x32_bf16 v[88:91], v[140:143], v[180:183], v[88:91]
	v_mfma_f32_16x16x32_bf16 v[76:79], v[132:135], v[204:207], v[76:79]
	v_mfma_f32_16x16x32_bf16 v[72:75], v[140:143], v[204:207], v[72:75]
	s_setprio 0
	s_setprio 1
	v_mfma_f32_16x16x32_bf16 v[116:119], v[144:147], v[160:163], 0
	v_mfma_f32_16x16x32_bf16 v[112:115], v[152:155], v[160:163], 0
	v_mfma_f32_16x16x32_bf16 v[100:103], v[144:147], v[168:171], 0
	v_mfma_f32_16x16x32_bf16 v[96:99], v[152:155], v[168:171], 0
	v_mfma_f32_16x16x32_bf16 v[84:87], v[144:147], v[176:179], 0
	v_mfma_f32_16x16x32_bf16 v[80:83], v[152:155], v[176:179], 0
	v_mfma_f32_16x16x32_bf16 v[68:71], v[144:147], v[200:203], 0
	v_mfma_f32_16x16x32_bf16 v[64:67], v[152:155], v[200:203], 0
	v_mfma_f32_16x16x32_bf16 v[116:119], v[148:151], v[164:167], v[116:119]
	v_mfma_f32_16x16x32_bf16 v[112:115], v[156:159], v[164:167], v[112:115]
	v_mfma_f32_16x16x32_bf16 v[100:103], v[148:151], v[172:175], v[100:103]
	v_mfma_f32_16x16x32_bf16 v[96:99], v[156:159], v[172:175], v[96:99]
	s_setprio 2
	s_barrier
	v_mfma_f32_16x16x32_bf16 v[84:87], v[148:151], v[180:183], v[84:87]
	v_mfma_f32_16x16x32_bf16 v[80:83], v[156:159], v[180:183], v[80:83]
	v_mfma_f32_16x16x32_bf16 v[68:71], v[148:151], v[204:207], v[68:71]
	v_mfma_f32_16x16x32_bf16 v[64:67], v[156:159], v[204:207], v[64:67]
	s_setprio 0
	s_add_i32 s67, s62, s49
	v_lshl_add_u64 v[208:209], s[40:41], 0, v[186:187]
	s_mov_b32 m0, s67
	ds_read_b128 v[160:163], v235 offset:16384
	ds_read_b128 v[164:167], v235 offset:17408
	ds_read_b128 v[168:171], v235 offset:18432
	ds_read_b128 v[172:175], v235 offset:19456
	ds_read_b128 v[176:179], v235 offset:20480
	ds_read_b128 v[180:183], v235 offset:21504
	ds_read_b128 v[200:203], v235 offset:22528
	ds_read_b128 v[204:207], v235 offset:23552
	global_load_lds_dwordx4 v[208:209], off
	s_add_i32 m0, s67, 0x2000
	s_add_u32 s68, s40, 0x40000
	v_lshl_add_u64 v[210:211], s[40:41], 0, v[190:191]
	s_addc_u32 s69, s41, 0
	s_add_i32 s67, s63, s49
	global_load_lds_dwordx4 v[210:211], off
	v_lshl_add_u64 v[212:213], s[68:69], 0, v[186:187]
	s_mov_b32 m0, s67
	v_lshl_add_u64 v[214:215], s[42:43], 0, v[188:189]
	global_load_lds_dwordx4 v[212:213], off
	s_add_i32 m0, s67, 0x2000
	v_lshl_add_u64 v[212:213], s[68:69], 0, v[190:191]
	global_load_lds_dwordx4 v[212:213], off
	s_mov_b32 m0, s50
	v_lshl_add_u64 v[212:213], s[42:43], 0, v[184:185]
	global_load_lds_dwordx4 v[212:213], off
	s_mov_b32 m0, s51
	s_nop 0
	global_load_lds_dwordx4 v[214:215], off
	s_waitcnt vmcnt(8)
	s_waitcnt lgkmcnt(0)
	s_barrier
	s_setprio 1
	s_waitcnt lgkmcnt(0)
	v_mfma_f32_16x16x32_bf16 v[60:63], v[120:123], v[160:163], 0
	v_mfma_f32_16x16x32_bf16 v[56:59], v[136:139], v[160:163], 0
	v_mfma_f32_16x16x32_bf16 v[44:47], v[120:123], v[168:171], 0
	v_mfma_f32_16x16x32_bf16 v[40:43], v[136:139], v[168:171], 0
	v_mfma_f32_16x16x32_bf16 v[28:31], v[120:123], v[176:179], 0
	v_mfma_f32_16x16x32_bf16 v[24:27], v[136:139], v[176:179], 0
	v_mfma_f32_16x16x32_bf16 v[12:15], v[120:123], v[200:203], 0
	v_mfma_f32_16x16x32_bf16 v[8:11], v[136:139], v[200:203], 0
	v_mfma_f32_16x16x32_bf16 v[60:63], v[132:135], v[164:167], v[60:63]
	v_mfma_f32_16x16x32_bf16 v[56:59], v[140:143], v[164:167], v[56:59]
	v_mfma_f32_16x16x32_bf16 v[44:47], v[132:135], v[172:175], v[44:47]
	v_mfma_f32_16x16x32_bf16 v[40:43], v[140:143], v[172:175], v[40:43]
	v_mfma_f32_16x16x32_bf16 v[28:31], v[132:135], v[180:183], v[28:31]
	v_mfma_f32_16x16x32_bf16 v[24:27], v[140:143], v[180:183], v[24:27]
	v_mfma_f32_16x16x32_bf16 v[12:15], v[132:135], v[204:207], v[12:15]
	v_mfma_f32_16x16x32_bf16 v[8:11], v[140:143], v[204:207], v[8:11]
	s_setprio 0
	s_setprio 1
	v_mfma_f32_16x16x32_bf16 v[52:55], v[144:147], v[160:163], 0
	v_mfma_f32_16x16x32_bf16 v[48:51], v[152:155], v[160:163], 0
	v_mfma_f32_16x16x32_bf16 v[36:39], v[144:147], v[168:171], 0
	v_mfma_f32_16x16x32_bf16 v[32:35], v[152:155], v[168:171], 0
	v_mfma_f32_16x16x32_bf16 v[20:23], v[144:147], v[176:179], 0
	v_mfma_f32_16x16x32_bf16 v[16:19], v[152:155], v[176:179], 0
	v_mfma_f32_16x16x32_bf16 v[4:7], v[144:147], v[200:203], 0
	v_mfma_f32_16x16x32_bf16 v[0:3], v[152:155], v[200:203], 0
	v_mfma_f32_16x16x32_bf16 v[52:55], v[148:151], v[164:167], v[52:55]
	v_mfma_f32_16x16x32_bf16 v[48:51], v[156:159], v[164:167], v[48:51]
	v_mfma_f32_16x16x32_bf16 v[36:39], v[148:151], v[172:175], v[36:39]
	v_mfma_f32_16x16x32_bf16 v[32:35], v[156:159], v[172:175], v[32:35]
	s_setprio 2
	s_barrier
	v_mfma_f32_16x16x32_bf16 v[20:23], v[148:151], v[180:183], v[20:23]
	v_mfma_f32_16x16x32_bf16 v[16:19], v[156:159], v[180:183], v[16:19]
	v_mfma_f32_16x16x32_bf16 v[4:7], v[148:151], v[204:207], v[4:7]
	v_mfma_f32_16x16x32_bf16 v[0:3], v[156:159], v[204:207], v[0:3]
	s_setprio 0
	s_add_i32 s67, 0, 0x18000
	s_add_i32 s68, 0, 0x1c000
	v_add_u32_e32 v140, s67, v232
	v_add_u32_e32 v156, s68, v232
	ds_read_b128 v[120:123], v140
	ds_read_b128 v[132:135], v140 offset:1024
	ds_read_b128 v[136:139], v140 offset:2048
	ds_read_b128 v[140:143], v140 offset:3072
	ds_read_b128 v[144:147], v156
	ds_read_b128 v[148:151], v156 offset:1024
	ds_read_b128 v[152:155], v156 offset:2048
	ds_read_b128 v[156:159], v156 offset:3072
	s_add_u32 s42, s42, 0x40000
	s_addc_u32 s43, s43, 0
	s_mov_b32 m0, s54
	v_lshl_add_u64 v[216:217], s[42:43], 0, v[184:185]
	ds_read_b128 v[160:163], v235 offset:32768
	ds_read_b128 v[164:167], v235 offset:33792
	ds_read_b128 v[168:171], v235 offset:34816
	ds_read_b128 v[172:175], v235 offset:35840
	ds_read_b128 v[176:179], v235 offset:36864
	ds_read_b128 v[180:183], v235 offset:37888
	ds_read_b128 v[200:203], v235 offset:38912
	ds_read_b128 v[204:207], v235 offset:39936
	global_load_lds_dwordx4 v[216:217], off
	s_mov_b32 m0, s55
	v_lshl_add_u64 v[216:217], s[42:43], 0, v[188:189]
	global_load_lds_dwordx4 v[216:217], off
	s_waitcnt vmcnt(8)
	s_waitcnt lgkmcnt(0)
	s_barrier
	s_setprio 1
	s_waitcnt lgkmcnt(0)
	v_mfma_f32_16x16x32_bf16 v[128:131], v[120:123], v[160:163], v[128:131]
	v_mfma_f32_16x16x32_bf16 v[124:127], v[136:139], v[160:163], v[124:127]
	v_mfma_f32_16x16x32_bf16 v[108:111], v[120:123], v[168:171], v[108:111]
	v_mfma_f32_16x16x32_bf16 v[104:107], v[136:139], v[168:171], v[104:107]
	v_mfma_f32_16x16x32_bf16 v[92:95], v[120:123], v[176:179], v[92:95]
	v_mfma_f32_16x16x32_bf16 v[88:91], v[136:139], v[176:179], v[88:91]
	v_mfma_f32_16x16x32_bf16 v[76:79], v[120:123], v[200:203], v[76:79]
	v_mfma_f32_16x16x32_bf16 v[72:75], v[136:139], v[200:203], v[72:75]
	v_mfma_f32_16x16x32_bf16 v[128:131], v[132:135], v[164:167], v[128:131]
	v_mfma_f32_16x16x32_bf16 v[124:127], v[140:143], v[164:167], v[124:127]
	v_mfma_f32_16x16x32_bf16 v[108:111], v[132:135], v[172:175], v[108:111]
	v_mfma_f32_16x16x32_bf16 v[104:107], v[140:143], v[172:175], v[104:107]
	v_mfma_f32_16x16x32_bf16 v[92:95], v[132:135], v[180:183], v[92:95]
	v_mfma_f32_16x16x32_bf16 v[88:91], v[140:143], v[180:183], v[88:91]
	v_mfma_f32_16x16x32_bf16 v[76:79], v[132:135], v[204:207], v[76:79]
	v_mfma_f32_16x16x32_bf16 v[72:75], v[140:143], v[204:207], v[72:75]
	s_setprio 0
	s_setprio 1
	v_mfma_f32_16x16x32_bf16 v[116:119], v[144:147], v[160:163], v[116:119]
	v_mfma_f32_16x16x32_bf16 v[112:115], v[152:155], v[160:163], v[112:115]
	v_mfma_f32_16x16x32_bf16 v[100:103], v[144:147], v[168:171], v[100:103]
	v_mfma_f32_16x16x32_bf16 v[96:99], v[152:155], v[168:171], v[96:99]
	v_mfma_f32_16x16x32_bf16 v[84:87], v[144:147], v[176:179], v[84:87]
	v_mfma_f32_16x16x32_bf16 v[80:83], v[152:155], v[176:179], v[80:83]
	v_mfma_f32_16x16x32_bf16 v[68:71], v[144:147], v[200:203], v[68:71]
	v_mfma_f32_16x16x32_bf16 v[64:67], v[152:155], v[200:203], v[64:67]
	v_mfma_f32_16x16x32_bf16 v[116:119], v[148:151], v[164:167], v[116:119]
	v_mfma_f32_16x16x32_bf16 v[112:115], v[156:159], v[164:167], v[112:115]
	v_mfma_f32_16x16x32_bf16 v[100:103], v[148:151], v[172:175], v[100:103]
	v_mfma_f32_16x16x32_bf16 v[96:99], v[156:159], v[172:175], v[96:99]
	s_setprio 2
	s_barrier
	v_mfma_f32_16x16x32_bf16 v[84:87], v[148:151], v[180:183], v[84:87]
	v_mfma_f32_16x16x32_bf16 v[80:83], v[156:159], v[180:183], v[80:83]
	v_mfma_f32_16x16x32_bf16 v[68:71], v[148:151], v[204:207], v[68:71]
	v_mfma_f32_16x16x32_bf16 v[64:67], v[156:159], v[204:207], v[64:67]
	s_setprio 0
	s_add_i32 s42, s67, s49
	v_lshl_add_u64 v[208:209], v[208:209], 0, s[18:19]
	s_mov_b32 m0, s42
	ds_read_b128 v[160:163], v235 offset:49152
	ds_read_b128 v[164:167], v235 offset:50176
	ds_read_b128 v[168:171], v235 offset:51200
	ds_read_b128 v[172:175], v235 offset:52224
	ds_read_b128 v[176:179], v235 offset:53248
	ds_read_b128 v[180:183], v235 offset:54272
	ds_read_b128 v[200:203], v235 offset:55296
	ds_read_b128 v[204:207], v235 offset:56320
	global_load_lds_dwordx4 v[208:209], off
	s_add_i32 m0, s42, 0x2000
	s_add_u32 s40, s40, 0x40080
	v_lshl_add_u64 v[208:209], v[210:211], 0, s[18:19]
	s_addc_u32 s41, s41, 0
	s_add_i32 s42, s68, s49
	global_load_lds_dwordx4 v[208:209], off
	s_mov_b32 m0, s42
	v_lshl_add_u64 v[208:209], s[40:41], 0, v[186:187]
	global_load_lds_dwordx4 v[208:209], off
	s_add_i32 m0, s42, 0x2000
	v_lshl_add_u64 v[208:209], s[40:41], 0, v[190:191]
	global_load_lds_dwordx4 v[208:209], off
	s_mov_b32 m0, s57
	v_lshl_add_u64 v[208:209], v[212:213], 0, s[18:19]
	global_load_lds_dwordx4 v[208:209], off
	s_mov_b32 m0, s58
	v_lshl_add_u64 v[208:209], v[214:215], 0, s[18:19]
	global_load_lds_dwordx4 v[208:209], off
	s_waitcnt vmcnt(8)
	s_waitcnt lgkmcnt(0)
	s_barrier
	s_setprio 1
	s_waitcnt lgkmcnt(0)
	v_mfma_f32_16x16x32_bf16 v[60:63], v[120:123], v[160:163], v[60:63]
	v_mfma_f32_16x16x32_bf16 v[56:59], v[136:139], v[160:163], v[56:59]
	v_mfma_f32_16x16x32_bf16 v[44:47], v[120:123], v[168:171], v[44:47]
	v_mfma_f32_16x16x32_bf16 v[40:43], v[136:139], v[168:171], v[40:43]
	v_mfma_f32_16x16x32_bf16 v[28:31], v[120:123], v[176:179], v[28:31]
	v_mfma_f32_16x16x32_bf16 v[24:27], v[136:139], v[176:179], v[24:27]
	v_mfma_f32_16x16x32_bf16 v[12:15], v[120:123], v[200:203], v[12:15]
	v_mfma_f32_16x16x32_bf16 v[8:11], v[136:139], v[200:203], v[8:11]
	v_mfma_f32_16x16x32_bf16 v[60:63], v[132:135], v[164:167], v[60:63]
	v_mfma_f32_16x16x32_bf16 v[56:59], v[140:143], v[164:167], v[56:59]
	v_mfma_f32_16x16x32_bf16 v[44:47], v[132:135], v[172:175], v[44:47]
	v_mfma_f32_16x16x32_bf16 v[40:43], v[140:143], v[172:175], v[40:43]
	v_mfma_f32_16x16x32_bf16 v[28:31], v[132:135], v[180:183], v[28:31]
	v_mfma_f32_16x16x32_bf16 v[24:27], v[140:143], v[180:183], v[24:27]
	v_mfma_f32_16x16x32_bf16 v[12:15], v[132:135], v[204:207], v[12:15]
	v_mfma_f32_16x16x32_bf16 v[8:11], v[140:143], v[204:207], v[8:11]
	s_setprio 0
	s_setprio 1
	v_mfma_f32_16x16x32_bf16 v[52:55], v[144:147], v[160:163], v[52:55]
	v_mfma_f32_16x16x32_bf16 v[48:51], v[152:155], v[160:163], v[48:51]
	v_mfma_f32_16x16x32_bf16 v[36:39], v[144:147], v[168:171], v[36:39]
	v_mfma_f32_16x16x32_bf16 v[32:35], v[152:155], v[168:171], v[32:35]
	v_mfma_f32_16x16x32_bf16 v[20:23], v[144:147], v[176:179], v[20:23]
	v_mfma_f32_16x16x32_bf16 v[16:19], v[152:155], v[176:179], v[16:19]
	v_mfma_f32_16x16x32_bf16 v[4:7], v[144:147], v[200:203], v[4:7]
	v_mfma_f32_16x16x32_bf16 v[0:3], v[152:155], v[200:203], v[0:3]
	v_mfma_f32_16x16x32_bf16 v[52:55], v[148:151], v[164:167], v[52:55]
	v_mfma_f32_16x16x32_bf16 v[48:51], v[156:159], v[164:167], v[48:51]
	v_mfma_f32_16x16x32_bf16 v[36:39], v[148:151], v[172:175], v[36:39]
	v_mfma_f32_16x16x32_bf16 v[32:35], v[156:159], v[172:175], v[32:35]
	s_setprio 2
	s_barrier
	v_mfma_f32_16x16x32_bf16 v[20:23], v[148:151], v[180:183], v[20:23]
	v_mfma_f32_16x16x32_bf16 v[16:19], v[156:159], v[180:183], v[16:19]
	v_mfma_f32_16x16x32_bf16 v[4:7], v[148:151], v[204:207], v[4:7]
	v_mfma_f32_16x16x32_bf16 v[0:3], v[156:159], v[204:207], v[0:3]
	s_setprio 0
	s_add_i32 s66, s66, 2
	s_add_u32 s38, s38, 0x100
	s_addc_u32 s39, s39, 0
	s_add_u32 s64, s64, 0x100
	s_addc_u32 s65, s65, 0
	s_cmp_gt_u32 s66, 13
.LBB0_1146:
	ds_read_b128 v[120:123], v233
	ds_read_b128 v[132:135], v233 offset:1024
	ds_read_b128 v[136:139], v233 offset:2048
	ds_read_b128 v[140:143], v233 offset:3072
	ds_read_b128 v[144:147], v234
	ds_read_b128 v[148:151], v234 offset:1024
	ds_read_b128 v[152:155], v234 offset:2048
	ds_read_b128 v[156:159], v234 offset:3072
	s_add_u32 s40, s38, 0xfffc0080
	s_addc_u32 s41, s39, -1
	s_cmp_eq_u32 s66, 12
	s_cselect_b32 s43, s23, s41
	s_cselect_b32 s42, s31, s40
	s_cselect_b32 s41, s25, s65
	s_cselect_b32 s40, s37, s64
	v_lshl_add_u64 v[208:209], s[38:39], 0, v[192:193]
	s_add_i32 m0, s50, 0xc000
	ds_read_b128 v[160:163], v235
	ds_read_b128 v[164:167], v235 offset:1024
	ds_read_b128 v[168:171], v235 offset:2048
	ds_read_b128 v[172:175], v235 offset:3072
	ds_read_b128 v[176:179], v235 offset:4096
	ds_read_b128 v[180:183], v235 offset:5120
	ds_read_b128 v[200:203], v235 offset:6144
	ds_read_b128 v[204:207], v235 offset:7168
	global_load_lds_dwordx4 v[208:209], off
	s_add_i32 m0, s50, 0xe000
	v_lshl_add_u64 v[208:209], s[38:39], 0, v[194:195]
	global_load_lds_dwordx4 v[208:209], off
	s_waitcnt vmcnt(8)
	s_waitcnt lgkmcnt(0)
	s_barrier
	s_setprio 1
	s_waitcnt lgkmcnt(0)
	v_mfma_f32_16x16x32_bf16 v[128:131], v[120:123], v[160:163], v[128:131]
	v_mfma_f32_16x16x32_bf16 v[124:127], v[136:139], v[160:163], v[124:127]
	v_mfma_f32_16x16x32_bf16 v[108:111], v[120:123], v[168:171], v[108:111]
	v_mfma_f32_16x16x32_bf16 v[104:107], v[136:139], v[168:171], v[104:107]
	v_mfma_f32_16x16x32_bf16 v[92:95], v[120:123], v[176:179], v[92:95]
	v_mfma_f32_16x16x32_bf16 v[88:91], v[136:139], v[176:179], v[88:91]
	v_mfma_f32_16x16x32_bf16 v[76:79], v[120:123], v[200:203], v[76:79]
	v_mfma_f32_16x16x32_bf16 v[72:75], v[136:139], v[200:203], v[72:75]
	v_mfma_f32_16x16x32_bf16 v[128:131], v[132:135], v[164:167], v[128:131]
	v_mfma_f32_16x16x32_bf16 v[124:127], v[140:143], v[164:167], v[124:127]
	v_mfma_f32_16x16x32_bf16 v[108:111], v[132:135], v[172:175], v[108:111]
	v_mfma_f32_16x16x32_bf16 v[104:107], v[140:143], v[172:175], v[104:107]
	v_mfma_f32_16x16x32_bf16 v[92:95], v[132:135], v[180:183], v[92:95]
	v_mfma_f32_16x16x32_bf16 v[88:91], v[140:143], v[180:183], v[88:91]
	v_mfma_f32_16x16x32_bf16 v[76:79], v[132:135], v[204:207], v[76:79]
	v_mfma_f32_16x16x32_bf16 v[72:75], v[140:143], v[204:207], v[72:75]
	s_setprio 0
	s_setprio 1
	v_mfma_f32_16x16x32_bf16 v[116:119], v[144:147], v[160:163], v[116:119]
	v_mfma_f32_16x16x32_bf16 v[112:115], v[152:155], v[160:163], v[112:115]
	v_mfma_f32_16x16x32_bf16 v[100:103], v[144:147], v[168:171], v[100:103]
	v_mfma_f32_16x16x32_bf16 v[96:99], v[152:155], v[168:171], v[96:99]
	v_mfma_f32_16x16x32_bf16 v[84:87], v[144:147], v[176:179], v[84:87]
	v_mfma_f32_16x16x32_bf16 v[80:83], v[152:155], v[176:179], v[80:83]
	v_mfma_f32_16x16x32_bf16 v[68:71], v[144:147], v[200:203], v[68:71]
	v_mfma_f32_16x16x32_bf16 v[64:67], v[152:155], v[200:203], v[64:67]
	v_mfma_f32_16x16x32_bf16 v[116:119], v[148:151], v[164:167], v[116:119]
	v_mfma_f32_16x16x32_bf16 v[112:115], v[156:159], v[164:167], v[112:115]
	v_mfma_f32_16x16x32_bf16 v[100:103], v[148:151], v[172:175], v[100:103]
	v_mfma_f32_16x16x32_bf16 v[96:99], v[156:159], v[172:175], v[96:99]
	s_setprio 2
	s_barrier
	v_mfma_f32_16x16x32_bf16 v[84:87], v[148:151], v[180:183], v[84:87]
	v_mfma_f32_16x16x32_bf16 v[80:83], v[156:159], v[180:183], v[80:83]
	v_mfma_f32_16x16x32_bf16 v[68:71], v[148:151], v[204:207], v[68:71]
	v_mfma_f32_16x16x32_bf16 v[64:67], v[156:159], v[204:207], v[64:67]
	s_setprio 0
	s_add_i32 s67, s62, s49
	v_lshl_add_u64 v[208:209], s[40:41], 0, v[186:187]
	s_mov_b32 m0, s67
	ds_read_b128 v[160:163], v235 offset:16384
	ds_read_b128 v[164:167], v235 offset:17408
	ds_read_b128 v[168:171], v235 offset:18432
	ds_read_b128 v[172:175], v235 offset:19456
	ds_read_b128 v[176:179], v235 offset:20480
	ds_read_b128 v[180:183], v235 offset:21504
	ds_read_b128 v[200:203], v235 offset:22528
	ds_read_b128 v[204:207], v235 offset:23552
	global_load_lds_dwordx4 v[208:209], off
	s_add_i32 m0, s67, 0x2000
	s_add_u32 s68, s40, 0x40000
	v_lshl_add_u64 v[210:211], s[40:41], 0, v[190:191]
	s_addc_u32 s69, s41, 0
	s_add_i32 s67, s63, s49
	global_load_lds_dwordx4 v[210:211], off
	v_lshl_add_u64 v[212:213], s[68:69], 0, v[186:187]
	s_mov_b32 m0, s67
	v_lshl_add_u64 v[214:215], s[42:43], 0, v[188:189]
	global_load_lds_dwordx4 v[212:213], off
	s_add_i32 m0, s67, 0x2000
	v_lshl_add_u64 v[212:213], s[68:69], 0, v[190:191]
	global_load_lds_dwordx4 v[212:213], off
	s_mov_b32 m0, s50
	v_lshl_add_u64 v[212:213], s[42:43], 0, v[184:185]
	global_load_lds_dwordx4 v[212:213], off
	s_mov_b32 m0, s51
	s_nop 0
	global_load_lds_dwordx4 v[214:215], off
	s_waitcnt vmcnt(8)
	s_waitcnt lgkmcnt(0)
	s_barrier
	s_setprio 1
	s_waitcnt lgkmcnt(0)
	v_mfma_f32_16x16x32_bf16 v[60:63], v[120:123], v[160:163], v[60:63]
	v_mfma_f32_16x16x32_bf16 v[56:59], v[136:139], v[160:163], v[56:59]
	v_mfma_f32_16x16x32_bf16 v[44:47], v[120:123], v[168:171], v[44:47]
	v_mfma_f32_16x16x32_bf16 v[40:43], v[136:139], v[168:171], v[40:43]
	v_mfma_f32_16x16x32_bf16 v[28:31], v[120:123], v[176:179], v[28:31]
	v_mfma_f32_16x16x32_bf16 v[24:27], v[136:139], v[176:179], v[24:27]
	v_mfma_f32_16x16x32_bf16 v[12:15], v[120:123], v[200:203], v[12:15]
	v_mfma_f32_16x16x32_bf16 v[8:11], v[136:139], v[200:203], v[8:11]
	v_mfma_f32_16x16x32_bf16 v[60:63], v[132:135], v[164:167], v[60:63]
	v_mfma_f32_16x16x32_bf16 v[56:59], v[140:143], v[164:167], v[56:59]
	v_mfma_f32_16x16x32_bf16 v[44:47], v[132:135], v[172:175], v[44:47]
	v_mfma_f32_16x16x32_bf16 v[40:43], v[140:143], v[172:175], v[40:43]
	v_mfma_f32_16x16x32_bf16 v[28:31], v[132:135], v[180:183], v[28:31]
	v_mfma_f32_16x16x32_bf16 v[24:27], v[140:143], v[180:183], v[24:27]
	v_mfma_f32_16x16x32_bf16 v[12:15], v[132:135], v[204:207], v[12:15]
	v_mfma_f32_16x16x32_bf16 v[8:11], v[140:143], v[204:207], v[8:11]
	s_setprio 0
	s_setprio 1
	v_mfma_f32_16x16x32_bf16 v[52:55], v[144:147], v[160:163], v[52:55]
	v_mfma_f32_16x16x32_bf16 v[48:51], v[152:155], v[160:163], v[48:51]
	v_mfma_f32_16x16x32_bf16 v[36:39], v[144:147], v[168:171], v[36:39]
	v_mfma_f32_16x16x32_bf16 v[32:35], v[152:155], v[168:171], v[32:35]
	v_mfma_f32_16x16x32_bf16 v[20:23], v[144:147], v[176:179], v[20:23]
	v_mfma_f32_16x16x32_bf16 v[16:19], v[152:155], v[176:179], v[16:19]
	v_mfma_f32_16x16x32_bf16 v[4:7], v[144:147], v[200:203], v[4:7]
	v_mfma_f32_16x16x32_bf16 v[0:3], v[152:155], v[200:203], v[0:3]
	v_mfma_f32_16x16x32_bf16 v[52:55], v[148:151], v[164:167], v[52:55]
	v_mfma_f32_16x16x32_bf16 v[48:51], v[156:159], v[164:167], v[48:51]
	v_mfma_f32_16x16x32_bf16 v[36:39], v[148:151], v[172:175], v[36:39]
	v_mfma_f32_16x16x32_bf16 v[32:35], v[156:159], v[172:175], v[32:35]
	s_setprio 2
	s_barrier
	v_mfma_f32_16x16x32_bf16 v[20:23], v[148:151], v[180:183], v[20:23]
	v_mfma_f32_16x16x32_bf16 v[16:19], v[156:159], v[180:183], v[16:19]
	v_mfma_f32_16x16x32_bf16 v[4:7], v[148:151], v[204:207], v[4:7]
	v_mfma_f32_16x16x32_bf16 v[0:3], v[156:159], v[204:207], v[0:3]
	s_setprio 0
	s_add_i32 s67, 0, 0x18000
	s_add_i32 s68, 0, 0x1c000
	v_add_u32_e32 v140, s67, v232
	v_add_u32_e32 v156, s68, v232
	ds_read_b128 v[120:123], v140
	ds_read_b128 v[132:135], v140 offset:1024
	ds_read_b128 v[136:139], v140 offset:2048
	ds_read_b128 v[140:143], v140 offset:3072
	ds_read_b128 v[144:147], v156
	ds_read_b128 v[148:151], v156 offset:1024
	ds_read_b128 v[152:155], v156 offset:2048
	ds_read_b128 v[156:159], v156 offset:3072
	s_add_u32 s42, s42, 0x40000
	s_addc_u32 s43, s43, 0
	s_mov_b32 m0, s54
	v_lshl_add_u64 v[216:217], s[42:43], 0, v[184:185]
	ds_read_b128 v[160:163], v235 offset:32768
	ds_read_b128 v[164:167], v235 offset:33792
	ds_read_b128 v[168:171], v235 offset:34816
	ds_read_b128 v[172:175], v235 offset:35840
	ds_read_b128 v[176:179], v235 offset:36864
	ds_read_b128 v[180:183], v235 offset:37888
	ds_read_b128 v[200:203], v235 offset:38912
	ds_read_b128 v[204:207], v235 offset:39936
	global_load_lds_dwordx4 v[216:217], off
	s_mov_b32 m0, s55
	v_lshl_add_u64 v[216:217], s[42:43], 0, v[188:189]
	global_load_lds_dwordx4 v[216:217], off
	s_waitcnt vmcnt(8)
	s_waitcnt lgkmcnt(0)
	s_barrier
	s_setprio 1
	s_waitcnt lgkmcnt(0)
	v_mfma_f32_16x16x32_bf16 v[128:131], v[120:123], v[160:163], v[128:131]
	v_mfma_f32_16x16x32_bf16 v[124:127], v[136:139], v[160:163], v[124:127]
	v_mfma_f32_16x16x32_bf16 v[108:111], v[120:123], v[168:171], v[108:111]
	v_mfma_f32_16x16x32_bf16 v[104:107], v[136:139], v[168:171], v[104:107]
	v_mfma_f32_16x16x32_bf16 v[92:95], v[120:123], v[176:179], v[92:95]
	v_mfma_f32_16x16x32_bf16 v[88:91], v[136:139], v[176:179], v[88:91]
	v_mfma_f32_16x16x32_bf16 v[76:79], v[120:123], v[200:203], v[76:79]
	v_mfma_f32_16x16x32_bf16 v[72:75], v[136:139], v[200:203], v[72:75]
	v_mfma_f32_16x16x32_bf16 v[128:131], v[132:135], v[164:167], v[128:131]
	v_mfma_f32_16x16x32_bf16 v[124:127], v[140:143], v[164:167], v[124:127]
	v_mfma_f32_16x16x32_bf16 v[108:111], v[132:135], v[172:175], v[108:111]
	v_mfma_f32_16x16x32_bf16 v[104:107], v[140:143], v[172:175], v[104:107]
	v_mfma_f32_16x16x32_bf16 v[92:95], v[132:135], v[180:183], v[92:95]
	v_mfma_f32_16x16x32_bf16 v[88:91], v[140:143], v[180:183], v[88:91]
	v_mfma_f32_16x16x32_bf16 v[76:79], v[132:135], v[204:207], v[76:79]
	v_mfma_f32_16x16x32_bf16 v[72:75], v[140:143], v[204:207], v[72:75]
	s_setprio 0
	s_setprio 1
	v_mfma_f32_16x16x32_bf16 v[116:119], v[144:147], v[160:163], v[116:119]
	v_mfma_f32_16x16x32_bf16 v[112:115], v[152:155], v[160:163], v[112:115]
	v_mfma_f32_16x16x32_bf16 v[100:103], v[144:147], v[168:171], v[100:103]
	v_mfma_f32_16x16x32_bf16 v[96:99], v[152:155], v[168:171], v[96:99]
	v_mfma_f32_16x16x32_bf16 v[84:87], v[144:147], v[176:179], v[84:87]
	v_mfma_f32_16x16x32_bf16 v[80:83], v[152:155], v[176:179], v[80:83]
	v_mfma_f32_16x16x32_bf16 v[68:71], v[144:147], v[200:203], v[68:71]
	v_mfma_f32_16x16x32_bf16 v[64:67], v[152:155], v[200:203], v[64:67]
	v_mfma_f32_16x16x32_bf16 v[116:119], v[148:151], v[164:167], v[116:119]
	v_mfma_f32_16x16x32_bf16 v[112:115], v[156:159], v[164:167], v[112:115]
	v_mfma_f32_16x16x32_bf16 v[100:103], v[148:151], v[172:175], v[100:103]
	v_mfma_f32_16x16x32_bf16 v[96:99], v[156:159], v[172:175], v[96:99]
	s_setprio 2
	s_barrier
	v_mfma_f32_16x16x32_bf16 v[84:87], v[148:151], v[180:183], v[84:87]
	v_mfma_f32_16x16x32_bf16 v[80:83], v[156:159], v[180:183], v[80:83]
	v_mfma_f32_16x16x32_bf16 v[68:71], v[148:151], v[204:207], v[68:71]
	v_mfma_f32_16x16x32_bf16 v[64:67], v[156:159], v[204:207], v[64:67]
	s_setprio 0
	s_add_i32 s42, s67, s49
	v_lshl_add_u64 v[208:209], v[208:209], 0, s[18:19]
	s_mov_b32 m0, s42
	ds_read_b128 v[160:163], v235 offset:49152
	ds_read_b128 v[164:167], v235 offset:50176
	ds_read_b128 v[168:171], v235 offset:51200
	ds_read_b128 v[172:175], v235 offset:52224
	ds_read_b128 v[176:179], v235 offset:53248
	ds_read_b128 v[180:183], v235 offset:54272
	ds_read_b128 v[200:203], v235 offset:55296
	ds_read_b128 v[204:207], v235 offset:56320
	global_load_lds_dwordx4 v[208:209], off
	s_add_i32 m0, s42, 0x2000
	s_add_u32 s40, s40, 0x40080
	v_lshl_add_u64 v[208:209], v[210:211], 0, s[18:19]
	s_addc_u32 s41, s41, 0
	s_add_i32 s42, s68, s49
	global_load_lds_dwordx4 v[208:209], off
	s_mov_b32 m0, s42
	v_lshl_add_u64 v[208:209], s[40:41], 0, v[186:187]
	global_load_lds_dwordx4 v[208:209], off
	s_add_i32 m0, s42, 0x2000
	v_lshl_add_u64 v[208:209], s[40:41], 0, v[190:191]
	global_load_lds_dwordx4 v[208:209], off
	s_mov_b32 m0, s57
	v_lshl_add_u64 v[208:209], v[212:213], 0, s[18:19]
	global_load_lds_dwordx4 v[208:209], off
	s_mov_b32 m0, s58
	v_lshl_add_u64 v[208:209], v[214:215], 0, s[18:19]
	global_load_lds_dwordx4 v[208:209], off
	s_waitcnt vmcnt(8)
	s_waitcnt lgkmcnt(0)
	s_barrier
	s_setprio 1
	s_waitcnt lgkmcnt(0)
	v_mfma_f32_16x16x32_bf16 v[60:63], v[120:123], v[160:163], v[60:63]
	v_mfma_f32_16x16x32_bf16 v[56:59], v[136:139], v[160:163], v[56:59]
	v_mfma_f32_16x16x32_bf16 v[44:47], v[120:123], v[168:171], v[44:47]
	v_mfma_f32_16x16x32_bf16 v[40:43], v[136:139], v[168:171], v[40:43]
	v_mfma_f32_16x16x32_bf16 v[28:31], v[120:123], v[176:179], v[28:31]
	v_mfma_f32_16x16x32_bf16 v[24:27], v[136:139], v[176:179], v[24:27]
	v_mfma_f32_16x16x32_bf16 v[12:15], v[120:123], v[200:203], v[12:15]
	v_mfma_f32_16x16x32_bf16 v[8:11], v[136:139], v[200:203], v[8:11]
	v_mfma_f32_16x16x32_bf16 v[60:63], v[132:135], v[164:167], v[60:63]
	v_mfma_f32_16x16x32_bf16 v[56:59], v[140:143], v[164:167], v[56:59]
	v_mfma_f32_16x16x32_bf16 v[44:47], v[132:135], v[172:175], v[44:47]
	v_mfma_f32_16x16x32_bf16 v[40:43], v[140:143], v[172:175], v[40:43]
	v_mfma_f32_16x16x32_bf16 v[28:31], v[132:135], v[180:183], v[28:31]
	v_mfma_f32_16x16x32_bf16 v[24:27], v[140:143], v[180:183], v[24:27]
	v_mfma_f32_16x16x32_bf16 v[12:15], v[132:135], v[204:207], v[12:15]
	v_mfma_f32_16x16x32_bf16 v[8:11], v[140:143], v[204:207], v[8:11]
	s_setprio 0
	s_setprio 1
	v_mfma_f32_16x16x32_bf16 v[52:55], v[144:147], v[160:163], v[52:55]
	v_mfma_f32_16x16x32_bf16 v[48:51], v[152:155], v[160:163], v[48:51]
	v_mfma_f32_16x16x32_bf16 v[36:39], v[144:147], v[168:171], v[36:39]
	v_mfma_f32_16x16x32_bf16 v[32:35], v[152:155], v[168:171], v[32:35]
	v_mfma_f32_16x16x32_bf16 v[20:23], v[144:147], v[176:179], v[20:23]
	v_mfma_f32_16x16x32_bf16 v[16:19], v[152:155], v[176:179], v[16:19]
	v_mfma_f32_16x16x32_bf16 v[4:7], v[144:147], v[200:203], v[4:7]
	v_mfma_f32_16x16x32_bf16 v[0:3], v[152:155], v[200:203], v[0:3]
	v_mfma_f32_16x16x32_bf16 v[52:55], v[148:151], v[164:167], v[52:55]
	v_mfma_f32_16x16x32_bf16 v[48:51], v[156:159], v[164:167], v[48:51]
	v_mfma_f32_16x16x32_bf16 v[36:39], v[148:151], v[172:175], v[36:39]
	v_mfma_f32_16x16x32_bf16 v[32:35], v[156:159], v[172:175], v[32:35]
	s_setprio 2
	s_barrier
	v_mfma_f32_16x16x32_bf16 v[20:23], v[148:151], v[180:183], v[20:23]
	v_mfma_f32_16x16x32_bf16 v[16:19], v[156:159], v[180:183], v[16:19]
	v_mfma_f32_16x16x32_bf16 v[4:7], v[148:151], v[204:207], v[4:7]
	v_mfma_f32_16x16x32_bf16 v[0:3], v[156:159], v[204:207], v[0:3]
	s_setprio 0
	s_add_i32 s66, s66, 2
	s_add_u32 s38, s38, 0x100
	s_addc_u32 s39, s39, 0
	s_add_u32 s64, s64, 0x100
	s_addc_u32 s65, s65, 0
	s_cmp_gt_u32 s66, 13
	s_cbranch_scc0 .LBB0_1146

.LBB0_1309:
	s_add_u32 s51, s26, 0x100
	s_addc_u32 s52, s27, 0
	s_mov_b32 s53, -2
	ds_read_b128 v[128:131], v197
	ds_read_b128 v[132:135], v197 offset:1024
	ds_read_b128 v[136:139], v197 offset:2048
	ds_read_b128 v[140:143], v197 offset:3072
	ds_read_b128 v[144:147], v198
	ds_read_b128 v[148:151], v198 offset:1024
	ds_read_b128 v[152:155], v198 offset:2048
	ds_read_b128 v[156:159], v198 offset:3072
	s_add_u32 s4, s24, 0x100
	s_addc_u32 s5, s25, 0
	s_cmp_eq_u32 s53, 40
	s_cselect_b32 s29, s21, s5
	s_cselect_b32 s28, s20, s4
	s_cselect_b32 s27, s23, s52
	s_cselect_b32 s26, s22, s51
	v_lshl_add_u64 v[212:213], s[24:25], 0, v[172:173]
	s_add_i32 m0, s36, 0xc000
	ds_read_b128 v[160:163], v199
	ds_read_b128 v[180:183], v199 offset:1024
	ds_read_b128 v[184:187], v199 offset:2048
	ds_read_b128 v[188:191], v199 offset:3072
	ds_read_b128 v[192:195], v199 offset:4096
	ds_read_b128 v[200:203], v199 offset:5120
	ds_read_b128 v[204:207], v199 offset:6144
	ds_read_b128 v[208:211], v199 offset:7168
	global_load_lds_dwordx4 v[212:213], off
	s_add_i32 m0, s36, 0xe000
	v_lshl_add_u64 v[212:213], s[24:25], 0, v[174:175]
	global_load_lds_dwordx4 v[212:213], off
	s_waitcnt vmcnt(8)
	s_waitcnt lgkmcnt(0)
	s_barrier
	s_setprio 1
	s_waitcnt lgkmcnt(0)
	v_mfma_f32_16x16x32_bf16 v[124:127], v[128:131], v[160:163], 0
	v_mfma_f32_16x16x32_bf16 v[120:123], v[136:139], v[160:163], 0
	v_mfma_f32_16x16x32_bf16 v[116:119], v[128:131], v[184:187], 0
	v_mfma_f32_16x16x32_bf16 v[108:111], v[136:139], v[184:187], 0
	v_mfma_f32_16x16x32_bf16 v[88:91], v[128:131], v[192:195], 0
	v_mfma_f32_16x16x32_bf16 v[100:103], v[136:139], v[192:195], 0
	v_mfma_f32_16x16x32_bf16 v[72:75], v[128:131], v[204:207], 0
	v_mfma_f32_16x16x32_bf16 v[76:79], v[136:139], v[204:207], 0
	v_mfma_f32_16x16x32_bf16 v[124:127], v[132:135], v[180:183], v[124:127]
	v_mfma_f32_16x16x32_bf16 v[120:123], v[140:143], v[180:183], v[120:123]
	v_mfma_f32_16x16x32_bf16 v[116:119], v[132:135], v[188:191], v[116:119]
	v_mfma_f32_16x16x32_bf16 v[108:111], v[140:143], v[188:191], v[108:111]
	v_mfma_f32_16x16x32_bf16 v[88:91], v[132:135], v[200:203], v[88:91]
	v_mfma_f32_16x16x32_bf16 v[100:103], v[140:143], v[200:203], v[100:103]
	v_mfma_f32_16x16x32_bf16 v[72:75], v[132:135], v[208:211], v[72:75]
	v_mfma_f32_16x16x32_bf16 v[76:79], v[140:143], v[208:211], v[76:79]
	s_setprio 0
	s_setprio 1
	v_mfma_f32_16x16x32_bf16 v[112:115], v[144:147], v[160:163], 0
	v_mfma_f32_16x16x32_bf16 v[104:107], v[152:155], v[160:163], 0
	v_mfma_f32_16x16x32_bf16 v[96:99], v[144:147], v[184:187], 0
	v_mfma_f32_16x16x32_bf16 v[92:95], v[152:155], v[184:187], 0
	v_mfma_f32_16x16x32_bf16 v[80:83], v[144:147], v[192:195], 0
	v_mfma_f32_16x16x32_bf16 v[84:87], v[152:155], v[192:195], 0
	v_mfma_f32_16x16x32_bf16 v[64:67], v[144:147], v[204:207], 0
	v_mfma_f32_16x16x32_bf16 v[68:71], v[152:155], v[204:207], 0
	v_mfma_f32_16x16x32_bf16 v[112:115], v[148:151], v[180:183], v[112:115]
	v_mfma_f32_16x16x32_bf16 v[104:107], v[156:159], v[180:183], v[104:107]
	v_mfma_f32_16x16x32_bf16 v[96:99], v[148:151], v[188:191], v[96:99]
	v_mfma_f32_16x16x32_bf16 v[92:95], v[156:159], v[188:191], v[92:95]
	s_setprio 2
	s_barrier
	v_mfma_f32_16x16x32_bf16 v[80:83], v[148:151], v[200:203], v[80:83]
	v_mfma_f32_16x16x32_bf16 v[84:87], v[156:159], v[200:203], v[84:87]
	v_mfma_f32_16x16x32_bf16 v[64:67], v[148:151], v[208:211], v[64:67]
	v_mfma_f32_16x16x32_bf16 v[68:71], v[156:159], v[208:211], v[68:71]
	s_setprio 0
	s_add_i32 s24, s45, s35
	v_lshl_add_u64 v[212:213], s[26:27], 0, v[166:167]
	s_mov_b32 m0, s24
	ds_read_b128 v[160:163], v199 offset:16384
	ds_read_b128 v[180:183], v199 offset:17408
	ds_read_b128 v[184:187], v199 offset:18432
	ds_read_b128 v[188:191], v199 offset:19456
	ds_read_b128 v[192:195], v199 offset:20480
	ds_read_b128 v[200:203], v199 offset:21504
	ds_read_b128 v[204:207], v199 offset:22528
	ds_read_b128 v[208:211], v199 offset:23552
	global_load_lds_dwordx4 v[212:213], off
	s_add_i32 m0, s24, 0x2000
	s_add_u32 s24, s26, 0xb0000
	v_lshl_add_u64 v[214:215], s[26:27], 0, v[170:171]
	s_addc_u32 s25, s27, 0
	s_add_i32 s54, s46, s35
	global_load_lds_dwordx4 v[214:215], off
	v_lshl_add_u64 v[216:217], s[24:25], 0, v[166:167]
	s_mov_b32 m0, s54
	v_lshl_add_u64 v[218:219], s[28:29], 0, v[168:169]
	global_load_lds_dwordx4 v[216:217], off
	s_add_i32 m0, s54, 0x2000
	v_lshl_add_u64 v[216:217], s[24:25], 0, v[170:171]
	global_load_lds_dwordx4 v[216:217], off
	s_mov_b32 m0, s36
	v_lshl_add_u64 v[216:217], s[28:29], 0, v[164:165]
	global_load_lds_dwordx4 v[216:217], off
	s_mov_b32 m0, s37
	s_nop 0
	global_load_lds_dwordx4 v[218:219], off
	s_waitcnt vmcnt(8)
	s_waitcnt lgkmcnt(0)
	s_barrier
	s_setprio 1
	s_waitcnt lgkmcnt(0)
	v_mfma_f32_16x16x32_bf16 v[56:59], v[128:131], v[160:163], 0
	v_mfma_f32_16x16x32_bf16 v[60:63], v[136:139], v[160:163], 0
	v_mfma_f32_16x16x32_bf16 v[40:43], v[128:131], v[184:187], 0
	v_mfma_f32_16x16x32_bf16 v[44:47], v[136:139], v[184:187], 0
	v_mfma_f32_16x16x32_bf16 v[24:27], v[128:131], v[192:195], 0
	v_mfma_f32_16x16x32_bf16 v[28:31], v[136:139], v[192:195], 0
	v_mfma_f32_16x16x32_bf16 v[8:11], v[128:131], v[204:207], 0
	v_mfma_f32_16x16x32_bf16 v[12:15], v[136:139], v[204:207], 0
	v_mfma_f32_16x16x32_bf16 v[56:59], v[132:135], v[180:183], v[56:59]
	v_mfma_f32_16x16x32_bf16 v[60:63], v[140:143], v[180:183], v[60:63]
	v_mfma_f32_16x16x32_bf16 v[40:43], v[132:135], v[188:191], v[40:43]
	v_mfma_f32_16x16x32_bf16 v[44:47], v[140:143], v[188:191], v[44:47]
	v_mfma_f32_16x16x32_bf16 v[24:27], v[132:135], v[200:203], v[24:27]
	v_mfma_f32_16x16x32_bf16 v[28:31], v[140:143], v[200:203], v[28:31]
	v_mfma_f32_16x16x32_bf16 v[8:11], v[132:135], v[208:211], v[8:11]
	v_mfma_f32_16x16x32_bf16 v[12:15], v[140:143], v[208:211], v[12:15]
	s_setprio 0
	s_setprio 1
	v_mfma_f32_16x16x32_bf16 v[48:51], v[144:147], v[160:163], 0
	v_mfma_f32_16x16x32_bf16 v[52:55], v[152:155], v[160:163], 0
	v_mfma_f32_16x16x32_bf16 v[32:35], v[144:147], v[184:187], 0
	v_mfma_f32_16x16x32_bf16 v[36:39], v[152:155], v[184:187], 0
	v_mfma_f32_16x16x32_bf16 v[16:19], v[144:147], v[192:195], 0
	v_mfma_f32_16x16x32_bf16 v[20:23], v[152:155], v[192:195], 0
	v_mfma_f32_16x16x32_bf16 v[0:3], v[144:147], v[204:207], 0
	v_mfma_f32_16x16x32_bf16 v[4:7], v[152:155], v[204:207], 0
	v_mfma_f32_16x16x32_bf16 v[48:51], v[148:151], v[180:183], v[48:51]
	v_mfma_f32_16x16x32_bf16 v[52:55], v[156:159], v[180:183], v[52:55]
	v_mfma_f32_16x16x32_bf16 v[32:35], v[148:151], v[188:191], v[32:35]
	v_mfma_f32_16x16x32_bf16 v[36:39], v[156:159], v[188:191], v[36:39]
	s_setprio 2
	s_barrier
	v_mfma_f32_16x16x32_bf16 v[16:19], v[148:151], v[200:203], v[16:19]
	v_mfma_f32_16x16x32_bf16 v[20:23], v[156:159], v[200:203], v[20:23]
	v_mfma_f32_16x16x32_bf16 v[0:3], v[148:151], v[208:211], v[0:3]
	v_mfma_f32_16x16x32_bf16 v[4:7], v[156:159], v[208:211], v[4:7]
	s_setprio 0
	s_add_i32 s54, 0, 0x18000
	s_add_i32 s55, 0, 0x1c000
	v_add_u32_e32 v140, s54, v196
	v_add_u32_e32 v156, s55, v196
	ds_read_b128 v[128:131], v140
	ds_read_b128 v[132:135], v140 offset:1024
	ds_read_b128 v[136:139], v140 offset:2048
	ds_read_b128 v[140:143], v140 offset:3072
	ds_read_b128 v[144:147], v156
	ds_read_b128 v[148:151], v156 offset:1024
	ds_read_b128 v[152:155], v156 offset:2048
	ds_read_b128 v[156:159], v156 offset:3072
	s_add_u32 s24, s28, 0xb0000
	s_addc_u32 s25, s29, 0
	s_mov_b32 m0, s38
	v_lshl_add_u64 v[220:221], s[24:25], 0, v[164:165]
	ds_read_b128 v[160:163], v199 offset:32768
	ds_read_b128 v[180:183], v199 offset:33792
	ds_read_b128 v[184:187], v199 offset:34816
	ds_read_b128 v[188:191], v199 offset:35840
	ds_read_b128 v[192:195], v199 offset:36864
	ds_read_b128 v[200:203], v199 offset:37888
	ds_read_b128 v[204:207], v199 offset:38912
	ds_read_b128 v[208:211], v199 offset:39936
	global_load_lds_dwordx4 v[220:221], off
	s_mov_b32 m0, s39
	v_lshl_add_u64 v[220:221], s[24:25], 0, v[168:169]
	global_load_lds_dwordx4 v[220:221], off
	s_waitcnt vmcnt(8)
	s_waitcnt lgkmcnt(0)
	s_barrier
	s_setprio 1
	s_waitcnt lgkmcnt(0)
	v_mfma_f32_16x16x32_bf16 v[124:127], v[128:131], v[160:163], v[124:127]
	v_mfma_f32_16x16x32_bf16 v[120:123], v[136:139], v[160:163], v[120:123]
	v_mfma_f32_16x16x32_bf16 v[116:119], v[128:131], v[184:187], v[116:119]
	v_mfma_f32_16x16x32_bf16 v[108:111], v[136:139], v[184:187], v[108:111]
	v_mfma_f32_16x16x32_bf16 v[88:91], v[128:131], v[192:195], v[88:91]
	v_mfma_f32_16x16x32_bf16 v[100:103], v[136:139], v[192:195], v[100:103]
	v_mfma_f32_16x16x32_bf16 v[72:75], v[128:131], v[204:207], v[72:75]
	v_mfma_f32_16x16x32_bf16 v[76:79], v[136:139], v[204:207], v[76:79]
	v_mfma_f32_16x16x32_bf16 v[124:127], v[132:135], v[180:183], v[124:127]
	v_mfma_f32_16x16x32_bf16 v[120:123], v[140:143], v[180:183], v[120:123]
	v_mfma_f32_16x16x32_bf16 v[116:119], v[132:135], v[188:191], v[116:119]
	v_mfma_f32_16x16x32_bf16 v[108:111], v[140:143], v[188:191], v[108:111]
	v_mfma_f32_16x16x32_bf16 v[88:91], v[132:135], v[200:203], v[88:91]
	v_mfma_f32_16x16x32_bf16 v[100:103], v[140:143], v[200:203], v[100:103]
	v_mfma_f32_16x16x32_bf16 v[72:75], v[132:135], v[208:211], v[72:75]
	v_mfma_f32_16x16x32_bf16 v[76:79], v[140:143], v[208:211], v[76:79]
	s_setprio 0
	s_setprio 1
	v_mfma_f32_16x16x32_bf16 v[112:115], v[144:147], v[160:163], v[112:115]
	v_mfma_f32_16x16x32_bf16 v[104:107], v[152:155], v[160:163], v[104:107]
	v_mfma_f32_16x16x32_bf16 v[96:99], v[144:147], v[184:187], v[96:99]
	v_mfma_f32_16x16x32_bf16 v[92:95], v[152:155], v[184:187], v[92:95]
	v_mfma_f32_16x16x32_bf16 v[80:83], v[144:147], v[192:195], v[80:83]
	v_mfma_f32_16x16x32_bf16 v[84:87], v[152:155], v[192:195], v[84:87]
	v_mfma_f32_16x16x32_bf16 v[64:67], v[144:147], v[204:207], v[64:67]
	v_mfma_f32_16x16x32_bf16 v[68:71], v[152:155], v[204:207], v[68:71]
	v_mfma_f32_16x16x32_bf16 v[112:115], v[148:151], v[180:183], v[112:115]
	v_mfma_f32_16x16x32_bf16 v[104:107], v[156:159], v[180:183], v[104:107]
	v_mfma_f32_16x16x32_bf16 v[96:99], v[148:151], v[188:191], v[96:99]
	v_mfma_f32_16x16x32_bf16 v[92:95], v[156:159], v[188:191], v[92:95]
	s_setprio 2
	s_barrier
	v_mfma_f32_16x16x32_bf16 v[80:83], v[148:151], v[200:203], v[80:83]
	v_mfma_f32_16x16x32_bf16 v[84:87], v[156:159], v[200:203], v[84:87]
	v_mfma_f32_16x16x32_bf16 v[64:67], v[148:151], v[208:211], v[64:67]
	v_mfma_f32_16x16x32_bf16 v[68:71], v[156:159], v[208:211], v[68:71]
	s_setprio 0
	s_add_i32 s24, s54, s35
	v_lshl_add_u64 v[212:213], v[212:213], 0, s[16:17]
	s_mov_b32 m0, s24
	ds_read_b128 v[160:163], v199 offset:49152
	ds_read_b128 v[180:183], v199 offset:50176
	ds_read_b128 v[184:187], v199 offset:51200
	ds_read_b128 v[188:191], v199 offset:52224
	ds_read_b128 v[192:195], v199 offset:53248
	ds_read_b128 v[200:203], v199 offset:54272
	ds_read_b128 v[204:207], v199 offset:55296
	ds_read_b128 v[208:211], v199 offset:56320
	global_load_lds_dwordx4 v[212:213], off
	s_add_i32 m0, s24, 0x2000
	s_add_u32 s24, s26, 0xb0080
	v_lshl_add_u64 v[212:213], v[214:215], 0, s[16:17]
	s_addc_u32 s25, s27, 0
	s_add_i32 s26, s55, s35
	global_load_lds_dwordx4 v[212:213], off
	s_mov_b32 m0, s26
	v_lshl_add_u64 v[212:213], s[24:25], 0, v[166:167]
	global_load_lds_dwordx4 v[212:213], off
	s_add_i32 m0, s26, 0x2000
	v_lshl_add_u64 v[212:213], s[24:25], 0, v[170:171]
	global_load_lds_dwordx4 v[212:213], off
	s_mov_b32 m0, s41
	v_lshl_add_u64 v[212:213], v[216:217], 0, s[16:17]
	global_load_lds_dwordx4 v[212:213], off
	s_mov_b32 m0, s42
	v_lshl_add_u64 v[212:213], v[218:219], 0, s[16:17]
	global_load_lds_dwordx4 v[212:213], off
	s_waitcnt vmcnt(8)
	s_waitcnt lgkmcnt(0)
	s_barrier
	s_setprio 1
	s_waitcnt lgkmcnt(0)
	v_mfma_f32_16x16x32_bf16 v[56:59], v[128:131], v[160:163], v[56:59]
	v_mfma_f32_16x16x32_bf16 v[60:63], v[136:139], v[160:163], v[60:63]
	v_mfma_f32_16x16x32_bf16 v[40:43], v[128:131], v[184:187], v[40:43]
	v_mfma_f32_16x16x32_bf16 v[44:47], v[136:139], v[184:187], v[44:47]
	v_mfma_f32_16x16x32_bf16 v[24:27], v[128:131], v[192:195], v[24:27]
	v_mfma_f32_16x16x32_bf16 v[28:31], v[136:139], v[192:195], v[28:31]
	v_mfma_f32_16x16x32_bf16 v[8:11], v[128:131], v[204:207], v[8:11]
	v_mfma_f32_16x16x32_bf16 v[12:15], v[136:139], v[204:207], v[12:15]
	v_mfma_f32_16x16x32_bf16 v[56:59], v[132:135], v[180:183], v[56:59]
	v_mfma_f32_16x16x32_bf16 v[60:63], v[140:143], v[180:183], v[60:63]
	v_mfma_f32_16x16x32_bf16 v[40:43], v[132:135], v[188:191], v[40:43]
	v_mfma_f32_16x16x32_bf16 v[44:47], v[140:143], v[188:191], v[44:47]
	v_mfma_f32_16x16x32_bf16 v[24:27], v[132:135], v[200:203], v[24:27]
	v_mfma_f32_16x16x32_bf16 v[28:31], v[140:143], v[200:203], v[28:31]
	v_mfma_f32_16x16x32_bf16 v[8:11], v[132:135], v[208:211], v[8:11]
	v_mfma_f32_16x16x32_bf16 v[12:15], v[140:143], v[208:211], v[12:15]
	s_setprio 0
	s_setprio 1
	v_mfma_f32_16x16x32_bf16 v[48:51], v[144:147], v[160:163], v[48:51]
	v_mfma_f32_16x16x32_bf16 v[52:55], v[152:155], v[160:163], v[52:55]
	v_mfma_f32_16x16x32_bf16 v[32:35], v[144:147], v[184:187], v[32:35]
	v_mfma_f32_16x16x32_bf16 v[36:39], v[152:155], v[184:187], v[36:39]
	v_mfma_f32_16x16x32_bf16 v[16:19], v[144:147], v[192:195], v[16:19]
	v_mfma_f32_16x16x32_bf16 v[20:23], v[152:155], v[192:195], v[20:23]
	v_mfma_f32_16x16x32_bf16 v[0:3], v[144:147], v[204:207], v[0:3]
	v_mfma_f32_16x16x32_bf16 v[4:7], v[152:155], v[204:207], v[4:7]
	v_mfma_f32_16x16x32_bf16 v[48:51], v[148:151], v[180:183], v[48:51]
	v_mfma_f32_16x16x32_bf16 v[52:55], v[156:159], v[180:183], v[52:55]
	v_mfma_f32_16x16x32_bf16 v[32:35], v[148:151], v[188:191], v[32:35]
	v_mfma_f32_16x16x32_bf16 v[36:39], v[156:159], v[188:191], v[36:39]
	s_setprio 2
	s_barrier
	v_mfma_f32_16x16x32_bf16 v[16:19], v[148:151], v[200:203], v[16:19]
	v_mfma_f32_16x16x32_bf16 v[20:23], v[156:159], v[200:203], v[20:23]
	v_mfma_f32_16x16x32_bf16 v[0:3], v[148:151], v[208:211], v[0:3]
	v_mfma_f32_16x16x32_bf16 v[4:7], v[156:159], v[208:211], v[4:7]
	s_setprio 0
	s_add_i32 s53, s53, 2
	s_add_u32 s51, s51, 0x100
	s_addc_u32 s52, s52, 0
	s_cmp_gt_u32 s53, 41
	s_mov_b64 s[24:25], s[4:5]
.LBB0_1310:
	ds_read_b128 v[128:131], v197
	ds_read_b128 v[132:135], v197 offset:1024
	ds_read_b128 v[136:139], v197 offset:2048
	ds_read_b128 v[140:143], v197 offset:3072
	ds_read_b128 v[144:147], v198
	ds_read_b128 v[148:151], v198 offset:1024
	ds_read_b128 v[152:155], v198 offset:2048
	ds_read_b128 v[156:159], v198 offset:3072
	s_add_u32 s4, s24, 0x100
	s_addc_u32 s5, s25, 0
	s_cmp_eq_u32 s53, 40
	s_cselect_b32 s29, s21, s5
	s_cselect_b32 s28, s20, s4
	s_cselect_b32 s27, s23, s52
	s_cselect_b32 s26, s22, s51
	v_lshl_add_u64 v[212:213], s[24:25], 0, v[172:173]
	s_add_i32 m0, s36, 0xc000
	ds_read_b128 v[160:163], v199
	ds_read_b128 v[180:183], v199 offset:1024
	ds_read_b128 v[184:187], v199 offset:2048
	ds_read_b128 v[188:191], v199 offset:3072
	ds_read_b128 v[192:195], v199 offset:4096
	ds_read_b128 v[200:203], v199 offset:5120
	ds_read_b128 v[204:207], v199 offset:6144
	ds_read_b128 v[208:211], v199 offset:7168
	global_load_lds_dwordx4 v[212:213], off
	s_add_i32 m0, s36, 0xe000
	v_lshl_add_u64 v[212:213], s[24:25], 0, v[174:175]
	global_load_lds_dwordx4 v[212:213], off
	s_waitcnt vmcnt(8)
	s_waitcnt lgkmcnt(0)
	s_barrier
	s_setprio 1
	s_waitcnt lgkmcnt(0)
	v_mfma_f32_16x16x32_bf16 v[124:127], v[128:131], v[160:163], v[124:127]
	v_mfma_f32_16x16x32_bf16 v[120:123], v[136:139], v[160:163], v[120:123]
	v_mfma_f32_16x16x32_bf16 v[116:119], v[128:131], v[184:187], v[116:119]
	v_mfma_f32_16x16x32_bf16 v[108:111], v[136:139], v[184:187], v[108:111]
	v_mfma_f32_16x16x32_bf16 v[88:91], v[128:131], v[192:195], v[88:91]
	v_mfma_f32_16x16x32_bf16 v[100:103], v[136:139], v[192:195], v[100:103]
	v_mfma_f32_16x16x32_bf16 v[72:75], v[128:131], v[204:207], v[72:75]
	v_mfma_f32_16x16x32_bf16 v[76:79], v[136:139], v[204:207], v[76:79]
	v_mfma_f32_16x16x32_bf16 v[124:127], v[132:135], v[180:183], v[124:127]
	v_mfma_f32_16x16x32_bf16 v[120:123], v[140:143], v[180:183], v[120:123]
	v_mfma_f32_16x16x32_bf16 v[116:119], v[132:135], v[188:191], v[116:119]
	v_mfma_f32_16x16x32_bf16 v[108:111], v[140:143], v[188:191], v[108:111]
	v_mfma_f32_16x16x32_bf16 v[88:91], v[132:135], v[200:203], v[88:91]
	v_mfma_f32_16x16x32_bf16 v[100:103], v[140:143], v[200:203], v[100:103]
	v_mfma_f32_16x16x32_bf16 v[72:75], v[132:135], v[208:211], v[72:75]
	v_mfma_f32_16x16x32_bf16 v[76:79], v[140:143], v[208:211], v[76:79]
	s_setprio 0
	s_setprio 1
	v_mfma_f32_16x16x32_bf16 v[112:115], v[144:147], v[160:163], v[112:115]
	v_mfma_f32_16x16x32_bf16 v[104:107], v[152:155], v[160:163], v[104:107]
	v_mfma_f32_16x16x32_bf16 v[96:99], v[144:147], v[184:187], v[96:99]
	v_mfma_f32_16x16x32_bf16 v[92:95], v[152:155], v[184:187], v[92:95]
	v_mfma_f32_16x16x32_bf16 v[80:83], v[144:147], v[192:195], v[80:83]
	v_mfma_f32_16x16x32_bf16 v[84:87], v[152:155], v[192:195], v[84:87]
	v_mfma_f32_16x16x32_bf16 v[64:67], v[144:147], v[204:207], v[64:67]
	v_mfma_f32_16x16x32_bf16 v[68:71], v[152:155], v[204:207], v[68:71]
	v_mfma_f32_16x16x32_bf16 v[112:115], v[148:151], v[180:183], v[112:115]
	v_mfma_f32_16x16x32_bf16 v[104:107], v[156:159], v[180:183], v[104:107]
	v_mfma_f32_16x16x32_bf16 v[96:99], v[148:151], v[188:191], v[96:99]
	v_mfma_f32_16x16x32_bf16 v[92:95], v[156:159], v[188:191], v[92:95]
	s_setprio 2
	s_barrier
	v_mfma_f32_16x16x32_bf16 v[80:83], v[148:151], v[200:203], v[80:83]
	v_mfma_f32_16x16x32_bf16 v[84:87], v[156:159], v[200:203], v[84:87]
	v_mfma_f32_16x16x32_bf16 v[64:67], v[148:151], v[208:211], v[64:67]
	v_mfma_f32_16x16x32_bf16 v[68:71], v[156:159], v[208:211], v[68:71]
	s_setprio 0
	s_add_i32 s24, s45, s35
	v_lshl_add_u64 v[212:213], s[26:27], 0, v[166:167]
	s_mov_b32 m0, s24
	ds_read_b128 v[160:163], v199 offset:16384
	ds_read_b128 v[180:183], v199 offset:17408
	ds_read_b128 v[184:187], v199 offset:18432
	ds_read_b128 v[188:191], v199 offset:19456
	ds_read_b128 v[192:195], v199 offset:20480
	ds_read_b128 v[200:203], v199 offset:21504
	ds_read_b128 v[204:207], v199 offset:22528
	ds_read_b128 v[208:211], v199 offset:23552
	global_load_lds_dwordx4 v[212:213], off
	s_add_i32 m0, s24, 0x2000
	s_add_u32 s24, s26, 0xb0000
	v_lshl_add_u64 v[214:215], s[26:27], 0, v[170:171]
	s_addc_u32 s25, s27, 0
	s_add_i32 s54, s46, s35
	global_load_lds_dwordx4 v[214:215], off
	v_lshl_add_u64 v[216:217], s[24:25], 0, v[166:167]
	s_mov_b32 m0, s54
	v_lshl_add_u64 v[218:219], s[28:29], 0, v[168:169]
	global_load_lds_dwordx4 v[216:217], off
	s_add_i32 m0, s54, 0x2000
	v_lshl_add_u64 v[216:217], s[24:25], 0, v[170:171]
	global_load_lds_dwordx4 v[216:217], off
	s_mov_b32 m0, s36
	v_lshl_add_u64 v[216:217], s[28:29], 0, v[164:165]
	global_load_lds_dwordx4 v[216:217], off
	s_mov_b32 m0, s37
	s_nop 0
	global_load_lds_dwordx4 v[218:219], off
	s_waitcnt vmcnt(8)
	s_waitcnt lgkmcnt(0)
	s_barrier
	s_setprio 1
	s_waitcnt lgkmcnt(0)
	v_mfma_f32_16x16x32_bf16 v[56:59], v[128:131], v[160:163], v[56:59]
	v_mfma_f32_16x16x32_bf16 v[60:63], v[136:139], v[160:163], v[60:63]
	v_mfma_f32_16x16x32_bf16 v[40:43], v[128:131], v[184:187], v[40:43]
	v_mfma_f32_16x16x32_bf16 v[44:47], v[136:139], v[184:187], v[44:47]
	v_mfma_f32_16x16x32_bf16 v[24:27], v[128:131], v[192:195], v[24:27]
	v_mfma_f32_16x16x32_bf16 v[28:31], v[136:139], v[192:195], v[28:31]
	v_mfma_f32_16x16x32_bf16 v[8:11], v[128:131], v[204:207], v[8:11]
	v_mfma_f32_16x16x32_bf16 v[12:15], v[136:139], v[204:207], v[12:15]
	v_mfma_f32_16x16x32_bf16 v[56:59], v[132:135], v[180:183], v[56:59]
	v_mfma_f32_16x16x32_bf16 v[60:63], v[140:143], v[180:183], v[60:63]
	v_mfma_f32_16x16x32_bf16 v[40:43], v[132:135], v[188:191], v[40:43]
	v_mfma_f32_16x16x32_bf16 v[44:47], v[140:143], v[188:191], v[44:47]
	v_mfma_f32_16x16x32_bf16 v[24:27], v[132:135], v[200:203], v[24:27]
	v_mfma_f32_16x16x32_bf16 v[28:31], v[140:143], v[200:203], v[28:31]
	v_mfma_f32_16x16x32_bf16 v[8:11], v[132:135], v[208:211], v[8:11]
	v_mfma_f32_16x16x32_bf16 v[12:15], v[140:143], v[208:211], v[12:15]
	s_setprio 0
	s_setprio 1
	v_mfma_f32_16x16x32_bf16 v[48:51], v[144:147], v[160:163], v[48:51]
	v_mfma_f32_16x16x32_bf16 v[52:55], v[152:155], v[160:163], v[52:55]
	v_mfma_f32_16x16x32_bf16 v[32:35], v[144:147], v[184:187], v[32:35]
	v_mfma_f32_16x16x32_bf16 v[36:39], v[152:155], v[184:187], v[36:39]
	v_mfma_f32_16x16x32_bf16 v[16:19], v[144:147], v[192:195], v[16:19]
	v_mfma_f32_16x16x32_bf16 v[20:23], v[152:155], v[192:195], v[20:23]
	v_mfma_f32_16x16x32_bf16 v[0:3], v[144:147], v[204:207], v[0:3]
	v_mfma_f32_16x16x32_bf16 v[4:7], v[152:155], v[204:207], v[4:7]
	v_mfma_f32_16x16x32_bf16 v[48:51], v[148:151], v[180:183], v[48:51]
	v_mfma_f32_16x16x32_bf16 v[52:55], v[156:159], v[180:183], v[52:55]
	v_mfma_f32_16x16x32_bf16 v[32:35], v[148:151], v[188:191], v[32:35]
	v_mfma_f32_16x16x32_bf16 v[36:39], v[156:159], v[188:191], v[36:39]
	s_setprio 2
	s_barrier
	v_mfma_f32_16x16x32_bf16 v[16:19], v[148:151], v[200:203], v[16:19]
	v_mfma_f32_16x16x32_bf16 v[20:23], v[156:159], v[200:203], v[20:23]
	v_mfma_f32_16x16x32_bf16 v[0:3], v[148:151], v[208:211], v[0:3]
	v_mfma_f32_16x16x32_bf16 v[4:7], v[156:159], v[208:211], v[4:7]
	s_setprio 0
	s_add_i32 s54, 0, 0x18000
	s_add_i32 s55, 0, 0x1c000
	v_add_u32_e32 v140, s54, v196
	v_add_u32_e32 v156, s55, v196
	ds_read_b128 v[128:131], v140
	ds_read_b128 v[132:135], v140 offset:1024
	ds_read_b128 v[136:139], v140 offset:2048
	ds_read_b128 v[140:143], v140 offset:3072
	ds_read_b128 v[144:147], v156
	ds_read_b128 v[148:151], v156 offset:1024
	ds_read_b128 v[152:155], v156 offset:2048
	ds_read_b128 v[156:159], v156 offset:3072
	s_add_u32 s24, s28, 0xb0000
	s_addc_u32 s25, s29, 0
	s_mov_b32 m0, s38
	v_lshl_add_u64 v[220:221], s[24:25], 0, v[164:165]
	ds_read_b128 v[160:163], v199 offset:32768
	ds_read_b128 v[180:183], v199 offset:33792
	ds_read_b128 v[184:187], v199 offset:34816
	ds_read_b128 v[188:191], v199 offset:35840
	ds_read_b128 v[192:195], v199 offset:36864
	ds_read_b128 v[200:203], v199 offset:37888
	ds_read_b128 v[204:207], v199 offset:38912
	ds_read_b128 v[208:211], v199 offset:39936
	global_load_lds_dwordx4 v[220:221], off
	s_mov_b32 m0, s39
	v_lshl_add_u64 v[220:221], s[24:25], 0, v[168:169]
	global_load_lds_dwordx4 v[220:221], off
	s_waitcnt vmcnt(8)
	s_waitcnt lgkmcnt(0)
	s_barrier
	s_setprio 1
	s_waitcnt lgkmcnt(0)
	v_mfma_f32_16x16x32_bf16 v[124:127], v[128:131], v[160:163], v[124:127]
	v_mfma_f32_16x16x32_bf16 v[120:123], v[136:139], v[160:163], v[120:123]
	v_mfma_f32_16x16x32_bf16 v[116:119], v[128:131], v[184:187], v[116:119]
	v_mfma_f32_16x16x32_bf16 v[108:111], v[136:139], v[184:187], v[108:111]
	v_mfma_f32_16x16x32_bf16 v[88:91], v[128:131], v[192:195], v[88:91]
	v_mfma_f32_16x16x32_bf16 v[100:103], v[136:139], v[192:195], v[100:103]
	v_mfma_f32_16x16x32_bf16 v[72:75], v[128:131], v[204:207], v[72:75]
	v_mfma_f32_16x16x32_bf16 v[76:79], v[136:139], v[204:207], v[76:79]
	v_mfma_f32_16x16x32_bf16 v[124:127], v[132:135], v[180:183], v[124:127]
	v_mfma_f32_16x16x32_bf16 v[120:123], v[140:143], v[180:183], v[120:123]
	v_mfma_f32_16x16x32_bf16 v[116:119], v[132:135], v[188:191], v[116:119]
	v_mfma_f32_16x16x32_bf16 v[108:111], v[140:143], v[188:191], v[108:111]
	v_mfma_f32_16x16x32_bf16 v[88:91], v[132:135], v[200:203], v[88:91]
	v_mfma_f32_16x16x32_bf16 v[100:103], v[140:143], v[200:203], v[100:103]
	v_mfma_f32_16x16x32_bf16 v[72:75], v[132:135], v[208:211], v[72:75]
	v_mfma_f32_16x16x32_bf16 v[76:79], v[140:143], v[208:211], v[76:79]
	s_setprio 0
	s_setprio 1
	v_mfma_f32_16x16x32_bf16 v[112:115], v[144:147], v[160:163], v[112:115]
	v_mfma_f32_16x16x32_bf16 v[104:107], v[152:155], v[160:163], v[104:107]
	v_mfma_f32_16x16x32_bf16 v[96:99], v[144:147], v[184:187], v[96:99]
	v_mfma_f32_16x16x32_bf16 v[92:95], v[152:155], v[184:187], v[92:95]
	v_mfma_f32_16x16x32_bf16 v[80:83], v[144:147], v[192:195], v[80:83]
	v_mfma_f32_16x16x32_bf16 v[84:87], v[152:155], v[192:195], v[84:87]
	v_mfma_f32_16x16x32_bf16 v[64:67], v[144:147], v[204:207], v[64:67]
	v_mfma_f32_16x16x32_bf16 v[68:71], v[152:155], v[204:207], v[68:71]
	v_mfma_f32_16x16x32_bf16 v[112:115], v[148:151], v[180:183], v[112:115]
	v_mfma_f32_16x16x32_bf16 v[104:107], v[156:159], v[180:183], v[104:107]
	v_mfma_f32_16x16x32_bf16 v[96:99], v[148:151], v[188:191], v[96:99]
	v_mfma_f32_16x16x32_bf16 v[92:95], v[156:159], v[188:191], v[92:95]
	s_setprio 2
	s_barrier
	v_mfma_f32_16x16x32_bf16 v[80:83], v[148:151], v[200:203], v[80:83]
	v_mfma_f32_16x16x32_bf16 v[84:87], v[156:159], v[200:203], v[84:87]
	v_mfma_f32_16x16x32_bf16 v[64:67], v[148:151], v[208:211], v[64:67]
	v_mfma_f32_16x16x32_bf16 v[68:71], v[156:159], v[208:211], v[68:71]
	s_setprio 0
	s_add_i32 s24, s54, s35
	v_lshl_add_u64 v[212:213], v[212:213], 0, s[16:17]
	s_mov_b32 m0, s24
	ds_read_b128 v[160:163], v199 offset:49152
	ds_read_b128 v[180:183], v199 offset:50176
	ds_read_b128 v[184:187], v199 offset:51200
	ds_read_b128 v[188:191], v199 offset:52224
	ds_read_b128 v[192:195], v199 offset:53248
	ds_read_b128 v[200:203], v199 offset:54272
	ds_read_b128 v[204:207], v199 offset:55296
	ds_read_b128 v[208:211], v199 offset:56320
	global_load_lds_dwordx4 v[212:213], off
	s_add_i32 m0, s24, 0x2000
	s_add_u32 s24, s26, 0xb0080
	v_lshl_add_u64 v[212:213], v[214:215], 0, s[16:17]
	s_addc_u32 s25, s27, 0
	s_add_i32 s26, s55, s35
	global_load_lds_dwordx4 v[212:213], off
	s_mov_b32 m0, s26
	v_lshl_add_u64 v[212:213], s[24:25], 0, v[166:167]
	global_load_lds_dwordx4 v[212:213], off
	s_add_i32 m0, s26, 0x2000
	v_lshl_add_u64 v[212:213], s[24:25], 0, v[170:171]
	global_load_lds_dwordx4 v[212:213], off
	s_mov_b32 m0, s41
	v_lshl_add_u64 v[212:213], v[216:217], 0, s[16:17]
	global_load_lds_dwordx4 v[212:213], off
	s_mov_b32 m0, s42
	v_lshl_add_u64 v[212:213], v[218:219], 0, s[16:17]
	global_load_lds_dwordx4 v[212:213], off
	s_waitcnt vmcnt(8)
	s_waitcnt lgkmcnt(0)
	s_barrier
	s_setprio 1
	s_waitcnt lgkmcnt(0)
	v_mfma_f32_16x16x32_bf16 v[56:59], v[128:131], v[160:163], v[56:59]
	v_mfma_f32_16x16x32_bf16 v[60:63], v[136:139], v[160:163], v[60:63]
	v_mfma_f32_16x16x32_bf16 v[40:43], v[128:131], v[184:187], v[40:43]
	v_mfma_f32_16x16x32_bf16 v[44:47], v[136:139], v[184:187], v[44:47]
	v_mfma_f32_16x16x32_bf16 v[24:27], v[128:131], v[192:195], v[24:27]
	v_mfma_f32_16x16x32_bf16 v[28:31], v[136:139], v[192:195], v[28:31]
	v_mfma_f32_16x16x32_bf16 v[8:11], v[128:131], v[204:207], v[8:11]
	v_mfma_f32_16x16x32_bf16 v[12:15], v[136:139], v[204:207], v[12:15]
	v_mfma_f32_16x16x32_bf16 v[56:59], v[132:135], v[180:183], v[56:59]
	v_mfma_f32_16x16x32_bf16 v[60:63], v[140:143], v[180:183], v[60:63]
	v_mfma_f32_16x16x32_bf16 v[40:43], v[132:135], v[188:191], v[40:43]
	v_mfma_f32_16x16x32_bf16 v[44:47], v[140:143], v[188:191], v[44:47]
	v_mfma_f32_16x16x32_bf16 v[24:27], v[132:135], v[200:203], v[24:27]
	v_mfma_f32_16x16x32_bf16 v[28:31], v[140:143], v[200:203], v[28:31]
	v_mfma_f32_16x16x32_bf16 v[8:11], v[132:135], v[208:211], v[8:11]
	v_mfma_f32_16x16x32_bf16 v[12:15], v[140:143], v[208:211], v[12:15]
	s_setprio 0
	s_setprio 1
	v_mfma_f32_16x16x32_bf16 v[48:51], v[144:147], v[160:163], v[48:51]
	v_mfma_f32_16x16x32_bf16 v[52:55], v[152:155], v[160:163], v[52:55]
	v_mfma_f32_16x16x32_bf16 v[32:35], v[144:147], v[184:187], v[32:35]
	v_mfma_f32_16x16x32_bf16 v[36:39], v[152:155], v[184:187], v[36:39]
	v_mfma_f32_16x16x32_bf16 v[16:19], v[144:147], v[192:195], v[16:19]
	v_mfma_f32_16x16x32_bf16 v[20:23], v[152:155], v[192:195], v[20:23]
	v_mfma_f32_16x16x32_bf16 v[0:3], v[144:147], v[204:207], v[0:3]
	v_mfma_f32_16x16x32_bf16 v[4:7], v[152:155], v[204:207], v[4:7]
	v_mfma_f32_16x16x32_bf16 v[48:51], v[148:151], v[180:183], v[48:51]
	v_mfma_f32_16x16x32_bf16 v[52:55], v[156:159], v[180:183], v[52:55]
	v_mfma_f32_16x16x32_bf16 v[32:35], v[148:151], v[188:191], v[32:35]
	v_mfma_f32_16x16x32_bf16 v[36:39], v[156:159], v[188:191], v[36:39]
	s_setprio 2
	s_barrier
	v_mfma_f32_16x16x32_bf16 v[16:19], v[148:151], v[200:203], v[16:19]
	v_mfma_f32_16x16x32_bf16 v[20:23], v[156:159], v[200:203], v[20:23]
	v_mfma_f32_16x16x32_bf16 v[0:3], v[148:151], v[208:211], v[0:3]
	v_mfma_f32_16x16x32_bf16 v[4:7], v[156:159], v[208:211], v[4:7]
	s_setprio 0
	s_add_i32 s53, s53, 2
	s_add_u32 s51, s51, 0x100
	s_addc_u32 s52, s52, 0
	s_cmp_gt_u32 s53, 41
	s_mov_b64 s[24:25], s[4:5]
	s_cbranch_scc0 .LBB0_1310
